# speedup vs baseline: 1.0048x; 1.0048x over previous
;     DI size_t aoff(const Unit& u, size_t tstep) const { return (size_t)u.pm * tstep; }
;     DI size_t boff(const Unit& u, size_t tstep) const { return (size_t)u.pn * tstep; }
;     DI bool next(int i, Unit& u) const { const long L = (long)i * G + c; if (L >= np) return false; u.pm = pmv; u.pn = (int)(L % nN); u.ks = (int)(L / nN); return true; }
;     DI size_t aoff(const Unit& u, size_t) const { return (size_t)u.ks * kbytes; }
;     DI size_t boff(const Unit& u, size_t tstep) const { return (size_t)u.pn * tstep + (size_t)u.ks * kbytes; }
;     DI bool next(int i, Unit& u) const { Unit t; if (!S.next(i / 3, t)) return false; u.pm = t.pm; u.pn = t.pn; u.ks = i % 3; return true; }
;     DI size_t aoff(const Unit& u, size_t tstep) const { return (u.ks < 2 ? offU : offOA) + (size_t)u.pm * tstep; }
; #define PG8_LDA(dst, b, h) do { _Pragma("unroll") for (int m = 0; m < 4; ++m) _Pragma("unroll") for (int k = 0; k < 2; ++k) dst[m][k] = *(const LAS bf16x8*)(lds + PG8_SA(b, h) + aoff + m * 2048 + k * 1024); } while (0)
; template <class Epi, class Sched>
; DI void gemm_phase(LAS unsigned char* lds, const Gemm g, const Sched& S, const Epi& E) {
;     ...
;         const bool has_next = S.next(ui + 1, nxt);
;         const char* nA = has_next ? (const char*)g.A + S.aoff(nxt, tstep) : cA; const char* nB = has_next ? (const char*)g.Bt + S.boff(nxt, tstep) : cB;
;         for (int t = 0; t < nt; t += 2) {
;             if constexpr (Epi::HAS_MID) { if (t == E.mid_t(nt)) { int fr3 = fr, fq3 = fq; asm volatile("" : "+v"(fr3), "+v"(fq3)); E.mid(acc, cur, wr, wc, fr3, fq3); } }
;             const bool last = (t == nt - 2);
;             const char* a1 = cA + (size_t)(t + 1) * kstep;
;             const char* a2 = last ? nA : cA + (size_t)(t + 2) * kstep; const char* b2 = last ? nB : cB + (size_t)(t + 2) * kstep;
;             const char* a3 = a2 + kstep; const char* b3 = b2 + kstep;
;             PG8_LDB(B0, 0, 0); PG8_SCHED; PG8_LDA(At, 0, 0); PG8_STAGE(PG8_SA(1, 1), a1 + hstep, voffA);
;             PG8_WAIT_L(8); PG8_BAR; PG8_WAIT_L(0); PG8_MMA(0, 0, At, B0); PG8_BAR; PG8_SCHED;
;             PG8_LDB(B1, 0, 1); PG8_STAGE(PG8_SB(0, 0), b2, voffB);
;             PG8_BAR; PG8_WAIT_L(0); PG8_MMA(0, 1, At, B1); PG8_BAR;
;             PG8_LDA(At, 0, 1); PG8_STAGE(PG8_SA(0, 0), a2, voffA);
;             PG8_BAR; PG8_WAIT_L(0); PG8_MMA(1, 0, At, B0); PG8_BAR; PG8_SCHED;
.LBB0_218:
	s_ashr_i32 s17, s16, 31
	s_lshl_b64 s[0:1], s[16:17], 20
	v_cmp_lt_i64_e32 vcc, s[18:19], v[140:141]
	s_add_u32 s18, s47, s0
	s_addc_u32 s19, s48, s1
	s_and_b64 s[0:1], vcc, exec
	s_cselect_b32 s17, s19, s41
	s_cselect_b32 s65, s18, s40
	s_ashr_i32 s15, s14, 31
	s_lshl_b64 s[0:1], s[14:15], 20
	s_add_u32 s36, s49, s0
	s_addc_u32 s37, s50, s1
	s_and_b64 s[0:1], vcc, exec
	s_cselect_b32 s15, s37, s43
	s_cselect_b32 s66, s36, s42
	s_add_u32 s40, s40, 0x80080
	s_addc_u32 s41, s41, 0
	s_add_u32 s67, s42, 0x100
	v_mov_b32_e32 v0, 0
	s_addc_u32 s68, s43, 0
	s_mov_b32 s69, -2
	ds_read_b128 v[150:153], v147
	ds_read_b128 v[154:157], v147 offset:1024
	ds_read_b128 v[162:165], v147 offset:2048
	ds_read_b128 v[166:169], v147 offset:3072
	s_add_u32 s0, s40, 0xfff80080
	s_addc_u32 s1, s41, -1
	s_cmp_eq_u32 s69, 28
	s_cselect_b32 s45, s17, s1
	s_cselect_b32 s44, s65, s0
	s_cselect_b32 s43, s15, s68
	s_cselect_b32 s42, s66, s67
	s_add_i32 m0, s39, 0xc000
	ds_read_b128 v[170:173], v148
	ds_read_b128 v[174:177], v148 offset:1024
	ds_read_b128 v[178:181], v148 offset:2048
	ds_read_b128 v[188:191], v148 offset:3072
	ds_read_b128 v[194:197], v148 offset:4096
	ds_read_b128 v[198:201], v148 offset:5120
	ds_read_b128 v[202:205], v148 offset:6144
	global_load_lds_dwordx4 v136, s[40:41]
	s_add_i32 m0, s39, 0xe000
	ds_read_b128 v[206:209], v148 offset:7168
	global_load_lds_dwordx4 v138, s[40:41]
	s_waitcnt lgkmcnt(8)
	s_barrier
	s_waitcnt lgkmcnt(0)
	s_setprio 1
	v_mfma_f32_16x16x32_bf16 v[124:127], v[150:153], v[170:173], 0
	v_mfma_f32_16x16x32_bf16 v[120:123], v[162:165], v[170:173], 0
	v_mfma_f32_16x16x32_bf16 v[108:111], v[150:153], v[178:181], 0
	v_mfma_f32_16x16x32_bf16 v[104:107], v[162:165], v[178:181], 0
	v_mfma_f32_16x16x32_bf16 v[92:95], v[150:153], v[194:197], 0
	v_mfma_f32_16x16x32_bf16 v[88:91], v[162:165], v[194:197], 0
	v_mfma_f32_16x16x32_bf16 v[76:79], v[150:153], v[202:205], 0
	v_mfma_f32_16x16x32_bf16 v[72:75], v[162:165], v[202:205], 0
	v_mfma_f32_16x16x32_bf16 v[124:127], v[154:157], v[174:177], v[124:127]
	v_mfma_f32_16x16x32_bf16 v[120:123], v[166:169], v[174:177], v[120:123]
	v_mfma_f32_16x16x32_bf16 v[108:111], v[154:157], v[188:191], v[108:111]
	v_mfma_f32_16x16x32_bf16 v[104:107], v[166:169], v[188:191], v[104:107]
	v_mfma_f32_16x16x32_bf16 v[92:95], v[154:157], v[198:201], v[92:95]
	v_mfma_f32_16x16x32_bf16 v[88:91], v[166:169], v[198:201], v[88:91]
	v_mfma_f32_16x16x32_bf16 v[76:79], v[154:157], v[206:209], v[76:79]
	v_mfma_f32_16x16x32_bf16 v[72:75], v[166:169], v[206:209], v[72:75]
	s_setprio 0
	s_barrier
	s_add_i32 s0, s34, s52
	s_mov_b32 m0, s0
	ds_read_b128 v[210:213], v149
	ds_read_b128 v[214:217], v149 offset:1024
	ds_read_b128 v[218:221], v149 offset:2048
	global_load_lds_dwordx4 v130, s[42:43]
	s_add_i32 m0, s0, 0x2000
	ds_read_b128 v[222:225], v149 offset:3072
	global_load_lds_dwordx4 v134, s[42:43]
	s_barrier
	s_waitcnt lgkmcnt(0)
	s_setprio 1
	v_mfma_f32_16x16x32_bf16 v[116:119], v[210:213], v[170:173], 0
	v_mfma_f32_16x16x32_bf16 v[112:115], v[218:221], v[170:173], 0
	v_mfma_f32_16x16x32_bf16 v[100:103], v[210:213], v[178:181], 0
	v_mfma_f32_16x16x32_bf16 v[96:99], v[218:221], v[178:181], 0
	v_mfma_f32_16x16x32_bf16 v[84:87], v[210:213], v[194:197], 0
	v_mfma_f32_16x16x32_bf16 v[80:83], v[218:221], v[194:197], 0
	v_mfma_f32_16x16x32_bf16 v[68:71], v[210:213], v[202:205], 0
	v_mfma_f32_16x16x32_bf16 v[64:67], v[218:221], v[202:205], 0
	v_mfma_f32_16x16x32_bf16 v[116:119], v[214:217], v[174:177], v[116:119]
	v_mfma_f32_16x16x32_bf16 v[112:115], v[222:225], v[174:177], v[112:115]
	v_mfma_f32_16x16x32_bf16 v[100:103], v[214:217], v[188:191], v[100:103]
	v_mfma_f32_16x16x32_bf16 v[96:99], v[222:225], v[188:191], v[96:99]
	v_mfma_f32_16x16x32_bf16 v[84:87], v[214:217], v[198:201], v[84:87]
	v_mfma_f32_16x16x32_bf16 v[80:83], v[222:225], v[198:201], v[80:83]
	v_mfma_f32_16x16x32_bf16 v[68:71], v[214:217], v[206:209], v[68:71]
	v_mfma_f32_16x16x32_bf16 v[64:67], v[222:225], v[206:209], v[64:67]
	s_setprio 0
	s_mov_b32 m0, s39
	s_barrier
	ds_read_b128 v[170:173], v148 offset:16384
	ds_read_b128 v[174:177], v148 offset:17408
	ds_read_b128 v[178:181], v148 offset:18432
	ds_read_b128 v[188:191], v148 offset:19456
	ds_read_b128 v[194:197], v148 offset:20480
	ds_read_b128 v[198:201], v148 offset:21504
	ds_read_b128 v[202:205], v148 offset:22528
	global_load_lds_dwordx4 v128, s[44:45]
	s_mov_b32 m0, s53
	ds_read_b128 v[206:209], v148 offset:23552
	global_load_lds_dwordx4 v132, s[44:45]
	s_barrier
	s_waitcnt lgkmcnt(0)
	s_setprio 1
	v_mfma_f32_16x16x32_bf16 v[60:63], v[150:153], v[170:173], 0
	v_mfma_f32_16x16x32_bf16 v[56:59], v[162:165], v[170:173], 0
	v_mfma_f32_16x16x32_bf16 v[44:47], v[150:153], v[178:181], 0
	v_mfma_f32_16x16x32_bf16 v[40:43], v[162:165], v[178:181], 0
	v_mfma_f32_16x16x32_bf16 v[28:31], v[150:153], v[194:197], 0
	v_mfma_f32_16x16x32_bf16 v[24:27], v[162:165], v[194:197], 0
	v_mfma_f32_16x16x32_bf16 v[12:15], v[150:153], v[202:205], 0
	v_mfma_f32_16x16x32_bf16 v[8:11], v[162:165], v[202:205], 0
	v_mfma_f32_16x16x32_bf16 v[60:63], v[154:157], v[174:177], v[60:63]
	v_mfma_f32_16x16x32_bf16 v[56:59], v[166:169], v[174:177], v[56:59]
	v_mfma_f32_16x16x32_bf16 v[44:47], v[154:157], v[188:191], v[44:47]
	v_mfma_f32_16x16x32_bf16 v[40:43], v[166:169], v[188:191], v[40:43]
	v_mfma_f32_16x16x32_bf16 v[28:31], v[154:157], v[198:201], v[28:31]
	v_mfma_f32_16x16x32_bf16 v[24:27], v[166:169], v[198:201], v[24:27]
	v_mfma_f32_16x16x32_bf16 v[12:15], v[154:157], v[206:209], v[12:15]
	v_mfma_f32_16x16x32_bf16 v[8:11], v[166:169], v[206:209], v[8:11]
	s_setprio 0
	s_barrier
; #define PG8_STAGE(bufoff, gbase, voff) do { _Pragma("unroll") for (int _i = 0; _i < 2; ++_i) \
;         __builtin_amdgcn_global_load_lds((const unsigned*)((const char*)(gbase) + (voff)[_i]), (LAS unsigned*)(lds + (bufoff) + ldsw + _i * 8192), 16, 0, 0); } while (0)
; #define PG8_LDA(dst, b, h) do { _Pragma("unroll") for (int m = 0; m < 4; ++m) _Pragma("unroll") for (int k = 0; k < 2; ++k) dst[m][k] = *(const LAS bf16x8*)(lds + PG8_SA(b, h) + aoff + m * 2048 + k * 1024); } while (0)
; #define PG8_LDB(dst, b, h) do { _Pragma("unroll") for (int n = 0; n < 2; ++n) _Pragma("unroll") for (int k = 0; k < 2; ++k) dst[n][k] = *(const LAS bf16x8*)(lds + PG8_SB(b, h) + boff + n * 2048 + k * 1024); } while (0)
; #define PG8_MMA(ai, bj, At, Bt) do { __builtin_amdgcn_s_setprio(1); _Pragma("unroll") for (int m = 0; m < 4; ++m) _Pragma("unroll") for (int n = 0; n < 2; ++n) _Pragma("unroll") for (int k = 0; k < 2; ++k) \
;         acc[ai][bj][m][n] = __builtin_amdgcn_mfma_f32_16x16x32_bf16(Bt[n][k], At[m][k], acc[ai][bj][m][n], 0, 0, 0); __builtin_amdgcn_s_setprio(0); } while (0)
; #define PG8_WAIT_V(n) asm volatile("s_waitcnt vmcnt(" #n ")" ::: "memory")
; #define PG8_WAIT_L(n) asm volatile("s_waitcnt lgkmcnt(" #n ")" ::: "memory")
; #define PG8_BAR __builtin_amdgcn_s_barrier()
; #define PG8_SCHED __builtin_amdgcn_sched_barrier(0)
; template <class Epi, class Sched>
; DI void gemm_phase(LAS unsigned char* lds, const Gemm g, const Sched& S, const Epi& E) {
;     ...
;             PG8_STAGE(PG8_SB(0, 1), b2 + hstep, voffB);
;             PG8_WAIT_V(6); PG8_BAR; PG8_MMA(1, 1, At, B1); PG8_BAR;
;             PG8_LDB(B0, 1, 0); PG8_SCHED; PG8_LDA(At, 1, 0); PG8_STAGE(PG8_SA(0, 1), a2 + hstep, voffA);
;             PG8_WAIT_L(8); PG8_BAR; PG8_WAIT_L(0); PG8_MMA(0, 0, At, B0); PG8_BAR; PG8_SCHED;
;             PG8_LDB(B1, 1, 1); PG8_STAGE(PG8_SB(1, 0), b3, voffB);
;             PG8_BAR; PG8_WAIT_L(0); PG8_MMA(0, 1, At, B1); PG8_BAR;
;             PG8_LDA(At, 1, 1); PG8_STAGE(PG8_SA(1, 0), a3, voffA);
	s_add_u32 s0, s42, 0x80000
	s_addc_u32 s1, s43, 0
	s_add_i32 s4, s35, s52
	s_mov_b32 m0, s4
	s_nop 0
	global_load_lds_dwordx4 v130, s[0:1]
	s_add_i32 m0, s4, 0x2000
	s_nop 0
	global_load_lds_dwordx4 v134, s[0:1]
	s_waitcnt vmcnt(6)
	s_barrier
	s_setprio 1
	v_mfma_f32_16x16x32_bf16 v[52:55], v[210:213], v[170:173], 0
	v_mfma_f32_16x16x32_bf16 v[48:51], v[218:221], v[170:173], 0
	v_mfma_f32_16x16x32_bf16 v[36:39], v[210:213], v[178:181], 0
	v_mfma_f32_16x16x32_bf16 v[32:35], v[218:221], v[178:181], 0
	v_mfma_f32_16x16x32_bf16 v[20:23], v[210:213], v[194:197], 0
	v_mfma_f32_16x16x32_bf16 v[16:19], v[218:221], v[194:197], 0
	v_mfma_f32_16x16x32_bf16 v[4:7], v[210:213], v[202:205], 0
	v_mfma_f32_16x16x32_bf16 v[0:3], v[218:221], v[202:205], 0
	v_mfma_f32_16x16x32_bf16 v[52:55], v[214:217], v[174:177], v[52:55]
	v_mfma_f32_16x16x32_bf16 v[48:51], v[222:225], v[174:177], v[48:51]
	v_mfma_f32_16x16x32_bf16 v[36:39], v[214:217], v[188:191], v[36:39]
	v_mfma_f32_16x16x32_bf16 v[32:35], v[222:225], v[188:191], v[32:35]
	v_mfma_f32_16x16x32_bf16 v[20:23], v[214:217], v[198:201], v[20:23]
	v_mfma_f32_16x16x32_bf16 v[16:19], v[222:225], v[198:201], v[16:19]
	v_mfma_f32_16x16x32_bf16 v[4:7], v[214:217], v[206:209], v[4:7]
	v_mfma_f32_16x16x32_bf16 v[0:3], v[222:225], v[206:209], v[0:3]
	s_setprio 0
	s_add_i32 s4, 0, 0x18000
	v_add_u32_e32 v158, s4, v146
	s_barrier
	ds_read_b128 v[150:153], v158
	ds_read_b128 v[154:157], v158 offset:1024
	ds_read_b128 v[162:165], v158 offset:2048
	ds_read_b128 v[166:169], v158 offset:3072
	s_add_u32 s0, s44, 0x80000
	s_addc_u32 s1, s45, 0
	s_mov_b32 m0, s54
	ds_read_b128 v[170:173], v148 offset:32768
	ds_read_b128 v[174:177], v148 offset:33792
	ds_read_b128 v[178:181], v148 offset:34816
	ds_read_b128 v[188:191], v148 offset:35840
	ds_read_b128 v[194:197], v148 offset:36864
	ds_read_b128 v[198:201], v148 offset:37888
	ds_read_b128 v[202:205], v148 offset:38912
	global_load_lds_dwordx4 v128, s[0:1]
	s_mov_b32 m0, s55
	ds_read_b128 v[206:209], v148 offset:39936
	global_load_lds_dwordx4 v132, s[0:1]
	s_waitcnt lgkmcnt(8)
	s_barrier
	s_waitcnt lgkmcnt(0)
	s_setprio 1
	v_mfma_f32_16x16x32_bf16 v[124:127], v[150:153], v[170:173], v[124:127]
	v_mfma_f32_16x16x32_bf16 v[120:123], v[162:165], v[170:173], v[120:123]
	v_mfma_f32_16x16x32_bf16 v[108:111], v[150:153], v[178:181], v[108:111]
	v_mfma_f32_16x16x32_bf16 v[104:107], v[162:165], v[178:181], v[104:107]
	v_mfma_f32_16x16x32_bf16 v[92:95], v[150:153], v[194:197], v[92:95]
	v_mfma_f32_16x16x32_bf16 v[88:91], v[162:165], v[194:197], v[88:91]
	v_mfma_f32_16x16x32_bf16 v[76:79], v[150:153], v[202:205], v[76:79]
	v_mfma_f32_16x16x32_bf16 v[72:75], v[162:165], v[202:205], v[72:75]
	v_mfma_f32_16x16x32_bf16 v[124:127], v[154:157], v[174:177], v[124:127]
	v_mfma_f32_16x16x32_bf16 v[120:123], v[166:169], v[174:177], v[120:123]
	v_mfma_f32_16x16x32_bf16 v[108:111], v[154:157], v[188:191], v[108:111]
	v_mfma_f32_16x16x32_bf16 v[104:107], v[166:169], v[188:191], v[104:107]
	v_mfma_f32_16x16x32_bf16 v[92:95], v[154:157], v[198:201], v[92:95]
	v_mfma_f32_16x16x32_bf16 v[88:91], v[166:169], v[198:201], v[88:91]
	v_mfma_f32_16x16x32_bf16 v[76:79], v[154:157], v[206:209], v[76:79]
	v_mfma_f32_16x16x32_bf16 v[72:75], v[166:169], v[206:209], v[72:75]
	s_setprio 0
	s_barrier
	s_add_i32 s5, 0, 0x1c000
	s_add_i32 s0, s4, s52
	v_add_u32_e32 v159, s5, v146
	s_add_i32 m0, s0, 0xffffff80
	ds_read_b128 v[210:213], v159
	ds_read_b128 v[214:217], v159 offset:1024
	ds_read_b128 v[218:221], v159 offset:2048
	global_load_lds_dwordx4 v130, s[42:43] offset:128
	s_add_i32 m0, s0, 0x1f80
	ds_read_b128 v[222:225], v159 offset:3072
	global_load_lds_dwordx4 v134, s[42:43] offset:128
	s_barrier
	s_waitcnt lgkmcnt(0)
	s_setprio 1
	v_mfma_f32_16x16x32_bf16 v[116:119], v[210:213], v[170:173], v[116:119]
	v_mfma_f32_16x16x32_bf16 v[112:115], v[218:221], v[170:173], v[112:115]
	v_mfma_f32_16x16x32_bf16 v[100:103], v[210:213], v[178:181], v[100:103]
	v_mfma_f32_16x16x32_bf16 v[96:99], v[218:221], v[178:181], v[96:99]
	v_mfma_f32_16x16x32_bf16 v[84:87], v[210:213], v[194:197], v[84:87]
	v_mfma_f32_16x16x32_bf16 v[80:83], v[218:221], v[194:197], v[80:83]
	v_mfma_f32_16x16x32_bf16 v[68:71], v[210:213], v[202:205], v[68:71]
	v_mfma_f32_16x16x32_bf16 v[64:67], v[218:221], v[202:205], v[64:67]
	v_mfma_f32_16x16x32_bf16 v[116:119], v[214:217], v[174:177], v[116:119]
	v_mfma_f32_16x16x32_bf16 v[112:115], v[222:225], v[174:177], v[112:115]
	v_mfma_f32_16x16x32_bf16 v[100:103], v[214:217], v[188:191], v[100:103]
	v_mfma_f32_16x16x32_bf16 v[96:99], v[222:225], v[188:191], v[96:99]
	v_mfma_f32_16x16x32_bf16 v[84:87], v[214:217], v[198:201], v[84:87]
	v_mfma_f32_16x16x32_bf16 v[80:83], v[222:225], v[198:201], v[80:83]
	v_mfma_f32_16x16x32_bf16 v[68:71], v[214:217], v[206:209], v[68:71]
	v_mfma_f32_16x16x32_bf16 v[64:67], v[222:225], v[206:209], v[64:67]
	s_setprio 0
	s_add_i32 m0, s59, 0xffffff80
	s_barrier
	ds_read_b128 v[170:173], v148 offset:49152
	ds_read_b128 v[174:177], v148 offset:50176
	ds_read_b128 v[178:181], v148 offset:51200
	ds_read_b128 v[188:191], v148 offset:52224
	ds_read_b128 v[194:197], v148 offset:53248
	ds_read_b128 v[198:201], v148 offset:54272
	ds_read_b128 v[202:205], v148 offset:55296
	global_load_lds_dwordx4 v128, s[44:45] offset:128
	s_add_i32 m0, s60, 0xffffff80
	ds_read_b128 v[206:209], v148 offset:56320
	global_load_lds_dwordx4 v132, s[44:45] offset:128
	s_barrier
; #define PG8_STAGE(bufoff, gbase, voff) do { _Pragma("unroll") for (int _i = 0; _i < 2; ++_i) \
;         __builtin_amdgcn_global_load_lds((const unsigned*)((const char*)(gbase) + (voff)[_i]), (LAS unsigned*)(lds + (bufoff) + ldsw + _i * 8192), 16, 0, 0); } while (0)
; #define PG8_LDA(dst, b, h) do { _Pragma("unroll") for (int m = 0; m < 4; ++m) _Pragma("unroll") for (int k = 0; k < 2; ++k) dst[m][k] = *(const LAS bf16x8*)(lds + PG8_SA(b, h) + aoff + m * 2048 + k * 1024); } while (0)
; #define PG8_LDB(dst, b, h) do { _Pragma("unroll") for (int n = 0; n < 2; ++n) _Pragma("unroll") for (int k = 0; k < 2; ++k) dst[n][k] = *(const LAS bf16x8*)(lds + PG8_SB(b, h) + boff + n * 2048 + k * 1024); } while (0)
; #define PG8_WAIT_V(n) asm volatile("s_waitcnt vmcnt(" #n ")" ::: "memory")
; #define PG8_WAIT_L(n) asm volatile("s_waitcnt lgkmcnt(" #n ")" ::: "memory")
; #define PG8_BAR __builtin_amdgcn_s_barrier()
; #define PG8_SCHED __builtin_amdgcn_sched_barrier(0)
; template <class Epi, class Sched>
; DI void gemm_phase(LAS unsigned char* lds, const Gemm g, const Sched& S, const Epi& E) {
;     ...
;             PG8_LDB(B0, 0, 0); PG8_SCHED; PG8_LDA(At, 0, 0); PG8_STAGE(PG8_SA(1, 1), a1 + hstep, voffA);
;             PG8_WAIT_L(8); PG8_BAR; PG8_WAIT_L(0); PG8_MMA(0, 0, At, B0); PG8_BAR; PG8_SCHED;
;             PG8_LDB(B1, 0, 1); PG8_STAGE(PG8_SB(0, 0), b2, voffB);
;             PG8_BAR; PG8_WAIT_L(0); PG8_MMA(0, 1, At, B1); PG8_BAR;
;             PG8_LDA(At, 0, 1); PG8_STAGE(PG8_SA(0, 0), a2, voffA);
;             PG8_BAR; PG8_WAIT_L(0); PG8_MMA(1, 0, At, B0); PG8_BAR; PG8_SCHED;
;             PG8_STAGE(PG8_SB(0, 1), b2 + hstep, voffB);
;             PG8_WAIT_V(6); PG8_BAR; PG8_MMA(1, 1, At, B1); PG8_BAR;
;             PG8_LDB(B0, 1, 0); PG8_SCHED; PG8_LDA(At, 1, 0); PG8_STAGE(PG8_SA(0, 1), a2 + hstep, voffA);
;             PG8_WAIT_L(8); PG8_BAR; PG8_WAIT_L(0); PG8_MMA(0, 0, At, B0); PG8_BAR; PG8_SCHED;
;             PG8_LDB(B1, 1, 1); PG8_STAGE(PG8_SB(1, 0), b3, voffB);
;             PG8_BAR; PG8_WAIT_L(0); PG8_MMA(0, 1, At, B1); PG8_BAR;
;             PG8_LDA(At, 1, 1); PG8_STAGE(PG8_SA(1, 0), a3, voffA);
;             PG8_BAR; PG8_WAIT_L(0); PG8_MMA(1, 0, At, B0); PG8_BAR; PG8_SCHED;
;             PG8_STAGE(PG8_SB(1, 1), b3 + hstep, voffB);
;             PG8_WAIT_V(6); PG8_BAR; PG8_MMA(1, 1, At, B1); PG8_BAR;
	s_waitcnt lgkmcnt(0)
	s_setprio 1
	v_mfma_f32_16x16x32_bf16 v[60:63], v[150:153], v[170:173], v[60:63]
	v_mfma_f32_16x16x32_bf16 v[56:59], v[162:165], v[170:173], v[56:59]
	v_mfma_f32_16x16x32_bf16 v[44:47], v[150:153], v[178:181], v[44:47]
	v_mfma_f32_16x16x32_bf16 v[40:43], v[162:165], v[178:181], v[40:43]
	v_mfma_f32_16x16x32_bf16 v[28:31], v[150:153], v[194:197], v[28:31]
	v_mfma_f32_16x16x32_bf16 v[24:27], v[162:165], v[194:197], v[24:27]
	v_mfma_f32_16x16x32_bf16 v[12:15], v[150:153], v[202:205], v[12:15]
	v_mfma_f32_16x16x32_bf16 v[8:11], v[162:165], v[202:205], v[8:11]
	v_mfma_f32_16x16x32_bf16 v[60:63], v[154:157], v[174:177], v[60:63]
	v_mfma_f32_16x16x32_bf16 v[56:59], v[166:169], v[174:177], v[56:59]
	v_mfma_f32_16x16x32_bf16 v[44:47], v[154:157], v[188:191], v[44:47]
	v_mfma_f32_16x16x32_bf16 v[40:43], v[166:169], v[188:191], v[40:43]
	v_mfma_f32_16x16x32_bf16 v[28:31], v[154:157], v[198:201], v[28:31]
	v_mfma_f32_16x16x32_bf16 v[24:27], v[166:169], v[198:201], v[24:27]
	v_mfma_f32_16x16x32_bf16 v[12:15], v[154:157], v[206:209], v[12:15]
	v_mfma_f32_16x16x32_bf16 v[8:11], v[166:169], v[206:209], v[8:11]
	s_setprio 0
	s_barrier
	s_add_u32 s0, s42, 0x80080
	s_addc_u32 s1, s43, 0
	s_add_i32 s4, s5, s52
	s_mov_b32 m0, s4
	s_nop 0
	global_load_lds_dwordx4 v130, s[0:1]
	s_add_i32 m0, s4, 0x2000
	s_nop 0
	global_load_lds_dwordx4 v134, s[0:1]
	s_waitcnt vmcnt(6)
	s_barrier
	s_setprio 1
	v_mfma_f32_16x16x32_bf16 v[52:55], v[210:213], v[170:173], v[52:55]
	v_mfma_f32_16x16x32_bf16 v[48:51], v[218:221], v[170:173], v[48:51]
	v_mfma_f32_16x16x32_bf16 v[36:39], v[210:213], v[178:181], v[36:39]
	v_mfma_f32_16x16x32_bf16 v[32:35], v[218:221], v[178:181], v[32:35]
	v_mfma_f32_16x16x32_bf16 v[20:23], v[210:213], v[194:197], v[20:23]
	v_mfma_f32_16x16x32_bf16 v[16:19], v[218:221], v[194:197], v[16:19]
	v_mfma_f32_16x16x32_bf16 v[4:7], v[210:213], v[202:205], v[4:7]
	v_mfma_f32_16x16x32_bf16 v[0:3], v[218:221], v[202:205], v[0:3]
	v_mfma_f32_16x16x32_bf16 v[52:55], v[214:217], v[174:177], v[52:55]
	v_mfma_f32_16x16x32_bf16 v[48:51], v[222:225], v[174:177], v[48:51]
	v_mfma_f32_16x16x32_bf16 v[36:39], v[214:217], v[188:191], v[36:39]
	v_mfma_f32_16x16x32_bf16 v[32:35], v[222:225], v[188:191], v[32:35]
	v_mfma_f32_16x16x32_bf16 v[20:23], v[214:217], v[198:201], v[20:23]
	v_mfma_f32_16x16x32_bf16 v[16:19], v[222:225], v[198:201], v[16:19]
	v_mfma_f32_16x16x32_bf16 v[4:7], v[214:217], v[206:209], v[4:7]
	v_mfma_f32_16x16x32_bf16 v[0:3], v[222:225], v[206:209], v[0:3]
	s_setprio 0
	s_add_i32 s69, s69, 2
	s_add_u32 s40, s40, 0x100
	s_addc_u32 s41, s41, 0
	s_add_u32 s67, s67, 0x100
	s_addc_u32 s68, s68, 0
	s_cmp_gt_u32 s69, 29
	s_barrier
	s_cbranch_scc0 .LBB0_219
	s_branch .Lpeel_done_219
.LBB0_219:
	ds_read_b128 v[150:153], v147
	ds_read_b128 v[154:157], v147 offset:1024
	ds_read_b128 v[162:165], v147 offset:2048
	ds_read_b128 v[166:169], v147 offset:3072
	s_add_u32 s0, s40, 0xfff80080
	s_addc_u32 s1, s41, -1
	s_cmp_eq_u32 s69, 28
	s_cselect_b32 s45, s17, s1
	s_cselect_b32 s44, s65, s0
	s_cselect_b32 s43, s15, s68
	s_cselect_b32 s42, s66, s67
	s_add_i32 m0, s39, 0xc000
	ds_read_b128 v[170:173], v148
	ds_read_b128 v[174:177], v148 offset:1024
	ds_read_b128 v[178:181], v148 offset:2048
	ds_read_b128 v[188:191], v148 offset:3072
	ds_read_b128 v[194:197], v148 offset:4096
	ds_read_b128 v[198:201], v148 offset:5120
	ds_read_b128 v[202:205], v148 offset:6144
	global_load_lds_dwordx4 v136, s[40:41]
	s_add_i32 m0, s39, 0xe000
	ds_read_b128 v[206:209], v148 offset:7168
	global_load_lds_dwordx4 v138, s[40:41]
	s_waitcnt lgkmcnt(8)
	s_barrier
	s_waitcnt lgkmcnt(0)
	s_setprio 1
	v_mfma_f32_16x16x32_bf16 v[124:127], v[150:153], v[170:173], v[124:127]
	v_mfma_f32_16x16x32_bf16 v[120:123], v[162:165], v[170:173], v[120:123]
	v_mfma_f32_16x16x32_bf16 v[108:111], v[150:153], v[178:181], v[108:111]
	v_mfma_f32_16x16x32_bf16 v[104:107], v[162:165], v[178:181], v[104:107]
	v_mfma_f32_16x16x32_bf16 v[92:95], v[150:153], v[194:197], v[92:95]
	v_mfma_f32_16x16x32_bf16 v[88:91], v[162:165], v[194:197], v[88:91]
	v_mfma_f32_16x16x32_bf16 v[76:79], v[150:153], v[202:205], v[76:79]
	v_mfma_f32_16x16x32_bf16 v[72:75], v[162:165], v[202:205], v[72:75]
	v_mfma_f32_16x16x32_bf16 v[124:127], v[154:157], v[174:177], v[124:127]
	v_mfma_f32_16x16x32_bf16 v[120:123], v[166:169], v[174:177], v[120:123]
	v_mfma_f32_16x16x32_bf16 v[108:111], v[154:157], v[188:191], v[108:111]
	v_mfma_f32_16x16x32_bf16 v[104:107], v[166:169], v[188:191], v[104:107]
	v_mfma_f32_16x16x32_bf16 v[92:95], v[154:157], v[198:201], v[92:95]
	v_mfma_f32_16x16x32_bf16 v[88:91], v[166:169], v[198:201], v[88:91]
	v_mfma_f32_16x16x32_bf16 v[76:79], v[154:157], v[206:209], v[76:79]
	v_mfma_f32_16x16x32_bf16 v[72:75], v[166:169], v[206:209], v[72:75]
	s_setprio 0
	s_barrier
	s_add_i32 s0, s34, s52
	s_mov_b32 m0, s0
	ds_read_b128 v[210:213], v149
	ds_read_b128 v[214:217], v149 offset:1024
	ds_read_b128 v[218:221], v149 offset:2048
	global_load_lds_dwordx4 v130, s[42:43]
	s_add_i32 m0, s0, 0x2000
	ds_read_b128 v[222:225], v149 offset:3072
	global_load_lds_dwordx4 v134, s[42:43]
	s_barrier
; #define PG8_STAGE(bufoff, gbase, voff) do { _Pragma("unroll") for (int _i = 0; _i < 2; ++_i) \
;         __builtin_amdgcn_global_load_lds((const unsigned*)((const char*)(gbase) + (voff)[_i]), (LAS unsigned*)(lds + (bufoff) + ldsw + _i * 8192), 16, 0, 0); } while (0)
; #define PG8_LDA(dst, b, h) do { _Pragma("unroll") for (int m = 0; m < 4; ++m) _Pragma("unroll") for (int k = 0; k < 2; ++k) dst[m][k] = *(const LAS bf16x8*)(lds + PG8_SA(b, h) + aoff + m * 2048 + k * 1024); } while (0)
; #define PG8_LDB(dst, b, h) do { _Pragma("unroll") for (int n = 0; n < 2; ++n) _Pragma("unroll") for (int k = 0; k < 2; ++k) dst[n][k] = *(const LAS bf16x8*)(lds + PG8_SB(b, h) + boff + n * 2048 + k * 1024); } while (0)
; #define PG8_MMA(ai, bj, At, Bt) do { __builtin_amdgcn_s_setprio(1); _Pragma("unroll") for (int m = 0; m < 4; ++m) _Pragma("unroll") for (int n = 0; n < 2; ++n) _Pragma("unroll") for (int k = 0; k < 2; ++k) \
;         acc[ai][bj][m][n] = __builtin_amdgcn_mfma_f32_16x16x32_bf16(Bt[n][k], At[m][k], acc[ai][bj][m][n], 0, 0, 0); __builtin_amdgcn_s_setprio(0); } while (0)
; #define PG8_WAIT_V(n) asm volatile("s_waitcnt vmcnt(" #n ")" ::: "memory")
; #define PG8_WAIT_L(n) asm volatile("s_waitcnt lgkmcnt(" #n ")" ::: "memory")
; #define PG8_BAR __builtin_amdgcn_s_barrier()
; #define PG8_SCHED __builtin_amdgcn_sched_barrier(0)
; template <class Epi, class Sched>
; DI void gemm_phase(LAS unsigned char* lds, const Gemm g, const Sched& S, const Epi& E) {
;     ...
;             PG8_BAR; PG8_WAIT_L(0); PG8_MMA(0, 1, At, B1); PG8_BAR;
;             PG8_LDA(At, 0, 1); PG8_STAGE(PG8_SA(0, 0), a2, voffA);
;             PG8_BAR; PG8_WAIT_L(0); PG8_MMA(1, 0, At, B0); PG8_BAR; PG8_SCHED;
;             PG8_STAGE(PG8_SB(0, 1), b2 + hstep, voffB);
;             PG8_WAIT_V(6); PG8_BAR; PG8_MMA(1, 1, At, B1); PG8_BAR;
;             PG8_LDB(B0, 1, 0); PG8_SCHED; PG8_LDA(At, 1, 0); PG8_STAGE(PG8_SA(0, 1), a2 + hstep, voffA);
;             PG8_WAIT_L(8); PG8_BAR; PG8_WAIT_L(0); PG8_MMA(0, 0, At, B0); PG8_BAR; PG8_SCHED;
	s_waitcnt lgkmcnt(0)
	s_setprio 1
	v_mfma_f32_16x16x32_bf16 v[116:119], v[210:213], v[170:173], v[116:119]
	v_mfma_f32_16x16x32_bf16 v[112:115], v[218:221], v[170:173], v[112:115]
	v_mfma_f32_16x16x32_bf16 v[100:103], v[210:213], v[178:181], v[100:103]
	v_mfma_f32_16x16x32_bf16 v[96:99], v[218:221], v[178:181], v[96:99]
	v_mfma_f32_16x16x32_bf16 v[84:87], v[210:213], v[194:197], v[84:87]
	v_mfma_f32_16x16x32_bf16 v[80:83], v[218:221], v[194:197], v[80:83]
	v_mfma_f32_16x16x32_bf16 v[68:71], v[210:213], v[202:205], v[68:71]
	v_mfma_f32_16x16x32_bf16 v[64:67], v[218:221], v[202:205], v[64:67]
	v_mfma_f32_16x16x32_bf16 v[116:119], v[214:217], v[174:177], v[116:119]
	v_mfma_f32_16x16x32_bf16 v[112:115], v[222:225], v[174:177], v[112:115]
	v_mfma_f32_16x16x32_bf16 v[100:103], v[214:217], v[188:191], v[100:103]
	v_mfma_f32_16x16x32_bf16 v[96:99], v[222:225], v[188:191], v[96:99]
	v_mfma_f32_16x16x32_bf16 v[84:87], v[214:217], v[198:201], v[84:87]
	v_mfma_f32_16x16x32_bf16 v[80:83], v[222:225], v[198:201], v[80:83]
	v_mfma_f32_16x16x32_bf16 v[68:71], v[214:217], v[206:209], v[68:71]
	v_mfma_f32_16x16x32_bf16 v[64:67], v[222:225], v[206:209], v[64:67]
	s_setprio 0
	s_mov_b32 m0, s39
	s_barrier
	ds_read_b128 v[170:173], v148 offset:16384
	ds_read_b128 v[174:177], v148 offset:17408
	ds_read_b128 v[178:181], v148 offset:18432
	ds_read_b128 v[188:191], v148 offset:19456
	ds_read_b128 v[194:197], v148 offset:20480
	ds_read_b128 v[198:201], v148 offset:21504
	ds_read_b128 v[202:205], v148 offset:22528
	global_load_lds_dwordx4 v128, s[44:45]
	s_mov_b32 m0, s53
	ds_read_b128 v[206:209], v148 offset:23552
	global_load_lds_dwordx4 v132, s[44:45]
	s_barrier
	s_waitcnt lgkmcnt(0)
	s_setprio 1
	v_mfma_f32_16x16x32_bf16 v[60:63], v[150:153], v[170:173], v[60:63]
	v_mfma_f32_16x16x32_bf16 v[56:59], v[162:165], v[170:173], v[56:59]
	v_mfma_f32_16x16x32_bf16 v[44:47], v[150:153], v[178:181], v[44:47]
	v_mfma_f32_16x16x32_bf16 v[40:43], v[162:165], v[178:181], v[40:43]
	v_mfma_f32_16x16x32_bf16 v[28:31], v[150:153], v[194:197], v[28:31]
	v_mfma_f32_16x16x32_bf16 v[24:27], v[162:165], v[194:197], v[24:27]
	v_mfma_f32_16x16x32_bf16 v[12:15], v[150:153], v[202:205], v[12:15]
	v_mfma_f32_16x16x32_bf16 v[8:11], v[162:165], v[202:205], v[8:11]
	v_mfma_f32_16x16x32_bf16 v[60:63], v[154:157], v[174:177], v[60:63]
	v_mfma_f32_16x16x32_bf16 v[56:59], v[166:169], v[174:177], v[56:59]
	v_mfma_f32_16x16x32_bf16 v[44:47], v[154:157], v[188:191], v[44:47]
	v_mfma_f32_16x16x32_bf16 v[40:43], v[166:169], v[188:191], v[40:43]
	v_mfma_f32_16x16x32_bf16 v[28:31], v[154:157], v[198:201], v[28:31]
	v_mfma_f32_16x16x32_bf16 v[24:27], v[166:169], v[198:201], v[24:27]
	v_mfma_f32_16x16x32_bf16 v[12:15], v[154:157], v[206:209], v[12:15]
	v_mfma_f32_16x16x32_bf16 v[8:11], v[166:169], v[206:209], v[8:11]
	s_setprio 0
	s_barrier
	s_add_u32 s0, s42, 0x80000
	s_addc_u32 s1, s43, 0
	s_add_i32 s4, s35, s52
	s_mov_b32 m0, s4
	s_nop 0
	global_load_lds_dwordx4 v130, s[0:1]
	s_add_i32 m0, s4, 0x2000
	s_nop 0
	global_load_lds_dwordx4 v134, s[0:1]
	s_waitcnt vmcnt(6)
	s_barrier
	s_setprio 1
	v_mfma_f32_16x16x32_bf16 v[52:55], v[210:213], v[170:173], v[52:55]
	v_mfma_f32_16x16x32_bf16 v[48:51], v[218:221], v[170:173], v[48:51]
	v_mfma_f32_16x16x32_bf16 v[36:39], v[210:213], v[178:181], v[36:39]
	v_mfma_f32_16x16x32_bf16 v[32:35], v[218:221], v[178:181], v[32:35]
	v_mfma_f32_16x16x32_bf16 v[20:23], v[210:213], v[194:197], v[20:23]
	v_mfma_f32_16x16x32_bf16 v[16:19], v[218:221], v[194:197], v[16:19]
	v_mfma_f32_16x16x32_bf16 v[4:7], v[210:213], v[202:205], v[4:7]
	v_mfma_f32_16x16x32_bf16 v[0:3], v[218:221], v[202:205], v[0:3]
	v_mfma_f32_16x16x32_bf16 v[52:55], v[214:217], v[174:177], v[52:55]
	v_mfma_f32_16x16x32_bf16 v[48:51], v[222:225], v[174:177], v[48:51]
	v_mfma_f32_16x16x32_bf16 v[36:39], v[214:217], v[188:191], v[36:39]
	v_mfma_f32_16x16x32_bf16 v[32:35], v[222:225], v[188:191], v[32:35]
	v_mfma_f32_16x16x32_bf16 v[20:23], v[214:217], v[198:201], v[20:23]
	v_mfma_f32_16x16x32_bf16 v[16:19], v[222:225], v[198:201], v[16:19]
	v_mfma_f32_16x16x32_bf16 v[4:7], v[214:217], v[206:209], v[4:7]
	v_mfma_f32_16x16x32_bf16 v[0:3], v[222:225], v[206:209], v[0:3]
	s_setprio 0
	s_add_i32 s4, 0, 0x18000
	s_barrier
	ds_read_b128 v[150:153], v158
	ds_read_b128 v[154:157], v158 offset:1024
	ds_read_b128 v[162:165], v158 offset:2048
	ds_read_b128 v[166:169], v158 offset:3072
	s_add_u32 s0, s44, 0x80000
	s_addc_u32 s1, s45, 0
	s_mov_b32 m0, s54
	ds_read_b128 v[170:173], v148 offset:32768
	ds_read_b128 v[174:177], v148 offset:33792
	ds_read_b128 v[178:181], v148 offset:34816
	ds_read_b128 v[188:191], v148 offset:35840
	ds_read_b128 v[194:197], v148 offset:36864
	ds_read_b128 v[198:201], v148 offset:37888
	ds_read_b128 v[202:205], v148 offset:38912
	global_load_lds_dwordx4 v128, s[0:1]
	s_mov_b32 m0, s55
	ds_read_b128 v[206:209], v148 offset:39936
	global_load_lds_dwordx4 v132, s[0:1]
	s_waitcnt lgkmcnt(8)
	s_barrier
; #define PG8_STAGE(bufoff, gbase, voff) do { _Pragma("unroll") for (int _i = 0; _i < 2; ++_i) \
;         __builtin_amdgcn_global_load_lds((const unsigned*)((const char*)(gbase) + (voff)[_i]), (LAS unsigned*)(lds + (bufoff) + ldsw + _i * 8192), 16, 0, 0); } while (0)
; #define PG8_LDA(dst, b, h) do { _Pragma("unroll") for (int m = 0; m < 4; ++m) _Pragma("unroll") for (int k = 0; k < 2; ++k) dst[m][k] = *(const LAS bf16x8*)(lds + PG8_SA(b, h) + aoff + m * 2048 + k * 1024); } while (0)
; #define PG8_LDB(dst, b, h) do { _Pragma("unroll") for (int n = 0; n < 2; ++n) _Pragma("unroll") for (int k = 0; k < 2; ++k) dst[n][k] = *(const LAS bf16x8*)(lds + PG8_SB(b, h) + boff + n * 2048 + k * 1024); } while (0)
; #define PG8_MMA(ai, bj, At, Bt) do { __builtin_amdgcn_s_setprio(1); _Pragma("unroll") for (int m = 0; m < 4; ++m) _Pragma("unroll") for (int n = 0; n < 2; ++n) _Pragma("unroll") for (int k = 0; k < 2; ++k) \
;         acc[ai][bj][m][n] = __builtin_amdgcn_mfma_f32_16x16x32_bf16(Bt[n][k], At[m][k], acc[ai][bj][m][n], 0, 0, 0); __builtin_amdgcn_s_setprio(0); } while (0)
; #define PG8_WAIT_V(n) asm volatile("s_waitcnt vmcnt(" #n ")" ::: "memory")
; #define PG8_WAIT_L(n) asm volatile("s_waitcnt lgkmcnt(" #n ")" ::: "memory")
; #define PG8_BAR __builtin_amdgcn_s_barrier()
; #define PG8_SCHED __builtin_amdgcn_sched_barrier(0)
; template <class Epi, class Sched>
; DI void gemm_phase(LAS unsigned char* lds, const Gemm g, const Sched& S, const Epi& E) {
;     ...
;             PG8_WAIT_L(8); PG8_BAR; PG8_WAIT_L(0); PG8_MMA(0, 0, At, B0); PG8_BAR; PG8_SCHED;
;             PG8_LDB(B1, 1, 1); PG8_STAGE(PG8_SB(1, 0), b3, voffB);
;             PG8_BAR; PG8_WAIT_L(0); PG8_MMA(0, 1, At, B1); PG8_BAR;
;             PG8_LDA(At, 1, 1); PG8_STAGE(PG8_SA(1, 0), a3, voffA);
;             PG8_BAR; PG8_WAIT_L(0); PG8_MMA(1, 0, At, B0); PG8_BAR; PG8_SCHED;
;             PG8_STAGE(PG8_SB(1, 1), b3 + hstep, voffB);
;             PG8_WAIT_V(6); PG8_BAR; PG8_MMA(1, 1, At, B1); PG8_BAR;
;         }
	s_waitcnt lgkmcnt(0)
	s_setprio 1
	v_mfma_f32_16x16x32_bf16 v[124:127], v[150:153], v[170:173], v[124:127]
	v_mfma_f32_16x16x32_bf16 v[120:123], v[162:165], v[170:173], v[120:123]
	v_mfma_f32_16x16x32_bf16 v[108:111], v[150:153], v[178:181], v[108:111]
	v_mfma_f32_16x16x32_bf16 v[104:107], v[162:165], v[178:181], v[104:107]
	v_mfma_f32_16x16x32_bf16 v[92:95], v[150:153], v[194:197], v[92:95]
	v_mfma_f32_16x16x32_bf16 v[88:91], v[162:165], v[194:197], v[88:91]
	v_mfma_f32_16x16x32_bf16 v[76:79], v[150:153], v[202:205], v[76:79]
	v_mfma_f32_16x16x32_bf16 v[72:75], v[162:165], v[202:205], v[72:75]
	v_mfma_f32_16x16x32_bf16 v[124:127], v[154:157], v[174:177], v[124:127]
	v_mfma_f32_16x16x32_bf16 v[120:123], v[166:169], v[174:177], v[120:123]
	v_mfma_f32_16x16x32_bf16 v[108:111], v[154:157], v[188:191], v[108:111]
	v_mfma_f32_16x16x32_bf16 v[104:107], v[166:169], v[188:191], v[104:107]
	v_mfma_f32_16x16x32_bf16 v[92:95], v[154:157], v[198:201], v[92:95]
	v_mfma_f32_16x16x32_bf16 v[88:91], v[166:169], v[198:201], v[88:91]
	v_mfma_f32_16x16x32_bf16 v[76:79], v[154:157], v[206:209], v[76:79]
	v_mfma_f32_16x16x32_bf16 v[72:75], v[166:169], v[206:209], v[72:75]
	s_setprio 0
	s_barrier
	s_add_i32 s5, 0, 0x1c000
	s_add_i32 s0, s4, s52
	s_add_i32 m0, s0, 0xffffff80
	ds_read_b128 v[210:213], v159
	ds_read_b128 v[214:217], v159 offset:1024
	ds_read_b128 v[218:221], v159 offset:2048
	global_load_lds_dwordx4 v130, s[42:43] offset:128
	s_add_i32 m0, s0, 0x1f80
	ds_read_b128 v[222:225], v159 offset:3072
	global_load_lds_dwordx4 v134, s[42:43] offset:128
	s_barrier
	s_waitcnt lgkmcnt(0)
	s_setprio 1
	v_mfma_f32_16x16x32_bf16 v[116:119], v[210:213], v[170:173], v[116:119]
	v_mfma_f32_16x16x32_bf16 v[112:115], v[218:221], v[170:173], v[112:115]
	v_mfma_f32_16x16x32_bf16 v[100:103], v[210:213], v[178:181], v[100:103]
	v_mfma_f32_16x16x32_bf16 v[96:99], v[218:221], v[178:181], v[96:99]
	v_mfma_f32_16x16x32_bf16 v[84:87], v[210:213], v[194:197], v[84:87]
	v_mfma_f32_16x16x32_bf16 v[80:83], v[218:221], v[194:197], v[80:83]
	v_mfma_f32_16x16x32_bf16 v[68:71], v[210:213], v[202:205], v[68:71]
	v_mfma_f32_16x16x32_bf16 v[64:67], v[218:221], v[202:205], v[64:67]
	v_mfma_f32_16x16x32_bf16 v[116:119], v[214:217], v[174:177], v[116:119]
	v_mfma_f32_16x16x32_bf16 v[112:115], v[222:225], v[174:177], v[112:115]
	v_mfma_f32_16x16x32_bf16 v[100:103], v[214:217], v[188:191], v[100:103]
	v_mfma_f32_16x16x32_bf16 v[96:99], v[222:225], v[188:191], v[96:99]
	v_mfma_f32_16x16x32_bf16 v[84:87], v[214:217], v[198:201], v[84:87]
	v_mfma_f32_16x16x32_bf16 v[80:83], v[222:225], v[198:201], v[80:83]
	v_mfma_f32_16x16x32_bf16 v[68:71], v[214:217], v[206:209], v[68:71]
	v_mfma_f32_16x16x32_bf16 v[64:67], v[222:225], v[206:209], v[64:67]
	s_setprio 0
	s_add_i32 m0, s59, 0xffffff80
	s_barrier
	ds_read_b128 v[170:173], v148 offset:49152
	ds_read_b128 v[174:177], v148 offset:50176
	ds_read_b128 v[178:181], v148 offset:51200
	ds_read_b128 v[188:191], v148 offset:52224
	ds_read_b128 v[194:197], v148 offset:53248
	ds_read_b128 v[198:201], v148 offset:54272
	ds_read_b128 v[202:205], v148 offset:55296
	global_load_lds_dwordx4 v128, s[44:45] offset:128
	s_add_i32 m0, s60, 0xffffff80
	ds_read_b128 v[206:209], v148 offset:56320
	global_load_lds_dwordx4 v132, s[44:45] offset:128
	s_barrier
	s_waitcnt lgkmcnt(0)
	s_setprio 1
	v_mfma_f32_16x16x32_bf16 v[60:63], v[150:153], v[170:173], v[60:63]
	v_mfma_f32_16x16x32_bf16 v[56:59], v[162:165], v[170:173], v[56:59]
	v_mfma_f32_16x16x32_bf16 v[44:47], v[150:153], v[178:181], v[44:47]
	v_mfma_f32_16x16x32_bf16 v[40:43], v[162:165], v[178:181], v[40:43]
	v_mfma_f32_16x16x32_bf16 v[28:31], v[150:153], v[194:197], v[28:31]
	v_mfma_f32_16x16x32_bf16 v[24:27], v[162:165], v[194:197], v[24:27]
	v_mfma_f32_16x16x32_bf16 v[12:15], v[150:153], v[202:205], v[12:15]
	v_mfma_f32_16x16x32_bf16 v[8:11], v[162:165], v[202:205], v[8:11]
	v_mfma_f32_16x16x32_bf16 v[60:63], v[154:157], v[174:177], v[60:63]
	v_mfma_f32_16x16x32_bf16 v[56:59], v[166:169], v[174:177], v[56:59]
	v_mfma_f32_16x16x32_bf16 v[44:47], v[154:157], v[188:191], v[44:47]
	v_mfma_f32_16x16x32_bf16 v[40:43], v[166:169], v[188:191], v[40:43]
	v_mfma_f32_16x16x32_bf16 v[28:31], v[154:157], v[198:201], v[28:31]
	v_mfma_f32_16x16x32_bf16 v[24:27], v[166:169], v[198:201], v[24:27]
	v_mfma_f32_16x16x32_bf16 v[12:15], v[154:157], v[206:209], v[12:15]
	v_mfma_f32_16x16x32_bf16 v[8:11], v[166:169], v[206:209], v[8:11]
	s_setprio 0
	s_barrier
	s_add_u32 s0, s42, 0x80080
	s_addc_u32 s1, s43, 0
	s_add_i32 s4, s5, s52
	s_mov_b32 m0, s4
	s_nop 0
	global_load_lds_dwordx4 v130, s[0:1]
	s_add_i32 m0, s4, 0x2000
	s_nop 0
	global_load_lds_dwordx4 v134, s[0:1]
	s_waitcnt vmcnt(6)
	s_barrier
	s_setprio 1
	v_mfma_f32_16x16x32_bf16 v[52:55], v[210:213], v[170:173], v[52:55]
	v_mfma_f32_16x16x32_bf16 v[48:51], v[218:221], v[170:173], v[48:51]
	v_mfma_f32_16x16x32_bf16 v[36:39], v[210:213], v[178:181], v[36:39]
	v_mfma_f32_16x16x32_bf16 v[32:35], v[218:221], v[178:181], v[32:35]
	v_mfma_f32_16x16x32_bf16 v[20:23], v[210:213], v[194:197], v[20:23]
	v_mfma_f32_16x16x32_bf16 v[16:19], v[218:221], v[194:197], v[16:19]
	v_mfma_f32_16x16x32_bf16 v[4:7], v[210:213], v[202:205], v[4:7]
	v_mfma_f32_16x16x32_bf16 v[0:3], v[218:221], v[202:205], v[0:3]
	v_mfma_f32_16x16x32_bf16 v[52:55], v[214:217], v[174:177], v[52:55]
	v_mfma_f32_16x16x32_bf16 v[48:51], v[222:225], v[174:177], v[48:51]
	v_mfma_f32_16x16x32_bf16 v[36:39], v[214:217], v[188:191], v[36:39]
	v_mfma_f32_16x16x32_bf16 v[32:35], v[222:225], v[188:191], v[32:35]
	v_mfma_f32_16x16x32_bf16 v[20:23], v[214:217], v[198:201], v[20:23]
	v_mfma_f32_16x16x32_bf16 v[16:19], v[222:225], v[198:201], v[16:19]
	v_mfma_f32_16x16x32_bf16 v[4:7], v[214:217], v[206:209], v[4:7]
	v_mfma_f32_16x16x32_bf16 v[0:3], v[222:225], v[206:209], v[0:3]
	s_setprio 0
	s_add_i32 s69, s69, 2
	s_add_u32 s40, s40, 0x100
	s_addc_u32 s41, s41, 0
	s_add_u32 s67, s67, 0x100
	s_addc_u32 s68, s68, 0
	s_cmp_gt_u32 s69, 29
	s_barrier
	s_cbranch_scc0 .LBB0_219

;     DI size_t aoff(const Unit& u, size_t tstep) const { return (size_t)u.pm * tstep; }
;     DI size_t boff(const Unit& u, size_t tstep) const { return (size_t)u.pn * tstep; }
;     DI bool next(int i, Unit& u) const { const long L = (long)i * G + c; if (L >= np) return false; u.pm = pmv; u.pn = (int)(L % nN); u.ks = (int)(L / nN); return true; }
;     DI size_t aoff(const Unit& u, size_t) const { return (size_t)u.ks * kbytes; }
;     DI size_t boff(const Unit& u, size_t tstep) const { return (size_t)u.pn * tstep + (size_t)u.ks * kbytes; }
;     DI bool next(int i, Unit& u) const { Unit t; if (!S.next(i / 3, t)) return false; u.pm = t.pm; u.pn = t.pn; u.ks = i % 3; return true; }
;     DI size_t aoff(const Unit& u, size_t tstep) const { return (u.ks < 2 ? offU : offOA) + (size_t)u.pm * tstep; }
; #define PG8_WAIT_V(n) asm volatile("s_waitcnt vmcnt(" #n ")" ::: "memory")
; template <class Epi, class Sched>
; DI void gemm_phase(LAS unsigned char* lds, const Gemm g, const Sched& S, const Epi& E) {
;     ...
;         const bool has_next = S.next(ui + 1, nxt);
;         const char* nA = has_next ? (const char*)g.A + S.aoff(nxt, tstep) : cA; const char* nB = has_next ? (const char*)g.Bt + S.boff(nxt, tstep) : cB;
;         for (int t = 0; t < nt; t += 2) {
;             if constexpr (Epi::HAS_MID) { if (t == E.mid_t(nt)) { int fr3 = fr, fq3 = fq; asm volatile("" : "+v"(fr3), "+v"(fq3)); E.mid(acc, cur, wr, wc, fr3, fq3); } }
;             const bool last = (t == nt - 2);
;             const char* a1 = cA + (size_t)(t + 1) * kstep;
;             const char* a2 = last ? nA : cA + (size_t)(t + 2) * kstep; const char* b2 = last ? nB : cB + (size_t)(t + 2) * kstep;
;             const char* a3 = a2 + kstep; const char* b3 = b2 + kstep;
;             PG8_LDB(B0, 0, 0); PG8_SCHED; PG8_LDA(At, 0, 0); PG8_STAGE(PG8_SA(1, 1), a1 + hstep, voffA);
;             PG8_WAIT_L(8); PG8_BAR; PG8_WAIT_L(0); PG8_MMA(0, 0, At, B0); PG8_BAR; PG8_SCHED;
;             PG8_LDB(B1, 0, 1); PG8_STAGE(PG8_SB(0, 0), b2, voffB);
;             PG8_BAR; PG8_WAIT_L(0); PG8_MMA(0, 1, At, B1); PG8_BAR;
;             PG8_LDA(At, 0, 1); PG8_STAGE(PG8_SA(0, 0), a2, voffA);
;             PG8_BAR; PG8_WAIT_L(0); PG8_MMA(1, 0, At, B0); PG8_BAR; PG8_SCHED;
;             PG8_STAGE(PG8_SB(0, 1), b2 + hstep, voffB);
;             PG8_WAIT_V(6); PG8_BAR; PG8_MMA(1, 1, At, B1); PG8_BAR;
.LBB0_296:
	s_add_u32 s40, s40, 0x160080
	s_addc_u32 s41, s41, 0
	s_add_u32 s35, s42, 0x100
	v_mov_b32_e32 v0, 0
	s_addc_u32 s68, s43, 0
	s_mov_b32 s69, -2
	s_waitcnt lgkmcnt(0)
	ds_read_b128 v[144:147], v158
	ds_read_b128 v[164:167], v158 offset:1024
	ds_read_b128 v[168:171], v158 offset:2048
	ds_read_b128 v[172:175], v158 offset:3072
	s_add_u32 s0, s40, 0xffea0080
	s_addc_u32 s1, s41, -1
	s_cmpk_eq_i32 s69, 0x54
	s_cselect_b32 s45, s9, s1
	s_cselect_b32 s44, s8, s0
	s_cselect_b32 s43, s11, s68
	s_cselect_b32 s42, s10, s35
	s_add_i32 m0, s54, 0xc000
	ds_read_b128 v[176:179], v159
	ds_read_b128 v[180:183], v159 offset:1024
	ds_read_b128 v[188:191], v159 offset:2048
	ds_read_b128 v[194:197], v159 offset:3072
	ds_read_b128 v[198:201], v159 offset:4096
	ds_read_b128 v[202:205], v159 offset:5120
	ds_read_b128 v[206:209], v159 offset:6144
	global_load_lds_dwordx4 v136, s[40:41]
	s_add_i32 m0, s54, 0xe000
	ds_read_b128 v[210:213], v159 offset:7168
	global_load_lds_dwordx4 v138, s[40:41]
	s_waitcnt lgkmcnt(8)
	s_barrier
	s_waitcnt lgkmcnt(0)
	s_setprio 1
	v_mfma_f32_16x16x32_bf16 v[124:127], v[144:147], v[176:179], 0
	v_mfma_f32_16x16x32_bf16 v[120:123], v[168:171], v[176:179], 0
	v_mfma_f32_16x16x32_bf16 v[108:111], v[144:147], v[188:191], 0
	v_mfma_f32_16x16x32_bf16 v[104:107], v[168:171], v[188:191], 0
	v_mfma_f32_16x16x32_bf16 v[92:95], v[144:147], v[198:201], 0
	v_mfma_f32_16x16x32_bf16 v[88:91], v[168:171], v[198:201], 0
	v_mfma_f32_16x16x32_bf16 v[76:79], v[144:147], v[206:209], 0
	v_mfma_f32_16x16x32_bf16 v[72:75], v[168:171], v[206:209], 0
	v_mfma_f32_16x16x32_bf16 v[124:127], v[164:167], v[180:183], v[124:127]
	v_mfma_f32_16x16x32_bf16 v[120:123], v[172:175], v[180:183], v[120:123]
	v_mfma_f32_16x16x32_bf16 v[108:111], v[164:167], v[194:197], v[108:111]
	v_mfma_f32_16x16x32_bf16 v[104:107], v[172:175], v[194:197], v[104:107]
	v_mfma_f32_16x16x32_bf16 v[92:95], v[164:167], v[202:205], v[92:95]
	v_mfma_f32_16x16x32_bf16 v[88:91], v[172:175], v[202:205], v[88:91]
	v_mfma_f32_16x16x32_bf16 v[76:79], v[164:167], v[210:213], v[76:79]
	v_mfma_f32_16x16x32_bf16 v[72:75], v[172:175], v[210:213], v[72:75]
	s_setprio 0
	s_barrier
	s_add_i32 s0, s63, s53
	s_mov_b32 m0, s0
	ds_read_b128 v[214:217], v161
	ds_read_b128 v[218:221], v161 offset:1024
	ds_read_b128 v[222:225], v161 offset:2048
	global_load_lds_dwordx4 v130, s[42:43]
	s_add_i32 m0, s0, 0x2000
	ds_read_b128 v[226:229], v161 offset:3072
	global_load_lds_dwordx4 v134, s[42:43]
	s_barrier
	s_waitcnt lgkmcnt(0)
	s_setprio 1
	v_mfma_f32_16x16x32_bf16 v[116:119], v[214:217], v[176:179], 0
	v_mfma_f32_16x16x32_bf16 v[112:115], v[222:225], v[176:179], 0
	v_mfma_f32_16x16x32_bf16 v[100:103], v[214:217], v[188:191], 0
	v_mfma_f32_16x16x32_bf16 v[96:99], v[222:225], v[188:191], 0
	v_mfma_f32_16x16x32_bf16 v[84:87], v[214:217], v[198:201], 0
	v_mfma_f32_16x16x32_bf16 v[80:83], v[222:225], v[198:201], 0
	v_mfma_f32_16x16x32_bf16 v[68:71], v[214:217], v[206:209], 0
	v_mfma_f32_16x16x32_bf16 v[64:67], v[222:225], v[206:209], 0
	v_mfma_f32_16x16x32_bf16 v[116:119], v[218:221], v[180:183], v[116:119]
	v_mfma_f32_16x16x32_bf16 v[112:115], v[226:229], v[180:183], v[112:115]
	v_mfma_f32_16x16x32_bf16 v[100:103], v[218:221], v[194:197], v[100:103]
	v_mfma_f32_16x16x32_bf16 v[96:99], v[226:229], v[194:197], v[96:99]
	v_mfma_f32_16x16x32_bf16 v[84:87], v[218:221], v[202:205], v[84:87]
	v_mfma_f32_16x16x32_bf16 v[80:83], v[226:229], v[202:205], v[80:83]
	v_mfma_f32_16x16x32_bf16 v[68:71], v[218:221], v[210:213], v[68:71]
	v_mfma_f32_16x16x32_bf16 v[64:67], v[226:229], v[210:213], v[64:67]
	s_setprio 0
	s_mov_b32 m0, s54
	s_barrier
	ds_read_b128 v[176:179], v159 offset:16384
	ds_read_b128 v[180:183], v159 offset:17408
	ds_read_b128 v[188:191], v159 offset:18432
	ds_read_b128 v[194:197], v159 offset:19456
	ds_read_b128 v[198:201], v159 offset:20480
	ds_read_b128 v[202:205], v159 offset:21504
	ds_read_b128 v[206:209], v159 offset:22528
	global_load_lds_dwordx4 v128, s[44:45]
	s_mov_b32 m0, s55
	ds_read_b128 v[210:213], v159 offset:23552
	global_load_lds_dwordx4 v132, s[44:45]
	s_barrier
	s_waitcnt lgkmcnt(0)
	s_setprio 1
	v_mfma_f32_16x16x32_bf16 v[60:63], v[144:147], v[176:179], 0
	v_mfma_f32_16x16x32_bf16 v[56:59], v[168:171], v[176:179], 0
	v_mfma_f32_16x16x32_bf16 v[44:47], v[144:147], v[188:191], 0
	v_mfma_f32_16x16x32_bf16 v[40:43], v[168:171], v[188:191], 0
	v_mfma_f32_16x16x32_bf16 v[28:31], v[144:147], v[198:201], 0
	v_mfma_f32_16x16x32_bf16 v[24:27], v[168:171], v[198:201], 0
	v_mfma_f32_16x16x32_bf16 v[12:15], v[144:147], v[206:209], 0
	v_mfma_f32_16x16x32_bf16 v[8:11], v[168:171], v[206:209], 0
	v_mfma_f32_16x16x32_bf16 v[60:63], v[164:167], v[180:183], v[60:63]
	v_mfma_f32_16x16x32_bf16 v[56:59], v[172:175], v[180:183], v[56:59]
	v_mfma_f32_16x16x32_bf16 v[44:47], v[164:167], v[194:197], v[44:47]
	v_mfma_f32_16x16x32_bf16 v[40:43], v[172:175], v[194:197], v[40:43]
	v_mfma_f32_16x16x32_bf16 v[28:31], v[164:167], v[202:205], v[28:31]
	v_mfma_f32_16x16x32_bf16 v[24:27], v[172:175], v[202:205], v[24:27]
	v_mfma_f32_16x16x32_bf16 v[12:15], v[164:167], v[210:213], v[12:15]
	v_mfma_f32_16x16x32_bf16 v[8:11], v[172:175], v[210:213], v[8:11]
	s_setprio 0
	s_barrier
	s_add_u32 s0, s42, 0x160000
	s_addc_u32 s1, s43, 0
	s_add_i32 s4, s64, s53
	s_mov_b32 m0, s4
	s_nop 0
	global_load_lds_dwordx4 v130, s[0:1]
	s_add_i32 m0, s4, 0x2000
	s_nop 0
	global_load_lds_dwordx4 v134, s[0:1]
	s_waitcnt vmcnt(6)
	s_barrier
; #define PG8_STAGE(bufoff, gbase, voff) do { _Pragma("unroll") for (int _i = 0; _i < 2; ++_i) \
;         __builtin_amdgcn_global_load_lds((const unsigned*)((const char*)(gbase) + (voff)[_i]), (LAS unsigned*)(lds + (bufoff) + ldsw + _i * 8192), 16, 0, 0); } while (0)
; #define PG8_LDA(dst, b, h) do { _Pragma("unroll") for (int m = 0; m < 4; ++m) _Pragma("unroll") for (int k = 0; k < 2; ++k) dst[m][k] = *(const LAS bf16x8*)(lds + PG8_SA(b, h) + aoff + m * 2048 + k * 1024); } while (0)
; #define PG8_LDB(dst, b, h) do { _Pragma("unroll") for (int n = 0; n < 2; ++n) _Pragma("unroll") for (int k = 0; k < 2; ++k) dst[n][k] = *(const LAS bf16x8*)(lds + PG8_SB(b, h) + boff + n * 2048 + k * 1024); } while (0)
; #define PG8_MMA(ai, bj, At, Bt) do { __builtin_amdgcn_s_setprio(1); _Pragma("unroll") for (int m = 0; m < 4; ++m) _Pragma("unroll") for (int n = 0; n < 2; ++n) _Pragma("unroll") for (int k = 0; k < 2; ++k) \
;         acc[ai][bj][m][n] = __builtin_amdgcn_mfma_f32_16x16x32_bf16(Bt[n][k], At[m][k], acc[ai][bj][m][n], 0, 0, 0); __builtin_amdgcn_s_setprio(0); } while (0)
; #define PG8_WAIT_V(n) asm volatile("s_waitcnt vmcnt(" #n ")" ::: "memory")
; #define PG8_WAIT_L(n) asm volatile("s_waitcnt lgkmcnt(" #n ")" ::: "memory")
; #define PG8_BAR __builtin_amdgcn_s_barrier()
; #define PG8_SCHED __builtin_amdgcn_sched_barrier(0)
; template <class Epi, class Sched>
; DI void gemm_phase(LAS unsigned char* lds, const Gemm g, const Sched& S, const Epi& E) {
;     ...
;             PG8_WAIT_V(6); PG8_BAR; PG8_MMA(1, 1, At, B1); PG8_BAR;
;             PG8_LDB(B0, 1, 0); PG8_SCHED; PG8_LDA(At, 1, 0); PG8_STAGE(PG8_SA(0, 1), a2 + hstep, voffA);
;             PG8_WAIT_L(8); PG8_BAR; PG8_WAIT_L(0); PG8_MMA(0, 0, At, B0); PG8_BAR; PG8_SCHED;
;             PG8_LDB(B1, 1, 1); PG8_STAGE(PG8_SB(1, 0), b3, voffB);
;             PG8_BAR; PG8_WAIT_L(0); PG8_MMA(0, 1, At, B1); PG8_BAR;
;             PG8_LDA(At, 1, 1); PG8_STAGE(PG8_SA(1, 0), a3, voffA);
	s_setprio 1
	v_mfma_f32_16x16x32_bf16 v[52:55], v[214:217], v[176:179], 0
	v_mfma_f32_16x16x32_bf16 v[48:51], v[222:225], v[176:179], 0
	v_mfma_f32_16x16x32_bf16 v[36:39], v[214:217], v[188:191], 0
	v_mfma_f32_16x16x32_bf16 v[32:35], v[222:225], v[188:191], 0
	v_mfma_f32_16x16x32_bf16 v[20:23], v[214:217], v[198:201], 0
	v_mfma_f32_16x16x32_bf16 v[16:19], v[222:225], v[198:201], 0
	v_mfma_f32_16x16x32_bf16 v[4:7], v[214:217], v[206:209], 0
	v_mfma_f32_16x16x32_bf16 v[0:3], v[222:225], v[206:209], 0
	v_mfma_f32_16x16x32_bf16 v[52:55], v[218:221], v[180:183], v[52:55]
	v_mfma_f32_16x16x32_bf16 v[48:51], v[226:229], v[180:183], v[48:51]
	v_mfma_f32_16x16x32_bf16 v[36:39], v[218:221], v[194:197], v[36:39]
	v_mfma_f32_16x16x32_bf16 v[32:35], v[226:229], v[194:197], v[32:35]
	v_mfma_f32_16x16x32_bf16 v[20:23], v[218:221], v[202:205], v[20:23]
	v_mfma_f32_16x16x32_bf16 v[16:19], v[226:229], v[202:205], v[16:19]
	v_mfma_f32_16x16x32_bf16 v[4:7], v[218:221], v[210:213], v[4:7]
	v_mfma_f32_16x16x32_bf16 v[0:3], v[226:229], v[210:213], v[0:3]
	s_setprio 0
	s_add_i32 s4, 0, 0x18000
	v_add_u32_e32 v230, s4, v157
	s_barrier
	ds_read_b128 v[144:147], v230
	ds_read_b128 v[164:167], v230 offset:1024
	ds_read_b128 v[168:171], v230 offset:2048
	ds_read_b128 v[172:175], v230 offset:3072
	s_add_u32 s0, s44, 0x160000
	s_addc_u32 s1, s45, 0
	s_mov_b32 m0, s56
	ds_read_b128 v[176:179], v159 offset:32768
	ds_read_b128 v[180:183], v159 offset:33792
	ds_read_b128 v[188:191], v159 offset:34816
	ds_read_b128 v[194:197], v159 offset:35840
	ds_read_b128 v[198:201], v159 offset:36864
	ds_read_b128 v[202:205], v159 offset:37888
	ds_read_b128 v[206:209], v159 offset:38912
	global_load_lds_dwordx4 v128, s[0:1]
	s_mov_b32 m0, s57
	ds_read_b128 v[210:213], v159 offset:39936
	global_load_lds_dwordx4 v132, s[0:1]
	s_waitcnt lgkmcnt(8)
	s_barrier
	s_waitcnt lgkmcnt(0)
	s_setprio 1
	v_mfma_f32_16x16x32_bf16 v[124:127], v[144:147], v[176:179], v[124:127]
	v_mfma_f32_16x16x32_bf16 v[120:123], v[168:171], v[176:179], v[120:123]
	v_mfma_f32_16x16x32_bf16 v[108:111], v[144:147], v[188:191], v[108:111]
	v_mfma_f32_16x16x32_bf16 v[104:107], v[168:171], v[188:191], v[104:107]
	v_mfma_f32_16x16x32_bf16 v[92:95], v[144:147], v[198:201], v[92:95]
	v_mfma_f32_16x16x32_bf16 v[88:91], v[168:171], v[198:201], v[88:91]
	v_mfma_f32_16x16x32_bf16 v[76:79], v[144:147], v[206:209], v[76:79]
	v_mfma_f32_16x16x32_bf16 v[72:75], v[168:171], v[206:209], v[72:75]
	v_mfma_f32_16x16x32_bf16 v[124:127], v[164:167], v[180:183], v[124:127]
	v_mfma_f32_16x16x32_bf16 v[120:123], v[172:175], v[180:183], v[120:123]
	v_mfma_f32_16x16x32_bf16 v[108:111], v[164:167], v[194:197], v[108:111]
	v_mfma_f32_16x16x32_bf16 v[104:107], v[172:175], v[194:197], v[104:107]
	v_mfma_f32_16x16x32_bf16 v[92:95], v[164:167], v[202:205], v[92:95]
	v_mfma_f32_16x16x32_bf16 v[88:91], v[172:175], v[202:205], v[88:91]
	v_mfma_f32_16x16x32_bf16 v[76:79], v[164:167], v[210:213], v[76:79]
	v_mfma_f32_16x16x32_bf16 v[72:75], v[172:175], v[210:213], v[72:75]
	s_setprio 0
	s_barrier
	s_add_i32 s5, 0, 0x1c000
	s_add_i32 s0, s4, s53
	v_add_u32_e32 v231, s5, v157
	s_add_i32 m0, s0, 0xffffff80
	ds_read_b128 v[214:217], v231
	ds_read_b128 v[218:221], v231 offset:1024
	ds_read_b128 v[222:225], v231 offset:2048
	global_load_lds_dwordx4 v130, s[42:43] offset:128
	s_add_i32 m0, s0, 0x1f80
	ds_read_b128 v[226:229], v231 offset:3072
	global_load_lds_dwordx4 v134, s[42:43] offset:128
	s_barrier
	s_waitcnt lgkmcnt(0)
	s_setprio 1
	v_mfma_f32_16x16x32_bf16 v[116:119], v[214:217], v[176:179], v[116:119]
	v_mfma_f32_16x16x32_bf16 v[112:115], v[222:225], v[176:179], v[112:115]
	v_mfma_f32_16x16x32_bf16 v[100:103], v[214:217], v[188:191], v[100:103]
	v_mfma_f32_16x16x32_bf16 v[96:99], v[222:225], v[188:191], v[96:99]
	v_mfma_f32_16x16x32_bf16 v[84:87], v[214:217], v[198:201], v[84:87]
	v_mfma_f32_16x16x32_bf16 v[80:83], v[222:225], v[198:201], v[80:83]
	v_mfma_f32_16x16x32_bf16 v[68:71], v[214:217], v[206:209], v[68:71]
	v_mfma_f32_16x16x32_bf16 v[64:67], v[222:225], v[206:209], v[64:67]
	v_mfma_f32_16x16x32_bf16 v[116:119], v[218:221], v[180:183], v[116:119]
	v_mfma_f32_16x16x32_bf16 v[112:115], v[226:229], v[180:183], v[112:115]
	v_mfma_f32_16x16x32_bf16 v[100:103], v[218:221], v[194:197], v[100:103]
	v_mfma_f32_16x16x32_bf16 v[96:99], v[226:229], v[194:197], v[96:99]
	v_mfma_f32_16x16x32_bf16 v[84:87], v[218:221], v[202:205], v[84:87]
	v_mfma_f32_16x16x32_bf16 v[80:83], v[226:229], v[202:205], v[80:83]
	v_mfma_f32_16x16x32_bf16 v[68:71], v[218:221], v[210:213], v[68:71]
	v_mfma_f32_16x16x32_bf16 v[64:67], v[226:229], v[210:213], v[64:67]
	s_setprio 0
	s_add_i32 m0, s61, 0xffffff80
	s_barrier
	ds_read_b128 v[176:179], v159 offset:49152
	ds_read_b128 v[180:183], v159 offset:50176
	ds_read_b128 v[188:191], v159 offset:51200
	ds_read_b128 v[194:197], v159 offset:52224
	ds_read_b128 v[198:201], v159 offset:53248
	ds_read_b128 v[202:205], v159 offset:54272
	ds_read_b128 v[206:209], v159 offset:55296
	global_load_lds_dwordx4 v128, s[44:45] offset:128
	s_add_i32 m0, s62, 0xffffff80
	ds_read_b128 v[210:213], v159 offset:56320
	global_load_lds_dwordx4 v132, s[44:45] offset:128
	s_barrier
; #define PG8_STAGE(bufoff, gbase, voff) do { _Pragma("unroll") for (int _i = 0; _i < 2; ++_i) \
;         __builtin_amdgcn_global_load_lds((const unsigned*)((const char*)(gbase) + (voff)[_i]), (LAS unsigned*)(lds + (bufoff) + ldsw + _i * 8192), 16, 0, 0); } while (0)
; #define PG8_LDA(dst, b, h) do { _Pragma("unroll") for (int m = 0; m < 4; ++m) _Pragma("unroll") for (int k = 0; k < 2; ++k) dst[m][k] = *(const LAS bf16x8*)(lds + PG8_SA(b, h) + aoff + m * 2048 + k * 1024); } while (0)
; #define PG8_LDB(dst, b, h) do { _Pragma("unroll") for (int n = 0; n < 2; ++n) _Pragma("unroll") for (int k = 0; k < 2; ++k) dst[n][k] = *(const LAS bf16x8*)(lds + PG8_SB(b, h) + boff + n * 2048 + k * 1024); } while (0)
; #define PG8_WAIT_V(n) asm volatile("s_waitcnt vmcnt(" #n ")" ::: "memory")
; #define PG8_WAIT_L(n) asm volatile("s_waitcnt lgkmcnt(" #n ")" ::: "memory")
; #define PG8_BAR __builtin_amdgcn_s_barrier()
; #define PG8_SCHED __builtin_amdgcn_sched_barrier(0)
; template <class Epi, class Sched>
; DI void gemm_phase(LAS unsigned char* lds, const Gemm g, const Sched& S, const Epi& E) {
;     ...
;             PG8_LDB(B0, 0, 0); PG8_SCHED; PG8_LDA(At, 0, 0); PG8_STAGE(PG8_SA(1, 1), a1 + hstep, voffA);
;             PG8_WAIT_L(8); PG8_BAR; PG8_WAIT_L(0); PG8_MMA(0, 0, At, B0); PG8_BAR; PG8_SCHED;
;             PG8_LDB(B1, 0, 1); PG8_STAGE(PG8_SB(0, 0), b2, voffB);
;             PG8_BAR; PG8_WAIT_L(0); PG8_MMA(0, 1, At, B1); PG8_BAR;
;             PG8_LDA(At, 0, 1); PG8_STAGE(PG8_SA(0, 0), a2, voffA);
;             PG8_BAR; PG8_WAIT_L(0); PG8_MMA(1, 0, At, B0); PG8_BAR; PG8_SCHED;
;             PG8_STAGE(PG8_SB(0, 1), b2 + hstep, voffB);
;             PG8_WAIT_V(6); PG8_BAR; PG8_MMA(1, 1, At, B1); PG8_BAR;
;             PG8_LDB(B0, 1, 0); PG8_SCHED; PG8_LDA(At, 1, 0); PG8_STAGE(PG8_SA(0, 1), a2 + hstep, voffA);
;             PG8_WAIT_L(8); PG8_BAR; PG8_WAIT_L(0); PG8_MMA(0, 0, At, B0); PG8_BAR; PG8_SCHED;
;             PG8_LDB(B1, 1, 1); PG8_STAGE(PG8_SB(1, 0), b3, voffB);
;             PG8_BAR; PG8_WAIT_L(0); PG8_MMA(0, 1, At, B1); PG8_BAR;
;             PG8_LDA(At, 1, 1); PG8_STAGE(PG8_SA(1, 0), a3, voffA);
;             PG8_BAR; PG8_WAIT_L(0); PG8_MMA(1, 0, At, B0); PG8_BAR; PG8_SCHED;
;             PG8_STAGE(PG8_SB(1, 1), b3 + hstep, voffB);
;             PG8_WAIT_V(6); PG8_BAR; PG8_MMA(1, 1, At, B1); PG8_BAR;
	s_waitcnt lgkmcnt(0)
	s_setprio 1
	v_mfma_f32_16x16x32_bf16 v[60:63], v[144:147], v[176:179], v[60:63]
	v_mfma_f32_16x16x32_bf16 v[56:59], v[168:171], v[176:179], v[56:59]
	v_mfma_f32_16x16x32_bf16 v[44:47], v[144:147], v[188:191], v[44:47]
	v_mfma_f32_16x16x32_bf16 v[40:43], v[168:171], v[188:191], v[40:43]
	v_mfma_f32_16x16x32_bf16 v[28:31], v[144:147], v[198:201], v[28:31]
	v_mfma_f32_16x16x32_bf16 v[24:27], v[168:171], v[198:201], v[24:27]
	v_mfma_f32_16x16x32_bf16 v[12:15], v[144:147], v[206:209], v[12:15]
	v_mfma_f32_16x16x32_bf16 v[8:11], v[168:171], v[206:209], v[8:11]
	v_mfma_f32_16x16x32_bf16 v[60:63], v[164:167], v[180:183], v[60:63]
	v_mfma_f32_16x16x32_bf16 v[56:59], v[172:175], v[180:183], v[56:59]
	v_mfma_f32_16x16x32_bf16 v[44:47], v[164:167], v[194:197], v[44:47]
	v_mfma_f32_16x16x32_bf16 v[40:43], v[172:175], v[194:197], v[40:43]
	v_mfma_f32_16x16x32_bf16 v[28:31], v[164:167], v[202:205], v[28:31]
	v_mfma_f32_16x16x32_bf16 v[24:27], v[172:175], v[202:205], v[24:27]
	v_mfma_f32_16x16x32_bf16 v[12:15], v[164:167], v[210:213], v[12:15]
	v_mfma_f32_16x16x32_bf16 v[8:11], v[172:175], v[210:213], v[8:11]
	s_setprio 0
	s_barrier
	s_add_u32 s0, s42, 0x160080
	s_addc_u32 s1, s43, 0
	s_add_i32 s4, s5, s53
	s_mov_b32 m0, s4
	s_nop 0
	global_load_lds_dwordx4 v130, s[0:1]
	s_add_i32 m0, s4, 0x2000
	s_nop 0
	global_load_lds_dwordx4 v134, s[0:1]
	s_waitcnt vmcnt(6)
	s_barrier
	s_setprio 1
	v_mfma_f32_16x16x32_bf16 v[52:55], v[214:217], v[176:179], v[52:55]
	v_mfma_f32_16x16x32_bf16 v[48:51], v[222:225], v[176:179], v[48:51]
	v_mfma_f32_16x16x32_bf16 v[36:39], v[214:217], v[188:191], v[36:39]
	v_mfma_f32_16x16x32_bf16 v[32:35], v[222:225], v[188:191], v[32:35]
	v_mfma_f32_16x16x32_bf16 v[20:23], v[214:217], v[198:201], v[20:23]
	v_mfma_f32_16x16x32_bf16 v[16:19], v[222:225], v[198:201], v[16:19]
	v_mfma_f32_16x16x32_bf16 v[4:7], v[214:217], v[206:209], v[4:7]
	v_mfma_f32_16x16x32_bf16 v[0:3], v[222:225], v[206:209], v[0:3]
	v_mfma_f32_16x16x32_bf16 v[52:55], v[218:221], v[180:183], v[52:55]
	v_mfma_f32_16x16x32_bf16 v[48:51], v[226:229], v[180:183], v[48:51]
	v_mfma_f32_16x16x32_bf16 v[36:39], v[218:221], v[194:197], v[36:39]
	v_mfma_f32_16x16x32_bf16 v[32:35], v[226:229], v[194:197], v[32:35]
	v_mfma_f32_16x16x32_bf16 v[20:23], v[218:221], v[202:205], v[20:23]
	v_mfma_f32_16x16x32_bf16 v[16:19], v[226:229], v[202:205], v[16:19]
	v_mfma_f32_16x16x32_bf16 v[4:7], v[218:221], v[210:213], v[4:7]
	v_mfma_f32_16x16x32_bf16 v[0:3], v[226:229], v[210:213], v[0:3]
	s_setprio 0
	s_add_i32 s69, s69, 2
	s_add_u32 s40, s40, 0x100
	s_addc_u32 s41, s41, 0
	s_add_u32 s35, s35, 0x100
	s_addc_u32 s68, s68, 0
	s_cmpk_gt_u32 s69, 0x55
	s_barrier
	s_cbranch_scc0 .LBB0_297
	s_branch .Lpeel_done_297
.LBB0_297:
	ds_read_b128 v[144:147], v158
	ds_read_b128 v[164:167], v158 offset:1024
	ds_read_b128 v[168:171], v158 offset:2048
	ds_read_b128 v[172:175], v158 offset:3072
	s_add_u32 s0, s40, 0xffea0080
	s_addc_u32 s1, s41, -1
	s_cmpk_eq_i32 s69, 0x54
	s_cselect_b32 s45, s9, s1
	s_cselect_b32 s44, s8, s0
	s_cselect_b32 s43, s11, s68
	s_cselect_b32 s42, s10, s35
	s_add_i32 m0, s54, 0xc000
	ds_read_b128 v[176:179], v159
	ds_read_b128 v[180:183], v159 offset:1024
	ds_read_b128 v[188:191], v159 offset:2048
	ds_read_b128 v[194:197], v159 offset:3072
	ds_read_b128 v[198:201], v159 offset:4096
	ds_read_b128 v[202:205], v159 offset:5120
	ds_read_b128 v[206:209], v159 offset:6144
	global_load_lds_dwordx4 v136, s[40:41]
	s_add_i32 m0, s54, 0xe000
	ds_read_b128 v[210:213], v159 offset:7168
	global_load_lds_dwordx4 v138, s[40:41]
	s_waitcnt lgkmcnt(8)
	s_barrier
	s_waitcnt lgkmcnt(0)
	s_setprio 1
	v_mfma_f32_16x16x32_bf16 v[124:127], v[144:147], v[176:179], v[124:127]
	v_mfma_f32_16x16x32_bf16 v[120:123], v[168:171], v[176:179], v[120:123]
	v_mfma_f32_16x16x32_bf16 v[108:111], v[144:147], v[188:191], v[108:111]
	v_mfma_f32_16x16x32_bf16 v[104:107], v[168:171], v[188:191], v[104:107]
	v_mfma_f32_16x16x32_bf16 v[92:95], v[144:147], v[198:201], v[92:95]
	v_mfma_f32_16x16x32_bf16 v[88:91], v[168:171], v[198:201], v[88:91]
	v_mfma_f32_16x16x32_bf16 v[76:79], v[144:147], v[206:209], v[76:79]
	v_mfma_f32_16x16x32_bf16 v[72:75], v[168:171], v[206:209], v[72:75]
	v_mfma_f32_16x16x32_bf16 v[124:127], v[164:167], v[180:183], v[124:127]
	v_mfma_f32_16x16x32_bf16 v[120:123], v[172:175], v[180:183], v[120:123]
	v_mfma_f32_16x16x32_bf16 v[108:111], v[164:167], v[194:197], v[108:111]
	v_mfma_f32_16x16x32_bf16 v[104:107], v[172:175], v[194:197], v[104:107]
	v_mfma_f32_16x16x32_bf16 v[92:95], v[164:167], v[202:205], v[92:95]
	v_mfma_f32_16x16x32_bf16 v[88:91], v[172:175], v[202:205], v[88:91]
	v_mfma_f32_16x16x32_bf16 v[76:79], v[164:167], v[210:213], v[76:79]
	v_mfma_f32_16x16x32_bf16 v[72:75], v[172:175], v[210:213], v[72:75]
	s_setprio 0
	s_barrier
	s_add_i32 s0, s63, s53
	s_mov_b32 m0, s0
	ds_read_b128 v[214:217], v161
	ds_read_b128 v[218:221], v161 offset:1024
	ds_read_b128 v[222:225], v161 offset:2048
	global_load_lds_dwordx4 v130, s[42:43]
	s_add_i32 m0, s0, 0x2000
	ds_read_b128 v[226:229], v161 offset:3072
	global_load_lds_dwordx4 v134, s[42:43]
	s_barrier
; #define PG8_STAGE(bufoff, gbase, voff) do { _Pragma("unroll") for (int _i = 0; _i < 2; ++_i) \
;         __builtin_amdgcn_global_load_lds((const unsigned*)((const char*)(gbase) + (voff)[_i]), (LAS unsigned*)(lds + (bufoff) + ldsw + _i * 8192), 16, 0, 0); } while (0)
; #define PG8_LDA(dst, b, h) do { _Pragma("unroll") for (int m = 0; m < 4; ++m) _Pragma("unroll") for (int k = 0; k < 2; ++k) dst[m][k] = *(const LAS bf16x8*)(lds + PG8_SA(b, h) + aoff + m * 2048 + k * 1024); } while (0)
; #define PG8_LDB(dst, b, h) do { _Pragma("unroll") for (int n = 0; n < 2; ++n) _Pragma("unroll") for (int k = 0; k < 2; ++k) dst[n][k] = *(const LAS bf16x8*)(lds + PG8_SB(b, h) + boff + n * 2048 + k * 1024); } while (0)
; #define PG8_MMA(ai, bj, At, Bt) do { __builtin_amdgcn_s_setprio(1); _Pragma("unroll") for (int m = 0; m < 4; ++m) _Pragma("unroll") for (int n = 0; n < 2; ++n) _Pragma("unroll") for (int k = 0; k < 2; ++k) \
;         acc[ai][bj][m][n] = __builtin_amdgcn_mfma_f32_16x16x32_bf16(Bt[n][k], At[m][k], acc[ai][bj][m][n], 0, 0, 0); __builtin_amdgcn_s_setprio(0); } while (0)
; #define PG8_WAIT_V(n) asm volatile("s_waitcnt vmcnt(" #n ")" ::: "memory")
; #define PG8_WAIT_L(n) asm volatile("s_waitcnt lgkmcnt(" #n ")" ::: "memory")
; #define PG8_BAR __builtin_amdgcn_s_barrier()
; #define PG8_SCHED __builtin_amdgcn_sched_barrier(0)
; template <class Epi, class Sched>
; DI void gemm_phase(LAS unsigned char* lds, const Gemm g, const Sched& S, const Epi& E) {
;     ...
;             PG8_BAR; PG8_WAIT_L(0); PG8_MMA(0, 1, At, B1); PG8_BAR;
;             PG8_LDA(At, 0, 1); PG8_STAGE(PG8_SA(0, 0), a2, voffA);
;             PG8_BAR; PG8_WAIT_L(0); PG8_MMA(1, 0, At, B0); PG8_BAR; PG8_SCHED;
;             PG8_STAGE(PG8_SB(0, 1), b2 + hstep, voffB);
;             PG8_WAIT_V(6); PG8_BAR; PG8_MMA(1, 1, At, B1); PG8_BAR;
;             PG8_LDB(B0, 1, 0); PG8_SCHED; PG8_LDA(At, 1, 0); PG8_STAGE(PG8_SA(0, 1), a2 + hstep, voffA);
;             PG8_WAIT_L(8); PG8_BAR; PG8_WAIT_L(0); PG8_MMA(0, 0, At, B0); PG8_BAR; PG8_SCHED;
	s_waitcnt lgkmcnt(0)
	s_setprio 1
	v_mfma_f32_16x16x32_bf16 v[116:119], v[214:217], v[176:179], v[116:119]
	v_mfma_f32_16x16x32_bf16 v[112:115], v[222:225], v[176:179], v[112:115]
	v_mfma_f32_16x16x32_bf16 v[100:103], v[214:217], v[188:191], v[100:103]
	v_mfma_f32_16x16x32_bf16 v[96:99], v[222:225], v[188:191], v[96:99]
	v_mfma_f32_16x16x32_bf16 v[84:87], v[214:217], v[198:201], v[84:87]
	v_mfma_f32_16x16x32_bf16 v[80:83], v[222:225], v[198:201], v[80:83]
	v_mfma_f32_16x16x32_bf16 v[68:71], v[214:217], v[206:209], v[68:71]
	v_mfma_f32_16x16x32_bf16 v[64:67], v[222:225], v[206:209], v[64:67]
	v_mfma_f32_16x16x32_bf16 v[116:119], v[218:221], v[180:183], v[116:119]
	v_mfma_f32_16x16x32_bf16 v[112:115], v[226:229], v[180:183], v[112:115]
	v_mfma_f32_16x16x32_bf16 v[100:103], v[218:221], v[194:197], v[100:103]
	v_mfma_f32_16x16x32_bf16 v[96:99], v[226:229], v[194:197], v[96:99]
	v_mfma_f32_16x16x32_bf16 v[84:87], v[218:221], v[202:205], v[84:87]
	v_mfma_f32_16x16x32_bf16 v[80:83], v[226:229], v[202:205], v[80:83]
	v_mfma_f32_16x16x32_bf16 v[68:71], v[218:221], v[210:213], v[68:71]
	v_mfma_f32_16x16x32_bf16 v[64:67], v[226:229], v[210:213], v[64:67]
	s_setprio 0
	s_mov_b32 m0, s54
	s_barrier
	ds_read_b128 v[176:179], v159 offset:16384
	ds_read_b128 v[180:183], v159 offset:17408
	ds_read_b128 v[188:191], v159 offset:18432
	ds_read_b128 v[194:197], v159 offset:19456
	ds_read_b128 v[198:201], v159 offset:20480
	ds_read_b128 v[202:205], v159 offset:21504
	ds_read_b128 v[206:209], v159 offset:22528
	global_load_lds_dwordx4 v128, s[44:45]
	s_mov_b32 m0, s55
	ds_read_b128 v[210:213], v159 offset:23552
	global_load_lds_dwordx4 v132, s[44:45]
	s_barrier
	s_waitcnt lgkmcnt(0)
	s_setprio 1
	v_mfma_f32_16x16x32_bf16 v[60:63], v[144:147], v[176:179], v[60:63]
	v_mfma_f32_16x16x32_bf16 v[56:59], v[168:171], v[176:179], v[56:59]
	v_mfma_f32_16x16x32_bf16 v[44:47], v[144:147], v[188:191], v[44:47]
	v_mfma_f32_16x16x32_bf16 v[40:43], v[168:171], v[188:191], v[40:43]
	v_mfma_f32_16x16x32_bf16 v[28:31], v[144:147], v[198:201], v[28:31]
	v_mfma_f32_16x16x32_bf16 v[24:27], v[168:171], v[198:201], v[24:27]
	v_mfma_f32_16x16x32_bf16 v[12:15], v[144:147], v[206:209], v[12:15]
	v_mfma_f32_16x16x32_bf16 v[8:11], v[168:171], v[206:209], v[8:11]
	v_mfma_f32_16x16x32_bf16 v[60:63], v[164:167], v[180:183], v[60:63]
	v_mfma_f32_16x16x32_bf16 v[56:59], v[172:175], v[180:183], v[56:59]
	v_mfma_f32_16x16x32_bf16 v[44:47], v[164:167], v[194:197], v[44:47]
	v_mfma_f32_16x16x32_bf16 v[40:43], v[172:175], v[194:197], v[40:43]
	v_mfma_f32_16x16x32_bf16 v[28:31], v[164:167], v[202:205], v[28:31]
	v_mfma_f32_16x16x32_bf16 v[24:27], v[172:175], v[202:205], v[24:27]
	v_mfma_f32_16x16x32_bf16 v[12:15], v[164:167], v[210:213], v[12:15]
	v_mfma_f32_16x16x32_bf16 v[8:11], v[172:175], v[210:213], v[8:11]
	s_setprio 0
	s_barrier
	s_add_u32 s0, s42, 0x160000
	s_addc_u32 s1, s43, 0
	s_add_i32 s4, s64, s53
	s_mov_b32 m0, s4
	s_nop 0
	global_load_lds_dwordx4 v130, s[0:1]
	s_add_i32 m0, s4, 0x2000
	s_nop 0
	global_load_lds_dwordx4 v134, s[0:1]
	s_waitcnt vmcnt(6)
	s_barrier
	s_setprio 1
	v_mfma_f32_16x16x32_bf16 v[52:55], v[214:217], v[176:179], v[52:55]
	v_mfma_f32_16x16x32_bf16 v[48:51], v[222:225], v[176:179], v[48:51]
	v_mfma_f32_16x16x32_bf16 v[36:39], v[214:217], v[188:191], v[36:39]
	v_mfma_f32_16x16x32_bf16 v[32:35], v[222:225], v[188:191], v[32:35]
	v_mfma_f32_16x16x32_bf16 v[20:23], v[214:217], v[198:201], v[20:23]
	v_mfma_f32_16x16x32_bf16 v[16:19], v[222:225], v[198:201], v[16:19]
	v_mfma_f32_16x16x32_bf16 v[4:7], v[214:217], v[206:209], v[4:7]
	v_mfma_f32_16x16x32_bf16 v[0:3], v[222:225], v[206:209], v[0:3]
	v_mfma_f32_16x16x32_bf16 v[52:55], v[218:221], v[180:183], v[52:55]
	v_mfma_f32_16x16x32_bf16 v[48:51], v[226:229], v[180:183], v[48:51]
	v_mfma_f32_16x16x32_bf16 v[36:39], v[218:221], v[194:197], v[36:39]
	v_mfma_f32_16x16x32_bf16 v[32:35], v[226:229], v[194:197], v[32:35]
	v_mfma_f32_16x16x32_bf16 v[20:23], v[218:221], v[202:205], v[20:23]
	v_mfma_f32_16x16x32_bf16 v[16:19], v[226:229], v[202:205], v[16:19]
	v_mfma_f32_16x16x32_bf16 v[4:7], v[218:221], v[210:213], v[4:7]
	v_mfma_f32_16x16x32_bf16 v[0:3], v[226:229], v[210:213], v[0:3]
	s_setprio 0
	s_add_i32 s4, 0, 0x18000
	s_barrier
	ds_read_b128 v[144:147], v230
	ds_read_b128 v[164:167], v230 offset:1024
	ds_read_b128 v[168:171], v230 offset:2048
	ds_read_b128 v[172:175], v230 offset:3072
	s_add_u32 s0, s44, 0x160000
	s_addc_u32 s1, s45, 0
	s_mov_b32 m0, s56
	ds_read_b128 v[176:179], v159 offset:32768
	ds_read_b128 v[180:183], v159 offset:33792
	ds_read_b128 v[188:191], v159 offset:34816
	ds_read_b128 v[194:197], v159 offset:35840
	ds_read_b128 v[198:201], v159 offset:36864
	ds_read_b128 v[202:205], v159 offset:37888
	ds_read_b128 v[206:209], v159 offset:38912
	global_load_lds_dwordx4 v128, s[0:1]
	s_mov_b32 m0, s57
	ds_read_b128 v[210:213], v159 offset:39936
	global_load_lds_dwordx4 v132, s[0:1]
	s_waitcnt lgkmcnt(8)
	s_barrier
; #define PG8_STAGE(bufoff, gbase, voff) do { _Pragma("unroll") for (int _i = 0; _i < 2; ++_i) \
;         __builtin_amdgcn_global_load_lds((const unsigned*)((const char*)(gbase) + (voff)[_i]), (LAS unsigned*)(lds + (bufoff) + ldsw + _i * 8192), 16, 0, 0); } while (0)
; #define PG8_LDA(dst, b, h) do { _Pragma("unroll") for (int m = 0; m < 4; ++m) _Pragma("unroll") for (int k = 0; k < 2; ++k) dst[m][k] = *(const LAS bf16x8*)(lds + PG8_SA(b, h) + aoff + m * 2048 + k * 1024); } while (0)
; #define PG8_LDB(dst, b, h) do { _Pragma("unroll") for (int n = 0; n < 2; ++n) _Pragma("unroll") for (int k = 0; k < 2; ++k) dst[n][k] = *(const LAS bf16x8*)(lds + PG8_SB(b, h) + boff + n * 2048 + k * 1024); } while (0)
; #define PG8_MMA(ai, bj, At, Bt) do { __builtin_amdgcn_s_setprio(1); _Pragma("unroll") for (int m = 0; m < 4; ++m) _Pragma("unroll") for (int n = 0; n < 2; ++n) _Pragma("unroll") for (int k = 0; k < 2; ++k) \
;         acc[ai][bj][m][n] = __builtin_amdgcn_mfma_f32_16x16x32_bf16(Bt[n][k], At[m][k], acc[ai][bj][m][n], 0, 0, 0); __builtin_amdgcn_s_setprio(0); } while (0)
; #define PG8_WAIT_V(n) asm volatile("s_waitcnt vmcnt(" #n ")" ::: "memory")
; #define PG8_WAIT_L(n) asm volatile("s_waitcnt lgkmcnt(" #n ")" ::: "memory")
; #define PG8_BAR __builtin_amdgcn_s_barrier()
; #define PG8_SCHED __builtin_amdgcn_sched_barrier(0)
; template <class Epi, class Sched>
; DI void gemm_phase(LAS unsigned char* lds, const Gemm g, const Sched& S, const Epi& E) {
;     ...
;             PG8_WAIT_L(8); PG8_BAR; PG8_WAIT_L(0); PG8_MMA(0, 0, At, B0); PG8_BAR; PG8_SCHED;
;             PG8_LDB(B1, 1, 1); PG8_STAGE(PG8_SB(1, 0), b3, voffB);
;             PG8_BAR; PG8_WAIT_L(0); PG8_MMA(0, 1, At, B1); PG8_BAR;
;             PG8_LDA(At, 1, 1); PG8_STAGE(PG8_SA(1, 0), a3, voffA);
;             PG8_BAR; PG8_WAIT_L(0); PG8_MMA(1, 0, At, B0); PG8_BAR; PG8_SCHED;
;             PG8_STAGE(PG8_SB(1, 1), b3 + hstep, voffB);
;             PG8_WAIT_V(6); PG8_BAR; PG8_MMA(1, 1, At, B1); PG8_BAR;
	s_waitcnt lgkmcnt(0)
	s_setprio 1
	v_mfma_f32_16x16x32_bf16 v[124:127], v[144:147], v[176:179], v[124:127]
	v_mfma_f32_16x16x32_bf16 v[120:123], v[168:171], v[176:179], v[120:123]
	v_mfma_f32_16x16x32_bf16 v[108:111], v[144:147], v[188:191], v[108:111]
	v_mfma_f32_16x16x32_bf16 v[104:107], v[168:171], v[188:191], v[104:107]
	v_mfma_f32_16x16x32_bf16 v[92:95], v[144:147], v[198:201], v[92:95]
	v_mfma_f32_16x16x32_bf16 v[88:91], v[168:171], v[198:201], v[88:91]
	v_mfma_f32_16x16x32_bf16 v[76:79], v[144:147], v[206:209], v[76:79]
	v_mfma_f32_16x16x32_bf16 v[72:75], v[168:171], v[206:209], v[72:75]
	v_mfma_f32_16x16x32_bf16 v[124:127], v[164:167], v[180:183], v[124:127]
	v_mfma_f32_16x16x32_bf16 v[120:123], v[172:175], v[180:183], v[120:123]
	v_mfma_f32_16x16x32_bf16 v[108:111], v[164:167], v[194:197], v[108:111]
	v_mfma_f32_16x16x32_bf16 v[104:107], v[172:175], v[194:197], v[104:107]
	v_mfma_f32_16x16x32_bf16 v[92:95], v[164:167], v[202:205], v[92:95]
	v_mfma_f32_16x16x32_bf16 v[88:91], v[172:175], v[202:205], v[88:91]
	v_mfma_f32_16x16x32_bf16 v[76:79], v[164:167], v[210:213], v[76:79]
	v_mfma_f32_16x16x32_bf16 v[72:75], v[172:175], v[210:213], v[72:75]
	s_setprio 0
	s_barrier
	s_add_i32 s5, 0, 0x1c000
	s_add_i32 s0, s4, s53
	s_add_i32 m0, s0, 0xffffff80
	ds_read_b128 v[214:217], v231
	ds_read_b128 v[218:221], v231 offset:1024
	ds_read_b128 v[222:225], v231 offset:2048
	global_load_lds_dwordx4 v130, s[42:43] offset:128
	s_add_i32 m0, s0, 0x1f80
	ds_read_b128 v[226:229], v231 offset:3072
	global_load_lds_dwordx4 v134, s[42:43] offset:128
	s_barrier
	s_waitcnt lgkmcnt(0)
	s_setprio 1
	v_mfma_f32_16x16x32_bf16 v[116:119], v[214:217], v[176:179], v[116:119]
	v_mfma_f32_16x16x32_bf16 v[112:115], v[222:225], v[176:179], v[112:115]
	v_mfma_f32_16x16x32_bf16 v[100:103], v[214:217], v[188:191], v[100:103]
	v_mfma_f32_16x16x32_bf16 v[96:99], v[222:225], v[188:191], v[96:99]
	v_mfma_f32_16x16x32_bf16 v[84:87], v[214:217], v[198:201], v[84:87]
	v_mfma_f32_16x16x32_bf16 v[80:83], v[222:225], v[198:201], v[80:83]
	v_mfma_f32_16x16x32_bf16 v[68:71], v[214:217], v[206:209], v[68:71]
	v_mfma_f32_16x16x32_bf16 v[64:67], v[222:225], v[206:209], v[64:67]
	v_mfma_f32_16x16x32_bf16 v[116:119], v[218:221], v[180:183], v[116:119]
	v_mfma_f32_16x16x32_bf16 v[112:115], v[226:229], v[180:183], v[112:115]
	v_mfma_f32_16x16x32_bf16 v[100:103], v[218:221], v[194:197], v[100:103]
	v_mfma_f32_16x16x32_bf16 v[96:99], v[226:229], v[194:197], v[96:99]
	v_mfma_f32_16x16x32_bf16 v[84:87], v[218:221], v[202:205], v[84:87]
	v_mfma_f32_16x16x32_bf16 v[80:83], v[226:229], v[202:205], v[80:83]
	v_mfma_f32_16x16x32_bf16 v[68:71], v[218:221], v[210:213], v[68:71]
	v_mfma_f32_16x16x32_bf16 v[64:67], v[226:229], v[210:213], v[64:67]
	s_setprio 0
	s_add_i32 m0, s61, 0xffffff80
	s_barrier
	ds_read_b128 v[176:179], v159 offset:49152
	ds_read_b128 v[180:183], v159 offset:50176
	ds_read_b128 v[188:191], v159 offset:51200
	ds_read_b128 v[194:197], v159 offset:52224
	ds_read_b128 v[198:201], v159 offset:53248
	ds_read_b128 v[202:205], v159 offset:54272
	ds_read_b128 v[206:209], v159 offset:55296
	global_load_lds_dwordx4 v128, s[44:45] offset:128
	s_add_i32 m0, s62, 0xffffff80
	ds_read_b128 v[210:213], v159 offset:56320
	global_load_lds_dwordx4 v132, s[44:45] offset:128
	s_barrier
	s_waitcnt lgkmcnt(0)
	s_setprio 1
	v_mfma_f32_16x16x32_bf16 v[60:63], v[144:147], v[176:179], v[60:63]
	v_mfma_f32_16x16x32_bf16 v[56:59], v[168:171], v[176:179], v[56:59]
	v_mfma_f32_16x16x32_bf16 v[44:47], v[144:147], v[188:191], v[44:47]
	v_mfma_f32_16x16x32_bf16 v[40:43], v[168:171], v[188:191], v[40:43]
	v_mfma_f32_16x16x32_bf16 v[28:31], v[144:147], v[198:201], v[28:31]
	v_mfma_f32_16x16x32_bf16 v[24:27], v[168:171], v[198:201], v[24:27]
	v_mfma_f32_16x16x32_bf16 v[12:15], v[144:147], v[206:209], v[12:15]
	v_mfma_f32_16x16x32_bf16 v[8:11], v[168:171], v[206:209], v[8:11]
	v_mfma_f32_16x16x32_bf16 v[60:63], v[164:167], v[180:183], v[60:63]
	v_mfma_f32_16x16x32_bf16 v[56:59], v[172:175], v[180:183], v[56:59]
	v_mfma_f32_16x16x32_bf16 v[44:47], v[164:167], v[194:197], v[44:47]
	v_mfma_f32_16x16x32_bf16 v[40:43], v[172:175], v[194:197], v[40:43]
	v_mfma_f32_16x16x32_bf16 v[28:31], v[164:167], v[202:205], v[28:31]
	v_mfma_f32_16x16x32_bf16 v[24:27], v[172:175], v[202:205], v[24:27]
	v_mfma_f32_16x16x32_bf16 v[12:15], v[164:167], v[210:213], v[12:15]
	v_mfma_f32_16x16x32_bf16 v[8:11], v[172:175], v[210:213], v[8:11]
	s_setprio 0
	s_barrier
	s_add_u32 s0, s42, 0x160080
	s_addc_u32 s1, s43, 0
	s_add_i32 s4, s5, s53
	s_mov_b32 m0, s4
	s_nop 0
	global_load_lds_dwordx4 v130, s[0:1]
	s_add_i32 m0, s4, 0x2000
	s_nop 0
	global_load_lds_dwordx4 v134, s[0:1]
	s_waitcnt vmcnt(6)
	s_barrier
	s_setprio 1
	v_mfma_f32_16x16x32_bf16 v[52:55], v[214:217], v[176:179], v[52:55]
	v_mfma_f32_16x16x32_bf16 v[48:51], v[222:225], v[176:179], v[48:51]
	v_mfma_f32_16x16x32_bf16 v[36:39], v[214:217], v[188:191], v[36:39]
	v_mfma_f32_16x16x32_bf16 v[32:35], v[222:225], v[188:191], v[32:35]
	v_mfma_f32_16x16x32_bf16 v[20:23], v[214:217], v[198:201], v[20:23]
	v_mfma_f32_16x16x32_bf16 v[16:19], v[222:225], v[198:201], v[16:19]
	v_mfma_f32_16x16x32_bf16 v[4:7], v[214:217], v[206:209], v[4:7]
	v_mfma_f32_16x16x32_bf16 v[0:3], v[222:225], v[206:209], v[0:3]
	v_mfma_f32_16x16x32_bf16 v[52:55], v[218:221], v[180:183], v[52:55]
	v_mfma_f32_16x16x32_bf16 v[48:51], v[226:229], v[180:183], v[48:51]
	v_mfma_f32_16x16x32_bf16 v[36:39], v[218:221], v[194:197], v[36:39]
	v_mfma_f32_16x16x32_bf16 v[32:35], v[226:229], v[194:197], v[32:35]
	v_mfma_f32_16x16x32_bf16 v[20:23], v[218:221], v[202:205], v[20:23]
	v_mfma_f32_16x16x32_bf16 v[16:19], v[226:229], v[202:205], v[16:19]
	v_mfma_f32_16x16x32_bf16 v[4:7], v[218:221], v[210:213], v[4:7]
	v_mfma_f32_16x16x32_bf16 v[0:3], v[226:229], v[210:213], v[0:3]
	s_setprio 0
	s_add_i32 s69, s69, 2
	s_add_u32 s40, s40, 0x100
	s_addc_u32 s41, s41, 0
	s_add_u32 s35, s35, 0x100
	s_addc_u32 s68, s68, 0
	s_cmpk_gt_u32 s69, 0x55
	s_barrier
	s_cbranch_scc0 .LBB0_297

;     DI size_t aoff(const Unit& u, size_t tstep) const { return (size_t)u.pm * tstep; }
;     DI size_t boff(const Unit& u, size_t tstep) const { return (size_t)u.pn * tstep; }
;     DI bool next(int i, Unit& u) const { const long L = (long)i * G + c; if (L >= np) return false; u.pm = pmv; u.pn = (int)(L % nN); u.ks = (int)(L / nN); return true; }
;     DI size_t aoff(const Unit& u, size_t) const { return (size_t)u.ks * kbytes; }
;     DI size_t boff(const Unit& u, size_t tstep) const { return (size_t)u.pn * tstep + (size_t)u.ks * kbytes; }
;     DI bool next(int i, Unit& u) const { Unit t; if (!S.next(i / 3, t)) return false; u.pm = t.pm; u.pn = t.pn; u.ks = i % 3; return true; }
;     DI size_t aoff(const Unit& u, size_t tstep) const { return (u.ks < 2 ? offU : offOA) + (size_t)u.pm * tstep; }
; #define PG8_LDA(dst, b, h) do { _Pragma("unroll") for (int m = 0; m < 4; ++m) _Pragma("unroll") for (int k = 0; k < 2; ++k) dst[m][k] = *(const LAS bf16x8*)(lds + PG8_SA(b, h) + aoff + m * 2048 + k * 1024); } while (0)
; template <class Epi, class Sched>
; DI void gemm_phase(LAS unsigned char* lds, const Gemm g, const Sched& S, const Epi& E) {
;     ...
;         const bool has_next = S.next(ui + 1, nxt);
;         const char* nA = has_next ? (const char*)g.A + S.aoff(nxt, tstep) : cA; const char* nB = has_next ? (const char*)g.Bt + S.boff(nxt, tstep) : cB;
;         for (int t = 0; t < nt; t += 2) {
;             if constexpr (Epi::HAS_MID) { if (t == E.mid_t(nt)) { int fr3 = fr, fq3 = fq; asm volatile("" : "+v"(fr3), "+v"(fq3)); E.mid(acc, cur, wr, wc, fr3, fq3); } }
;             const bool last = (t == nt - 2);
;             const char* a1 = cA + (size_t)(t + 1) * kstep;
;             const char* a2 = last ? nA : cA + (size_t)(t + 2) * kstep; const char* b2 = last ? nB : cB + (size_t)(t + 2) * kstep;
;             const char* a3 = a2 + kstep; const char* b3 = b2 + kstep;
;             PG8_LDB(B0, 0, 0); PG8_SCHED; PG8_LDA(At, 0, 0); PG8_STAGE(PG8_SA(1, 1), a1 + hstep, voffA);
;             PG8_WAIT_L(8); PG8_BAR; PG8_WAIT_L(0); PG8_MMA(0, 0, At, B0); PG8_BAR; PG8_SCHED;
;             PG8_LDB(B1, 0, 1); PG8_STAGE(PG8_SB(0, 0), b2, voffB);
;             PG8_BAR; PG8_WAIT_L(0); PG8_MMA(0, 1, At, B1); PG8_BAR;
;             PG8_LDA(At, 0, 1); PG8_STAGE(PG8_SA(0, 0), a2, voffA);
;             PG8_BAR; PG8_WAIT_L(0); PG8_MMA(1, 0, At, B0); PG8_BAR; PG8_SCHED;
.LBB0_526:
	s_ashr_i32 s51, s50, 31
	s_lshl_b64 s[0:1], s[50:51], 20
	s_add_u32 s52, s70, s0
	v_cmp_lt_i64_e32 vcc, s[12:13], v[142:143]
	s_addc_u32 s53, s71, s1
	s_and_b64 s[0:1], vcc, exec
	s_cselect_b32 s14, s53, s9
	s_cselect_b32 s15, s52, s8
	s_ashr_i32 s49, s48, 31
	s_lshl_b64 s[0:1], s[48:49], 20
	s_add_u32 s54, s72, s0
	s_addc_u32 s55, s73, s1
	s_and_b64 s[0:1], vcc, exec
	s_cselect_b32 s16, s55, s11
	s_cselect_b32 s17, s54, s10
	s_add_u32 s8, s8, 0x80080
	s_addc_u32 s9, s9, 0
	s_add_u32 s28, s10, 0x100
	v_mov_b32_e32 v0, 0
	s_addc_u32 s34, s11, 0
	s_mov_b32 s35, -2
	ds_read_b128 v[146:149], v164
	ds_read_b128 v[150:153], v164 offset:1024
	ds_read_b128 v[154:157], v164 offset:2048
	ds_read_b128 v[170:173], v164 offset:3072
	s_add_u32 s0, s8, 0xfff80080
	s_addc_u32 s1, s9, -1
	s_cmp_eq_u32 s35, 28
	s_cselect_b32 s13, s14, s1
	s_cselect_b32 s12, s15, s0
	s_cselect_b32 s11, s16, s34
	s_cselect_b32 s10, s17, s28
	s_add_i32 m0, s59, 0xc000
	ds_read_b128 v[174:177], v165
	ds_read_b128 v[178:181], v165 offset:1024
	ds_read_b128 v[188:191], v165 offset:2048
	ds_read_b128 v[194:197], v165 offset:3072
	ds_read_b128 v[198:201], v165 offset:4096
	ds_read_b128 v[202:205], v165 offset:5120
	ds_read_b128 v[206:209], v165 offset:6144
	global_load_lds_dwordx4 v138, s[8:9]
	s_add_i32 m0, s59, 0xe000
	ds_read_b128 v[210:213], v165 offset:7168
	global_load_lds_dwordx4 v140, s[8:9]
	s_waitcnt lgkmcnt(8)
	s_barrier
	s_waitcnt lgkmcnt(0)
	s_setprio 1
	v_mfma_f32_16x16x32_bf16 v[124:127], v[146:149], v[174:177], 0
	v_mfma_f32_16x16x32_bf16 v[120:123], v[154:157], v[174:177], 0
	v_mfma_f32_16x16x32_bf16 v[108:111], v[146:149], v[188:191], 0
	v_mfma_f32_16x16x32_bf16 v[104:107], v[154:157], v[188:191], 0
	v_mfma_f32_16x16x32_bf16 v[92:95], v[146:149], v[198:201], 0
	v_mfma_f32_16x16x32_bf16 v[88:91], v[154:157], v[198:201], 0
	v_mfma_f32_16x16x32_bf16 v[76:79], v[146:149], v[206:209], 0
	v_mfma_f32_16x16x32_bf16 v[72:75], v[154:157], v[206:209], 0
	v_mfma_f32_16x16x32_bf16 v[124:127], v[150:153], v[178:181], v[124:127]
	v_mfma_f32_16x16x32_bf16 v[120:123], v[170:173], v[178:181], v[120:123]
	v_mfma_f32_16x16x32_bf16 v[108:111], v[150:153], v[194:197], v[108:111]
	v_mfma_f32_16x16x32_bf16 v[104:107], v[170:173], v[194:197], v[104:107]
	v_mfma_f32_16x16x32_bf16 v[92:95], v[150:153], v[202:205], v[92:95]
	v_mfma_f32_16x16x32_bf16 v[88:91], v[170:173], v[202:205], v[88:91]
	v_mfma_f32_16x16x32_bf16 v[76:79], v[150:153], v[210:213], v[76:79]
	v_mfma_f32_16x16x32_bf16 v[72:75], v[170:173], v[210:213], v[72:75]
	s_setprio 0
	s_barrier
	s_add_i32 s0, s47, s74
	s_mov_b32 m0, s0
	ds_read_b128 v[214:217], v166
	ds_read_b128 v[218:221], v166 offset:1024
	ds_read_b128 v[222:225], v166 offset:2048
	global_load_lds_dwordx4 v130, s[10:11]
	s_add_i32 m0, s0, 0x2000
	ds_read_b128 v[226:229], v166 offset:3072
	global_load_lds_dwordx4 v134, s[10:11]
	s_barrier
	s_waitcnt lgkmcnt(0)
	s_setprio 1
	v_mfma_f32_16x16x32_bf16 v[116:119], v[214:217], v[174:177], 0
	v_mfma_f32_16x16x32_bf16 v[112:115], v[222:225], v[174:177], 0
	v_mfma_f32_16x16x32_bf16 v[100:103], v[214:217], v[188:191], 0
	v_mfma_f32_16x16x32_bf16 v[96:99], v[222:225], v[188:191], 0
	v_mfma_f32_16x16x32_bf16 v[84:87], v[214:217], v[198:201], 0
	v_mfma_f32_16x16x32_bf16 v[80:83], v[222:225], v[198:201], 0
	v_mfma_f32_16x16x32_bf16 v[68:71], v[214:217], v[206:209], 0
	v_mfma_f32_16x16x32_bf16 v[64:67], v[222:225], v[206:209], 0
	v_mfma_f32_16x16x32_bf16 v[116:119], v[218:221], v[178:181], v[116:119]
	v_mfma_f32_16x16x32_bf16 v[112:115], v[226:229], v[178:181], v[112:115]
	v_mfma_f32_16x16x32_bf16 v[100:103], v[218:221], v[194:197], v[100:103]
	v_mfma_f32_16x16x32_bf16 v[96:99], v[226:229], v[194:197], v[96:99]
	v_mfma_f32_16x16x32_bf16 v[84:87], v[218:221], v[202:205], v[84:87]
	v_mfma_f32_16x16x32_bf16 v[80:83], v[226:229], v[202:205], v[80:83]
	v_mfma_f32_16x16x32_bf16 v[68:71], v[218:221], v[210:213], v[68:71]
	v_mfma_f32_16x16x32_bf16 v[64:67], v[226:229], v[210:213], v[64:67]
	s_setprio 0
	s_mov_b32 m0, s59
	s_barrier
	ds_read_b128 v[174:177], v165 offset:16384
	ds_read_b128 v[178:181], v165 offset:17408
	ds_read_b128 v[188:191], v165 offset:18432
	ds_read_b128 v[194:197], v165 offset:19456
	ds_read_b128 v[198:201], v165 offset:20480
	ds_read_b128 v[202:205], v165 offset:21504
	ds_read_b128 v[206:209], v165 offset:22528
	global_load_lds_dwordx4 v128, s[12:13]
	s_mov_b32 m0, s75
	ds_read_b128 v[210:213], v165 offset:23552
	global_load_lds_dwordx4 v132, s[12:13]
	s_barrier
	s_waitcnt lgkmcnt(0)
	s_setprio 1
	v_mfma_f32_16x16x32_bf16 v[60:63], v[146:149], v[174:177], 0
	v_mfma_f32_16x16x32_bf16 v[56:59], v[154:157], v[174:177], 0
	v_mfma_f32_16x16x32_bf16 v[44:47], v[146:149], v[188:191], 0
	v_mfma_f32_16x16x32_bf16 v[40:43], v[154:157], v[188:191], 0
	v_mfma_f32_16x16x32_bf16 v[28:31], v[146:149], v[198:201], 0
	v_mfma_f32_16x16x32_bf16 v[24:27], v[154:157], v[198:201], 0
	v_mfma_f32_16x16x32_bf16 v[12:15], v[146:149], v[206:209], 0
	v_mfma_f32_16x16x32_bf16 v[8:11], v[154:157], v[206:209], 0
	v_mfma_f32_16x16x32_bf16 v[60:63], v[150:153], v[178:181], v[60:63]
	v_mfma_f32_16x16x32_bf16 v[56:59], v[170:173], v[178:181], v[56:59]
	v_mfma_f32_16x16x32_bf16 v[44:47], v[150:153], v[194:197], v[44:47]
	v_mfma_f32_16x16x32_bf16 v[40:43], v[170:173], v[194:197], v[40:43]
	v_mfma_f32_16x16x32_bf16 v[28:31], v[150:153], v[202:205], v[28:31]
	v_mfma_f32_16x16x32_bf16 v[24:27], v[170:173], v[202:205], v[24:27]
	v_mfma_f32_16x16x32_bf16 v[12:15], v[150:153], v[210:213], v[12:15]
	v_mfma_f32_16x16x32_bf16 v[8:11], v[170:173], v[210:213], v[8:11]
	s_setprio 0
	s_barrier
; #define PG8_STAGE(bufoff, gbase, voff) do { _Pragma("unroll") for (int _i = 0; _i < 2; ++_i) \
;         __builtin_amdgcn_global_load_lds((const unsigned*)((const char*)(gbase) + (voff)[_i]), (LAS unsigned*)(lds + (bufoff) + ldsw + _i * 8192), 16, 0, 0); } while (0)
; #define PG8_LDA(dst, b, h) do { _Pragma("unroll") for (int m = 0; m < 4; ++m) _Pragma("unroll") for (int k = 0; k < 2; ++k) dst[m][k] = *(const LAS bf16x8*)(lds + PG8_SA(b, h) + aoff + m * 2048 + k * 1024); } while (0)
; #define PG8_LDB(dst, b, h) do { _Pragma("unroll") for (int n = 0; n < 2; ++n) _Pragma("unroll") for (int k = 0; k < 2; ++k) dst[n][k] = *(const LAS bf16x8*)(lds + PG8_SB(b, h) + boff + n * 2048 + k * 1024); } while (0)
; #define PG8_MMA(ai, bj, At, Bt) do { __builtin_amdgcn_s_setprio(1); _Pragma("unroll") for (int m = 0; m < 4; ++m) _Pragma("unroll") for (int n = 0; n < 2; ++n) _Pragma("unroll") for (int k = 0; k < 2; ++k) \
;         acc[ai][bj][m][n] = __builtin_amdgcn_mfma_f32_16x16x32_bf16(Bt[n][k], At[m][k], acc[ai][bj][m][n], 0, 0, 0); __builtin_amdgcn_s_setprio(0); } while (0)
; #define PG8_WAIT_V(n) asm volatile("s_waitcnt vmcnt(" #n ")" ::: "memory")
; #define PG8_WAIT_L(n) asm volatile("s_waitcnt lgkmcnt(" #n ")" ::: "memory")
; #define PG8_BAR __builtin_amdgcn_s_barrier()
; #define PG8_SCHED __builtin_amdgcn_sched_barrier(0)
; template <class Epi, class Sched>
; DI void gemm_phase(LAS unsigned char* lds, const Gemm g, const Sched& S, const Epi& E) {
;     ...
;             PG8_STAGE(PG8_SB(0, 1), b2 + hstep, voffB);
;             PG8_WAIT_V(6); PG8_BAR; PG8_MMA(1, 1, At, B1); PG8_BAR;
;             PG8_LDB(B0, 1, 0); PG8_SCHED; PG8_LDA(At, 1, 0); PG8_STAGE(PG8_SA(0, 1), a2 + hstep, voffA);
;             PG8_WAIT_L(8); PG8_BAR; PG8_WAIT_L(0); PG8_MMA(0, 0, At, B0); PG8_BAR; PG8_SCHED;
;             PG8_LDB(B1, 1, 1); PG8_STAGE(PG8_SB(1, 0), b3, voffB);
;             PG8_BAR; PG8_WAIT_L(0); PG8_MMA(0, 1, At, B1); PG8_BAR;
;             PG8_LDA(At, 1, 1); PG8_STAGE(PG8_SA(1, 0), a3, voffA);
;             PG8_BAR; PG8_WAIT_L(0); PG8_MMA(1, 0, At, B0); PG8_BAR; PG8_SCHED;
	s_add_u32 s0, s10, 0x80000
	s_addc_u32 s1, s11, 0
	s_add_i32 s4, s87, s74
	s_mov_b32 m0, s4
	s_nop 0
	global_load_lds_dwordx4 v130, s[0:1]
	s_add_i32 m0, s4, 0x2000
	s_nop 0
	global_load_lds_dwordx4 v134, s[0:1]
	s_waitcnt vmcnt(6)
	s_barrier
	s_setprio 1
	v_mfma_f32_16x16x32_bf16 v[52:55], v[214:217], v[174:177], 0
	v_mfma_f32_16x16x32_bf16 v[48:51], v[222:225], v[174:177], 0
	v_mfma_f32_16x16x32_bf16 v[36:39], v[214:217], v[188:191], 0
	v_mfma_f32_16x16x32_bf16 v[32:35], v[222:225], v[188:191], 0
	v_mfma_f32_16x16x32_bf16 v[20:23], v[214:217], v[198:201], 0
	v_mfma_f32_16x16x32_bf16 v[16:19], v[222:225], v[198:201], 0
	v_mfma_f32_16x16x32_bf16 v[4:7], v[214:217], v[206:209], 0
	v_mfma_f32_16x16x32_bf16 v[0:3], v[222:225], v[206:209], 0
	v_mfma_f32_16x16x32_bf16 v[52:55], v[218:221], v[178:181], v[52:55]
	v_mfma_f32_16x16x32_bf16 v[48:51], v[226:229], v[178:181], v[48:51]
	v_mfma_f32_16x16x32_bf16 v[36:39], v[218:221], v[194:197], v[36:39]
	v_mfma_f32_16x16x32_bf16 v[32:35], v[226:229], v[194:197], v[32:35]
	v_mfma_f32_16x16x32_bf16 v[20:23], v[218:221], v[202:205], v[20:23]
	v_mfma_f32_16x16x32_bf16 v[16:19], v[226:229], v[202:205], v[16:19]
	v_mfma_f32_16x16x32_bf16 v[4:7], v[218:221], v[210:213], v[4:7]
	v_mfma_f32_16x16x32_bf16 v[0:3], v[226:229], v[210:213], v[0:3]
	s_setprio 0
	s_add_i32 s4, 0, 0x18000
	v_add_u32_e32 v158, s4, v163
	s_barrier
	ds_read_b128 v[146:149], v158
	ds_read_b128 v[150:153], v158 offset:1024
	ds_read_b128 v[154:157], v158 offset:2048
	ds_read_b128 v[170:173], v158 offset:3072
	s_add_u32 s0, s12, 0x80000
	s_addc_u32 s1, s13, 0
	s_mov_b32 m0, s76
	ds_read_b128 v[174:177], v165 offset:32768
	ds_read_b128 v[178:181], v165 offset:33792
	ds_read_b128 v[188:191], v165 offset:34816
	ds_read_b128 v[194:197], v165 offset:35840
	ds_read_b128 v[198:201], v165 offset:36864
	ds_read_b128 v[202:205], v165 offset:37888
	ds_read_b128 v[206:209], v165 offset:38912
	global_load_lds_dwordx4 v128, s[0:1]
	s_mov_b32 m0, s77
	ds_read_b128 v[210:213], v165 offset:39936
	global_load_lds_dwordx4 v132, s[0:1]
	s_waitcnt lgkmcnt(8)
	s_barrier
	s_waitcnt lgkmcnt(0)
	s_setprio 1
	v_mfma_f32_16x16x32_bf16 v[124:127], v[146:149], v[174:177], v[124:127]
	v_mfma_f32_16x16x32_bf16 v[120:123], v[154:157], v[174:177], v[120:123]
	v_mfma_f32_16x16x32_bf16 v[108:111], v[146:149], v[188:191], v[108:111]
	v_mfma_f32_16x16x32_bf16 v[104:107], v[154:157], v[188:191], v[104:107]
	v_mfma_f32_16x16x32_bf16 v[92:95], v[146:149], v[198:201], v[92:95]
	v_mfma_f32_16x16x32_bf16 v[88:91], v[154:157], v[198:201], v[88:91]
	v_mfma_f32_16x16x32_bf16 v[76:79], v[146:149], v[206:209], v[76:79]
	v_mfma_f32_16x16x32_bf16 v[72:75], v[154:157], v[206:209], v[72:75]
	v_mfma_f32_16x16x32_bf16 v[124:127], v[150:153], v[178:181], v[124:127]
	v_mfma_f32_16x16x32_bf16 v[120:123], v[170:173], v[178:181], v[120:123]
	v_mfma_f32_16x16x32_bf16 v[108:111], v[150:153], v[194:197], v[108:111]
	v_mfma_f32_16x16x32_bf16 v[104:107], v[170:173], v[194:197], v[104:107]
	v_mfma_f32_16x16x32_bf16 v[92:95], v[150:153], v[202:205], v[92:95]
	v_mfma_f32_16x16x32_bf16 v[88:91], v[170:173], v[202:205], v[88:91]
	v_mfma_f32_16x16x32_bf16 v[76:79], v[150:153], v[210:213], v[76:79]
	v_mfma_f32_16x16x32_bf16 v[72:75], v[170:173], v[210:213], v[72:75]
	s_setprio 0
	s_barrier
	s_add_i32 s5, 0, 0x1c000
	s_add_i32 s0, s4, s74
	v_add_u32_e32 v159, s5, v163
	s_add_i32 m0, s0, 0xffffff80
	ds_read_b128 v[214:217], v159
	ds_read_b128 v[218:221], v159 offset:1024
	ds_read_b128 v[222:225], v159 offset:2048
	global_load_lds_dwordx4 v130, s[10:11] offset:128
	s_add_i32 m0, s0, 0x1f80
	ds_read_b128 v[226:229], v159 offset:3072
	global_load_lds_dwordx4 v134, s[10:11] offset:128
	s_barrier
	s_waitcnt lgkmcnt(0)
	s_setprio 1
	v_mfma_f32_16x16x32_bf16 v[116:119], v[214:217], v[174:177], v[116:119]
	v_mfma_f32_16x16x32_bf16 v[112:115], v[222:225], v[174:177], v[112:115]
	v_mfma_f32_16x16x32_bf16 v[100:103], v[214:217], v[188:191], v[100:103]
	v_mfma_f32_16x16x32_bf16 v[96:99], v[222:225], v[188:191], v[96:99]
	v_mfma_f32_16x16x32_bf16 v[84:87], v[214:217], v[198:201], v[84:87]
	v_mfma_f32_16x16x32_bf16 v[80:83], v[222:225], v[198:201], v[80:83]
	v_mfma_f32_16x16x32_bf16 v[68:71], v[214:217], v[206:209], v[68:71]
	v_mfma_f32_16x16x32_bf16 v[64:67], v[222:225], v[206:209], v[64:67]
	v_mfma_f32_16x16x32_bf16 v[116:119], v[218:221], v[178:181], v[116:119]
	v_mfma_f32_16x16x32_bf16 v[112:115], v[226:229], v[178:181], v[112:115]
	v_mfma_f32_16x16x32_bf16 v[100:103], v[218:221], v[194:197], v[100:103]
	v_mfma_f32_16x16x32_bf16 v[96:99], v[226:229], v[194:197], v[96:99]
	v_mfma_f32_16x16x32_bf16 v[84:87], v[218:221], v[202:205], v[84:87]
	v_mfma_f32_16x16x32_bf16 v[80:83], v[226:229], v[202:205], v[80:83]
	v_mfma_f32_16x16x32_bf16 v[68:71], v[218:221], v[210:213], v[68:71]
	v_mfma_f32_16x16x32_bf16 v[64:67], v[226:229], v[210:213], v[64:67]
	s_setprio 0
	s_add_i32 m0, s97, 0xffffff80
	s_barrier
	ds_read_b128 v[174:177], v165 offset:49152
	ds_read_b128 v[178:181], v165 offset:50176
	ds_read_b128 v[188:191], v165 offset:51200
	ds_read_b128 v[194:197], v165 offset:52224
	ds_read_b128 v[198:201], v165 offset:53248
	ds_read_b128 v[202:205], v165 offset:54272
	ds_read_b128 v[206:209], v165 offset:55296
	global_load_lds_dwordx4 v128, s[12:13] offset:128
	s_add_i32 m0, s84, 0xffffff80
	ds_read_b128 v[210:213], v165 offset:56320
	global_load_lds_dwordx4 v132, s[12:13] offset:128
	s_barrier
; #define PG8_STAGE(bufoff, gbase, voff) do { _Pragma("unroll") for (int _i = 0; _i < 2; ++_i) \
;         __builtin_amdgcn_global_load_lds((const unsigned*)((const char*)(gbase) + (voff)[_i]), (LAS unsigned*)(lds + (bufoff) + ldsw + _i * 8192), 16, 0, 0); } while (0)
; #define PG8_LDA(dst, b, h) do { _Pragma("unroll") for (int m = 0; m < 4; ++m) _Pragma("unroll") for (int k = 0; k < 2; ++k) dst[m][k] = *(const LAS bf16x8*)(lds + PG8_SA(b, h) + aoff + m * 2048 + k * 1024); } while (0)
; #define PG8_LDB(dst, b, h) do { _Pragma("unroll") for (int n = 0; n < 2; ++n) _Pragma("unroll") for (int k = 0; k < 2; ++k) dst[n][k] = *(const LAS bf16x8*)(lds + PG8_SB(b, h) + boff + n * 2048 + k * 1024); } while (0)
; #define PG8_MMA(ai, bj, At, Bt) do { __builtin_amdgcn_s_setprio(1); _Pragma("unroll") for (int m = 0; m < 4; ++m) _Pragma("unroll") for (int n = 0; n < 2; ++n) _Pragma("unroll") for (int k = 0; k < 2; ++k) \
;         acc[ai][bj][m][n] = __builtin_amdgcn_mfma_f32_16x16x32_bf16(Bt[n][k], At[m][k], acc[ai][bj][m][n], 0, 0, 0); __builtin_amdgcn_s_setprio(0); } while (0)
; #define PG8_WAIT_V(n) asm volatile("s_waitcnt vmcnt(" #n ")" ::: "memory")
; #define PG8_WAIT_L(n) asm volatile("s_waitcnt lgkmcnt(" #n ")" ::: "memory")
; #define PG8_BAR __builtin_amdgcn_s_barrier()
; #define PG8_SCHED __builtin_amdgcn_sched_barrier(0)
; template <class Epi, class Sched>
; DI void gemm_phase(LAS unsigned char* lds, const Gemm g, const Sched& S, const Epi& E) {
;     ...
;             const bool last = (t == nt - 2);
;             const char* a1 = cA + (size_t)(t + 1) * kstep;
;             const char* a2 = last ? nA : cA + (size_t)(t + 2) * kstep; const char* b2 = last ? nB : cB + (size_t)(t + 2) * kstep;
;             const char* a3 = a2 + kstep; const char* b3 = b2 + kstep;
;             PG8_LDB(B0, 0, 0); PG8_SCHED; PG8_LDA(At, 0, 0); PG8_STAGE(PG8_SA(1, 1), a1 + hstep, voffA);
;             PG8_WAIT_L(8); PG8_BAR; PG8_WAIT_L(0); PG8_MMA(0, 0, At, B0); PG8_BAR; PG8_SCHED;
;             PG8_LDB(B1, 0, 1); PG8_STAGE(PG8_SB(0, 0), b2, voffB);
;     ...
;             PG8_BAR; PG8_WAIT_L(0); PG8_MMA(1, 0, At, B0); PG8_BAR; PG8_SCHED;
;             PG8_STAGE(PG8_SB(1, 1), b3 + hstep, voffB);
;             PG8_WAIT_V(6); PG8_BAR; PG8_MMA(1, 1, At, B1); PG8_BAR;
	s_waitcnt lgkmcnt(0)
	s_setprio 1
	v_mfma_f32_16x16x32_bf16 v[60:63], v[146:149], v[174:177], v[60:63]
	v_mfma_f32_16x16x32_bf16 v[56:59], v[154:157], v[174:177], v[56:59]
	v_mfma_f32_16x16x32_bf16 v[44:47], v[146:149], v[188:191], v[44:47]
	v_mfma_f32_16x16x32_bf16 v[40:43], v[154:157], v[188:191], v[40:43]
	v_mfma_f32_16x16x32_bf16 v[28:31], v[146:149], v[198:201], v[28:31]
	v_mfma_f32_16x16x32_bf16 v[24:27], v[154:157], v[198:201], v[24:27]
	v_mfma_f32_16x16x32_bf16 v[12:15], v[146:149], v[206:209], v[12:15]
	v_mfma_f32_16x16x32_bf16 v[8:11], v[154:157], v[206:209], v[8:11]
	v_mfma_f32_16x16x32_bf16 v[60:63], v[150:153], v[178:181], v[60:63]
	v_mfma_f32_16x16x32_bf16 v[56:59], v[170:173], v[178:181], v[56:59]
	v_mfma_f32_16x16x32_bf16 v[44:47], v[150:153], v[194:197], v[44:47]
	v_mfma_f32_16x16x32_bf16 v[40:43], v[170:173], v[194:197], v[40:43]
	v_mfma_f32_16x16x32_bf16 v[28:31], v[150:153], v[202:205], v[28:31]
	v_mfma_f32_16x16x32_bf16 v[24:27], v[170:173], v[202:205], v[24:27]
	v_mfma_f32_16x16x32_bf16 v[12:15], v[150:153], v[210:213], v[12:15]
	v_mfma_f32_16x16x32_bf16 v[8:11], v[170:173], v[210:213], v[8:11]
	s_setprio 0
	s_barrier
	s_add_u32 s0, s10, 0x80080
	s_addc_u32 s1, s11, 0
	s_add_i32 s4, s5, s74
	s_mov_b32 m0, s4
	s_nop 0
	global_load_lds_dwordx4 v130, s[0:1]
	v_lshl_add_u64 v[146:147], s[0:1], 0, v[134:135]
	s_add_i32 m0, s4, 0x2000
	s_nop 0
	global_load_lds_dwordx4 v134, s[0:1]
	s_waitcnt vmcnt(6)
	s_barrier
	s_setprio 1
	v_mfma_f32_16x16x32_bf16 v[52:55], v[214:217], v[174:177], v[52:55]
	v_mfma_f32_16x16x32_bf16 v[48:51], v[222:225], v[174:177], v[48:51]
	v_mfma_f32_16x16x32_bf16 v[36:39], v[214:217], v[188:191], v[36:39]
	v_mfma_f32_16x16x32_bf16 v[32:35], v[222:225], v[188:191], v[32:35]
	v_mfma_f32_16x16x32_bf16 v[20:23], v[214:217], v[198:201], v[20:23]
	v_mfma_f32_16x16x32_bf16 v[16:19], v[222:225], v[198:201], v[16:19]
	v_mfma_f32_16x16x32_bf16 v[4:7], v[214:217], v[206:209], v[4:7]
	v_mfma_f32_16x16x32_bf16 v[0:3], v[222:225], v[206:209], v[0:3]
	v_mfma_f32_16x16x32_bf16 v[52:55], v[218:221], v[178:181], v[52:55]
	v_mfma_f32_16x16x32_bf16 v[48:51], v[226:229], v[178:181], v[48:51]
	v_mfma_f32_16x16x32_bf16 v[36:39], v[218:221], v[194:197], v[36:39]
	v_mfma_f32_16x16x32_bf16 v[32:35], v[226:229], v[194:197], v[32:35]
	v_mfma_f32_16x16x32_bf16 v[20:23], v[218:221], v[202:205], v[20:23]
	v_mfma_f32_16x16x32_bf16 v[16:19], v[226:229], v[202:205], v[16:19]
	v_mfma_f32_16x16x32_bf16 v[4:7], v[218:221], v[210:213], v[4:7]
	v_mfma_f32_16x16x32_bf16 v[0:3], v[226:229], v[210:213], v[0:3]
	s_setprio 0
	s_add_i32 s35, s35, 2
	s_add_u32 s8, s8, 0x100
	s_addc_u32 s9, s9, 0
	s_add_u32 s28, s28, 0x100
	s_addc_u32 s34, s34, 0
	s_cmp_gt_u32 s35, 29
	s_barrier
	s_cbranch_scc0 .LBB0_527
	s_branch .Lpeel_done_527
.LBB0_527:
	ds_read_b128 v[146:149], v164
	ds_read_b128 v[150:153], v164 offset:1024
	ds_read_b128 v[154:157], v164 offset:2048
	ds_read_b128 v[170:173], v164 offset:3072
	s_add_u32 s0, s8, 0xfff80080
	s_addc_u32 s1, s9, -1
	s_cmp_eq_u32 s35, 28
	s_cselect_b32 s13, s14, s1
	s_cselect_b32 s12, s15, s0
	s_cselect_b32 s11, s16, s34
	s_cselect_b32 s10, s17, s28
	s_add_i32 m0, s59, 0xc000
	ds_read_b128 v[174:177], v165
	ds_read_b128 v[178:181], v165 offset:1024
	ds_read_b128 v[188:191], v165 offset:2048
	ds_read_b128 v[194:197], v165 offset:3072
	ds_read_b128 v[198:201], v165 offset:4096
	ds_read_b128 v[202:205], v165 offset:5120
	ds_read_b128 v[206:209], v165 offset:6144
	global_load_lds_dwordx4 v138, s[8:9]
	s_add_i32 m0, s59, 0xe000
	ds_read_b128 v[210:213], v165 offset:7168
	global_load_lds_dwordx4 v140, s[8:9]
	s_waitcnt lgkmcnt(8)
	s_barrier
	s_waitcnt lgkmcnt(0)
	s_setprio 1
	v_mfma_f32_16x16x32_bf16 v[124:127], v[146:149], v[174:177], v[124:127]
	v_mfma_f32_16x16x32_bf16 v[120:123], v[154:157], v[174:177], v[120:123]
	v_mfma_f32_16x16x32_bf16 v[108:111], v[146:149], v[188:191], v[108:111]
	v_mfma_f32_16x16x32_bf16 v[104:107], v[154:157], v[188:191], v[104:107]
	v_mfma_f32_16x16x32_bf16 v[92:95], v[146:149], v[198:201], v[92:95]
	v_mfma_f32_16x16x32_bf16 v[88:91], v[154:157], v[198:201], v[88:91]
	v_mfma_f32_16x16x32_bf16 v[76:79], v[146:149], v[206:209], v[76:79]
	v_mfma_f32_16x16x32_bf16 v[72:75], v[154:157], v[206:209], v[72:75]
	v_mfma_f32_16x16x32_bf16 v[124:127], v[150:153], v[178:181], v[124:127]
	v_mfma_f32_16x16x32_bf16 v[120:123], v[170:173], v[178:181], v[120:123]
	v_mfma_f32_16x16x32_bf16 v[108:111], v[150:153], v[194:197], v[108:111]
	v_mfma_f32_16x16x32_bf16 v[104:107], v[170:173], v[194:197], v[104:107]
	v_mfma_f32_16x16x32_bf16 v[92:95], v[150:153], v[202:205], v[92:95]
	v_mfma_f32_16x16x32_bf16 v[88:91], v[170:173], v[202:205], v[88:91]
	v_mfma_f32_16x16x32_bf16 v[76:79], v[150:153], v[210:213], v[76:79]
	v_mfma_f32_16x16x32_bf16 v[72:75], v[170:173], v[210:213], v[72:75]
	s_setprio 0
	s_barrier
	s_add_i32 s0, s47, s74
	s_mov_b32 m0, s0
	ds_read_b128 v[214:217], v166
	ds_read_b128 v[218:221], v166 offset:1024
	ds_read_b128 v[222:225], v166 offset:2048
	global_load_lds_dwordx4 v130, s[10:11]
	s_add_i32 m0, s0, 0x2000
	ds_read_b128 v[226:229], v166 offset:3072
	global_load_lds_dwordx4 v134, s[10:11]
	s_barrier
; #define PG8_STAGE(bufoff, gbase, voff) do { _Pragma("unroll") for (int _i = 0; _i < 2; ++_i) \
;         __builtin_amdgcn_global_load_lds((const unsigned*)((const char*)(gbase) + (voff)[_i]), (LAS unsigned*)(lds + (bufoff) + ldsw + _i * 8192), 16, 0, 0); } while (0)
; #define PG8_LDA(dst, b, h) do { _Pragma("unroll") for (int m = 0; m < 4; ++m) _Pragma("unroll") for (int k = 0; k < 2; ++k) dst[m][k] = *(const LAS bf16x8*)(lds + PG8_SA(b, h) + aoff + m * 2048 + k * 1024); } while (0)
; #define PG8_LDB(dst, b, h) do { _Pragma("unroll") for (int n = 0; n < 2; ++n) _Pragma("unroll") for (int k = 0; k < 2; ++k) dst[n][k] = *(const LAS bf16x8*)(lds + PG8_SB(b, h) + boff + n * 2048 + k * 1024); } while (0)
; #define PG8_MMA(ai, bj, At, Bt) do { __builtin_amdgcn_s_setprio(1); _Pragma("unroll") for (int m = 0; m < 4; ++m) _Pragma("unroll") for (int n = 0; n < 2; ++n) _Pragma("unroll") for (int k = 0; k < 2; ++k) \
;         acc[ai][bj][m][n] = __builtin_amdgcn_mfma_f32_16x16x32_bf16(Bt[n][k], At[m][k], acc[ai][bj][m][n], 0, 0, 0); __builtin_amdgcn_s_setprio(0); } while (0)
; #define PG8_WAIT_V(n) asm volatile("s_waitcnt vmcnt(" #n ")" ::: "memory")
; #define PG8_WAIT_L(n) asm volatile("s_waitcnt lgkmcnt(" #n ")" ::: "memory")
; #define PG8_BAR __builtin_amdgcn_s_barrier()
; #define PG8_SCHED __builtin_amdgcn_sched_barrier(0)
; template <class Epi, class Sched>
; DI void gemm_phase(LAS unsigned char* lds, const Gemm g, const Sched& S, const Epi& E) {
;     ...
;             PG8_BAR; PG8_WAIT_L(0); PG8_MMA(0, 1, At, B1); PG8_BAR;
;             PG8_LDA(At, 0, 1); PG8_STAGE(PG8_SA(0, 0), a2, voffA);
;             PG8_BAR; PG8_WAIT_L(0); PG8_MMA(1, 0, At, B0); PG8_BAR; PG8_SCHED;
;             PG8_STAGE(PG8_SB(0, 1), b2 + hstep, voffB);
;             PG8_WAIT_V(6); PG8_BAR; PG8_MMA(1, 1, At, B1); PG8_BAR;
;             PG8_LDB(B0, 1, 0); PG8_SCHED; PG8_LDA(At, 1, 0); PG8_STAGE(PG8_SA(0, 1), a2 + hstep, voffA);
;             PG8_WAIT_L(8); PG8_BAR; PG8_WAIT_L(0); PG8_MMA(0, 0, At, B0); PG8_BAR; PG8_SCHED;
	s_waitcnt lgkmcnt(0)
	s_setprio 1
	v_mfma_f32_16x16x32_bf16 v[116:119], v[214:217], v[174:177], v[116:119]
	v_mfma_f32_16x16x32_bf16 v[112:115], v[222:225], v[174:177], v[112:115]
	v_mfma_f32_16x16x32_bf16 v[100:103], v[214:217], v[188:191], v[100:103]
	v_mfma_f32_16x16x32_bf16 v[96:99], v[222:225], v[188:191], v[96:99]
	v_mfma_f32_16x16x32_bf16 v[84:87], v[214:217], v[198:201], v[84:87]
	v_mfma_f32_16x16x32_bf16 v[80:83], v[222:225], v[198:201], v[80:83]
	v_mfma_f32_16x16x32_bf16 v[68:71], v[214:217], v[206:209], v[68:71]
	v_mfma_f32_16x16x32_bf16 v[64:67], v[222:225], v[206:209], v[64:67]
	v_mfma_f32_16x16x32_bf16 v[116:119], v[218:221], v[178:181], v[116:119]
	v_mfma_f32_16x16x32_bf16 v[112:115], v[226:229], v[178:181], v[112:115]
	v_mfma_f32_16x16x32_bf16 v[100:103], v[218:221], v[194:197], v[100:103]
	v_mfma_f32_16x16x32_bf16 v[96:99], v[226:229], v[194:197], v[96:99]
	v_mfma_f32_16x16x32_bf16 v[84:87], v[218:221], v[202:205], v[84:87]
	v_mfma_f32_16x16x32_bf16 v[80:83], v[226:229], v[202:205], v[80:83]
	v_mfma_f32_16x16x32_bf16 v[68:71], v[218:221], v[210:213], v[68:71]
	v_mfma_f32_16x16x32_bf16 v[64:67], v[226:229], v[210:213], v[64:67]
	s_setprio 0
	s_mov_b32 m0, s59
	s_barrier
	ds_read_b128 v[174:177], v165 offset:16384
	ds_read_b128 v[178:181], v165 offset:17408
	ds_read_b128 v[188:191], v165 offset:18432
	ds_read_b128 v[194:197], v165 offset:19456
	ds_read_b128 v[198:201], v165 offset:20480
	ds_read_b128 v[202:205], v165 offset:21504
	ds_read_b128 v[206:209], v165 offset:22528
	global_load_lds_dwordx4 v128, s[12:13]
	s_mov_b32 m0, s75
	ds_read_b128 v[210:213], v165 offset:23552
	global_load_lds_dwordx4 v132, s[12:13]
	s_barrier
	s_waitcnt lgkmcnt(0)
	s_setprio 1
	v_mfma_f32_16x16x32_bf16 v[60:63], v[146:149], v[174:177], v[60:63]
	v_mfma_f32_16x16x32_bf16 v[56:59], v[154:157], v[174:177], v[56:59]
	v_mfma_f32_16x16x32_bf16 v[44:47], v[146:149], v[188:191], v[44:47]
	v_mfma_f32_16x16x32_bf16 v[40:43], v[154:157], v[188:191], v[40:43]
	v_mfma_f32_16x16x32_bf16 v[28:31], v[146:149], v[198:201], v[28:31]
	v_mfma_f32_16x16x32_bf16 v[24:27], v[154:157], v[198:201], v[24:27]
	v_mfma_f32_16x16x32_bf16 v[12:15], v[146:149], v[206:209], v[12:15]
	v_mfma_f32_16x16x32_bf16 v[8:11], v[154:157], v[206:209], v[8:11]
	v_mfma_f32_16x16x32_bf16 v[60:63], v[150:153], v[178:181], v[60:63]
	v_mfma_f32_16x16x32_bf16 v[56:59], v[170:173], v[178:181], v[56:59]
	v_mfma_f32_16x16x32_bf16 v[44:47], v[150:153], v[194:197], v[44:47]
	v_mfma_f32_16x16x32_bf16 v[40:43], v[170:173], v[194:197], v[40:43]
	v_mfma_f32_16x16x32_bf16 v[28:31], v[150:153], v[202:205], v[28:31]
	v_mfma_f32_16x16x32_bf16 v[24:27], v[170:173], v[202:205], v[24:27]
	v_mfma_f32_16x16x32_bf16 v[12:15], v[150:153], v[210:213], v[12:15]
	v_mfma_f32_16x16x32_bf16 v[8:11], v[170:173], v[210:213], v[8:11]
	s_setprio 0
	s_barrier
	s_add_u32 s0, s10, 0x80000
	s_addc_u32 s1, s11, 0
	s_add_i32 s4, s87, s74
	s_mov_b32 m0, s4
	s_nop 0
	global_load_lds_dwordx4 v130, s[0:1]
	s_add_i32 m0, s4, 0x2000
	s_nop 0
	global_load_lds_dwordx4 v134, s[0:1]
	s_waitcnt vmcnt(6)
	s_barrier
	s_setprio 1
	v_mfma_f32_16x16x32_bf16 v[52:55], v[214:217], v[174:177], v[52:55]
	v_mfma_f32_16x16x32_bf16 v[48:51], v[222:225], v[174:177], v[48:51]
	v_mfma_f32_16x16x32_bf16 v[36:39], v[214:217], v[188:191], v[36:39]
	v_mfma_f32_16x16x32_bf16 v[32:35], v[222:225], v[188:191], v[32:35]
	v_mfma_f32_16x16x32_bf16 v[20:23], v[214:217], v[198:201], v[20:23]
	v_mfma_f32_16x16x32_bf16 v[16:19], v[222:225], v[198:201], v[16:19]
	v_mfma_f32_16x16x32_bf16 v[4:7], v[214:217], v[206:209], v[4:7]
	v_mfma_f32_16x16x32_bf16 v[0:3], v[222:225], v[206:209], v[0:3]
	v_mfma_f32_16x16x32_bf16 v[52:55], v[218:221], v[178:181], v[52:55]
	v_mfma_f32_16x16x32_bf16 v[48:51], v[226:229], v[178:181], v[48:51]
	v_mfma_f32_16x16x32_bf16 v[36:39], v[218:221], v[194:197], v[36:39]
	v_mfma_f32_16x16x32_bf16 v[32:35], v[226:229], v[194:197], v[32:35]
	v_mfma_f32_16x16x32_bf16 v[20:23], v[218:221], v[202:205], v[20:23]
	v_mfma_f32_16x16x32_bf16 v[16:19], v[226:229], v[202:205], v[16:19]
	v_mfma_f32_16x16x32_bf16 v[4:7], v[218:221], v[210:213], v[4:7]
	v_mfma_f32_16x16x32_bf16 v[0:3], v[226:229], v[210:213], v[0:3]
	s_setprio 0
	s_add_i32 s4, 0, 0x18000
	s_barrier
	ds_read_b128 v[146:149], v158
	ds_read_b128 v[150:153], v158 offset:1024
	ds_read_b128 v[154:157], v158 offset:2048
	ds_read_b128 v[170:173], v158 offset:3072
	s_add_u32 s0, s12, 0x80000
	s_addc_u32 s1, s13, 0
	s_mov_b32 m0, s76
	ds_read_b128 v[174:177], v165 offset:32768
	ds_read_b128 v[178:181], v165 offset:33792
	ds_read_b128 v[188:191], v165 offset:34816
	ds_read_b128 v[194:197], v165 offset:35840
	ds_read_b128 v[198:201], v165 offset:36864
	ds_read_b128 v[202:205], v165 offset:37888
	ds_read_b128 v[206:209], v165 offset:38912
	global_load_lds_dwordx4 v128, s[0:1]
	s_mov_b32 m0, s77
	ds_read_b128 v[210:213], v165 offset:39936
	global_load_lds_dwordx4 v132, s[0:1]
	s_waitcnt lgkmcnt(8)
	s_barrier
; #define PG8_STAGE(bufoff, gbase, voff) do { _Pragma("unroll") for (int _i = 0; _i < 2; ++_i) \
;         __builtin_amdgcn_global_load_lds((const unsigned*)((const char*)(gbase) + (voff)[_i]), (LAS unsigned*)(lds + (bufoff) + ldsw + _i * 8192), 16, 0, 0); } while (0)
; #define PG8_LDA(dst, b, h) do { _Pragma("unroll") for (int m = 0; m < 4; ++m) _Pragma("unroll") for (int k = 0; k < 2; ++k) dst[m][k] = *(const LAS bf16x8*)(lds + PG8_SA(b, h) + aoff + m * 2048 + k * 1024); } while (0)
; #define PG8_LDB(dst, b, h) do { _Pragma("unroll") for (int n = 0; n < 2; ++n) _Pragma("unroll") for (int k = 0; k < 2; ++k) dst[n][k] = *(const LAS bf16x8*)(lds + PG8_SB(b, h) + boff + n * 2048 + k * 1024); } while (0)
; #define PG8_MMA(ai, bj, At, Bt) do { __builtin_amdgcn_s_setprio(1); _Pragma("unroll") for (int m = 0; m < 4; ++m) _Pragma("unroll") for (int n = 0; n < 2; ++n) _Pragma("unroll") for (int k = 0; k < 2; ++k) \
;         acc[ai][bj][m][n] = __builtin_amdgcn_mfma_f32_16x16x32_bf16(Bt[n][k], At[m][k], acc[ai][bj][m][n], 0, 0, 0); __builtin_amdgcn_s_setprio(0); } while (0)
; #define PG8_WAIT_V(n) asm volatile("s_waitcnt vmcnt(" #n ")" ::: "memory")
; #define PG8_WAIT_L(n) asm volatile("s_waitcnt lgkmcnt(" #n ")" ::: "memory")
; #define PG8_BAR __builtin_amdgcn_s_barrier()
; #define PG8_SCHED __builtin_amdgcn_sched_barrier(0)
; template <class Epi, class Sched>
; DI void gemm_phase(LAS unsigned char* lds, const Gemm g, const Sched& S, const Epi& E) {
;     ...
;             PG8_WAIT_L(8); PG8_BAR; PG8_WAIT_L(0); PG8_MMA(0, 0, At, B0); PG8_BAR; PG8_SCHED;
;             PG8_LDB(B1, 1, 1); PG8_STAGE(PG8_SB(1, 0), b3, voffB);
;             PG8_BAR; PG8_WAIT_L(0); PG8_MMA(0, 1, At, B1); PG8_BAR;
;             PG8_LDA(At, 1, 1); PG8_STAGE(PG8_SA(1, 0), a3, voffA);
;             PG8_BAR; PG8_WAIT_L(0); PG8_MMA(1, 0, At, B0); PG8_BAR; PG8_SCHED;
;             PG8_STAGE(PG8_SB(1, 1), b3 + hstep, voffB);
;             PG8_WAIT_V(6); PG8_BAR; PG8_MMA(1, 1, At, B1); PG8_BAR;
	s_waitcnt lgkmcnt(0)
	s_setprio 1
	v_mfma_f32_16x16x32_bf16 v[124:127], v[146:149], v[174:177], v[124:127]
	v_mfma_f32_16x16x32_bf16 v[120:123], v[154:157], v[174:177], v[120:123]
	v_mfma_f32_16x16x32_bf16 v[108:111], v[146:149], v[188:191], v[108:111]
	v_mfma_f32_16x16x32_bf16 v[104:107], v[154:157], v[188:191], v[104:107]
	v_mfma_f32_16x16x32_bf16 v[92:95], v[146:149], v[198:201], v[92:95]
	v_mfma_f32_16x16x32_bf16 v[88:91], v[154:157], v[198:201], v[88:91]
	v_mfma_f32_16x16x32_bf16 v[76:79], v[146:149], v[206:209], v[76:79]
	v_mfma_f32_16x16x32_bf16 v[72:75], v[154:157], v[206:209], v[72:75]
	v_mfma_f32_16x16x32_bf16 v[124:127], v[150:153], v[178:181], v[124:127]
	v_mfma_f32_16x16x32_bf16 v[120:123], v[170:173], v[178:181], v[120:123]
	v_mfma_f32_16x16x32_bf16 v[108:111], v[150:153], v[194:197], v[108:111]
	v_mfma_f32_16x16x32_bf16 v[104:107], v[170:173], v[194:197], v[104:107]
	v_mfma_f32_16x16x32_bf16 v[92:95], v[150:153], v[202:205], v[92:95]
	v_mfma_f32_16x16x32_bf16 v[88:91], v[170:173], v[202:205], v[88:91]
	v_mfma_f32_16x16x32_bf16 v[76:79], v[150:153], v[210:213], v[76:79]
	v_mfma_f32_16x16x32_bf16 v[72:75], v[170:173], v[210:213], v[72:75]
	s_setprio 0
	s_barrier
	s_add_i32 s5, 0, 0x1c000
	s_add_i32 s0, s4, s74
	s_add_i32 m0, s0, 0xffffff80
	ds_read_b128 v[214:217], v159
	ds_read_b128 v[218:221], v159 offset:1024
	ds_read_b128 v[222:225], v159 offset:2048
	global_load_lds_dwordx4 v130, s[10:11] offset:128
	s_add_i32 m0, s0, 0x1f80
	ds_read_b128 v[226:229], v159 offset:3072
	global_load_lds_dwordx4 v134, s[10:11] offset:128
	s_barrier
	s_waitcnt lgkmcnt(0)
	s_setprio 1
	v_mfma_f32_16x16x32_bf16 v[116:119], v[214:217], v[174:177], v[116:119]
	v_mfma_f32_16x16x32_bf16 v[112:115], v[222:225], v[174:177], v[112:115]
	v_mfma_f32_16x16x32_bf16 v[100:103], v[214:217], v[188:191], v[100:103]
	v_mfma_f32_16x16x32_bf16 v[96:99], v[222:225], v[188:191], v[96:99]
	v_mfma_f32_16x16x32_bf16 v[84:87], v[214:217], v[198:201], v[84:87]
	v_mfma_f32_16x16x32_bf16 v[80:83], v[222:225], v[198:201], v[80:83]
	v_mfma_f32_16x16x32_bf16 v[68:71], v[214:217], v[206:209], v[68:71]
	v_mfma_f32_16x16x32_bf16 v[64:67], v[222:225], v[206:209], v[64:67]
	v_mfma_f32_16x16x32_bf16 v[116:119], v[218:221], v[178:181], v[116:119]
	v_mfma_f32_16x16x32_bf16 v[112:115], v[226:229], v[178:181], v[112:115]
	v_mfma_f32_16x16x32_bf16 v[100:103], v[218:221], v[194:197], v[100:103]
	v_mfma_f32_16x16x32_bf16 v[96:99], v[226:229], v[194:197], v[96:99]
	v_mfma_f32_16x16x32_bf16 v[84:87], v[218:221], v[202:205], v[84:87]
	v_mfma_f32_16x16x32_bf16 v[80:83], v[226:229], v[202:205], v[80:83]
	v_mfma_f32_16x16x32_bf16 v[68:71], v[218:221], v[210:213], v[68:71]
	v_mfma_f32_16x16x32_bf16 v[64:67], v[226:229], v[210:213], v[64:67]
	s_setprio 0
	s_add_i32 m0, s97, 0xffffff80
	s_barrier
	ds_read_b128 v[174:177], v165 offset:49152
	ds_read_b128 v[178:181], v165 offset:50176
	ds_read_b128 v[188:191], v165 offset:51200
	ds_read_b128 v[194:197], v165 offset:52224
	ds_read_b128 v[198:201], v165 offset:53248
	ds_read_b128 v[202:205], v165 offset:54272
	ds_read_b128 v[206:209], v165 offset:55296
	global_load_lds_dwordx4 v128, s[12:13] offset:128
	s_add_i32 m0, s84, 0xffffff80
	ds_read_b128 v[210:213], v165 offset:56320
	global_load_lds_dwordx4 v132, s[12:13] offset:128
	s_barrier
	s_waitcnt lgkmcnt(0)
	s_setprio 1
	v_mfma_f32_16x16x32_bf16 v[60:63], v[146:149], v[174:177], v[60:63]
	v_mfma_f32_16x16x32_bf16 v[56:59], v[154:157], v[174:177], v[56:59]
	v_mfma_f32_16x16x32_bf16 v[44:47], v[146:149], v[188:191], v[44:47]
	v_mfma_f32_16x16x32_bf16 v[40:43], v[154:157], v[188:191], v[40:43]
	v_mfma_f32_16x16x32_bf16 v[28:31], v[146:149], v[198:201], v[28:31]
	v_mfma_f32_16x16x32_bf16 v[24:27], v[154:157], v[198:201], v[24:27]
	v_mfma_f32_16x16x32_bf16 v[12:15], v[146:149], v[206:209], v[12:15]
	v_mfma_f32_16x16x32_bf16 v[8:11], v[154:157], v[206:209], v[8:11]
	v_mfma_f32_16x16x32_bf16 v[60:63], v[150:153], v[178:181], v[60:63]
	v_mfma_f32_16x16x32_bf16 v[56:59], v[170:173], v[178:181], v[56:59]
	v_mfma_f32_16x16x32_bf16 v[44:47], v[150:153], v[194:197], v[44:47]
	v_mfma_f32_16x16x32_bf16 v[40:43], v[170:173], v[194:197], v[40:43]
	v_mfma_f32_16x16x32_bf16 v[28:31], v[150:153], v[202:205], v[28:31]
	v_mfma_f32_16x16x32_bf16 v[24:27], v[170:173], v[202:205], v[24:27]
	v_mfma_f32_16x16x32_bf16 v[12:15], v[150:153], v[210:213], v[12:15]
	v_mfma_f32_16x16x32_bf16 v[8:11], v[170:173], v[210:213], v[8:11]
	s_setprio 0
	s_barrier
	s_add_u32 s0, s10, 0x80080
	s_addc_u32 s1, s11, 0
	s_add_i32 s4, s5, s74
	s_mov_b32 m0, s4
	s_nop 0
	global_load_lds_dwordx4 v130, s[0:1]
	v_lshl_add_u64 v[146:147], s[0:1], 0, v[134:135]
	s_add_i32 m0, s4, 0x2000
	s_nop 0
	global_load_lds_dwordx4 v134, s[0:1]
	s_waitcnt vmcnt(6)
	s_barrier
	s_setprio 1
	v_mfma_f32_16x16x32_bf16 v[52:55], v[214:217], v[174:177], v[52:55]
	v_mfma_f32_16x16x32_bf16 v[48:51], v[222:225], v[174:177], v[48:51]
	v_mfma_f32_16x16x32_bf16 v[36:39], v[214:217], v[188:191], v[36:39]
	v_mfma_f32_16x16x32_bf16 v[32:35], v[222:225], v[188:191], v[32:35]
	v_mfma_f32_16x16x32_bf16 v[20:23], v[214:217], v[198:201], v[20:23]
	v_mfma_f32_16x16x32_bf16 v[16:19], v[222:225], v[198:201], v[16:19]
	v_mfma_f32_16x16x32_bf16 v[4:7], v[214:217], v[206:209], v[4:7]
	v_mfma_f32_16x16x32_bf16 v[0:3], v[222:225], v[206:209], v[0:3]
	v_mfma_f32_16x16x32_bf16 v[52:55], v[218:221], v[178:181], v[52:55]
	v_mfma_f32_16x16x32_bf16 v[48:51], v[226:229], v[178:181], v[48:51]
	v_mfma_f32_16x16x32_bf16 v[36:39], v[218:221], v[194:197], v[36:39]
	v_mfma_f32_16x16x32_bf16 v[32:35], v[226:229], v[194:197], v[32:35]
	v_mfma_f32_16x16x32_bf16 v[20:23], v[218:221], v[202:205], v[20:23]
	v_mfma_f32_16x16x32_bf16 v[16:19], v[226:229], v[202:205], v[16:19]
	v_mfma_f32_16x16x32_bf16 v[4:7], v[218:221], v[210:213], v[4:7]
	v_mfma_f32_16x16x32_bf16 v[0:3], v[226:229], v[210:213], v[0:3]
	s_setprio 0
	s_add_i32 s35, s35, 2
	s_add_u32 s8, s8, 0x100
	s_addc_u32 s9, s9, 0
	s_add_u32 s28, s28, 0x100
	s_addc_u32 s34, s34, 0
	s_cmp_gt_u32 s35, 29
	s_barrier
	s_cbranch_scc0 .LBB0_527

;     DI size_t aoff(const Unit& u, size_t tstep) const { return (size_t)u.pm * tstep; }
;     DI size_t boff(const Unit& u, size_t tstep) const { return (size_t)u.pn * tstep; }
;     DI bool next(int i, Unit& u) const { const long L = (long)i * G + c; if (L >= np) return false; u.pm = pmv; u.pn = (int)(L % nN); u.ks = (int)(L / nN); return true; }
;     DI size_t aoff(const Unit& u, size_t) const { return (size_t)u.ks * kbytes; }
;     DI size_t boff(const Unit& u, size_t tstep) const { return (size_t)u.pn * tstep + (size_t)u.ks * kbytes; }
;     DI bool next(int i, Unit& u) const { Unit t; if (!S.next(i / 3, t)) return false; u.pm = t.pm; u.pn = t.pn; u.ks = i % 3; return true; }
;     DI size_t aoff(const Unit& u, size_t tstep) const { return (u.ks < 2 ? offU : offOA) + (size_t)u.pm * tstep; }
; #define PG8_LDA(dst, b, h) do { _Pragma("unroll") for (int m = 0; m < 4; ++m) _Pragma("unroll") for (int k = 0; k < 2; ++k) dst[m][k] = *(const LAS bf16x8*)(lds + PG8_SA(b, h) + aoff + m * 2048 + k * 1024); } while (0)
; template <class Epi, class Sched>
; DI void gemm_phase(LAS unsigned char* lds, const Gemm g, const Sched& S, const Epi& E) {
;     ...
;         const bool has_next = S.next(ui + 1, nxt);
;         const char* nA = has_next ? (const char*)g.A + S.aoff(nxt, tstep) : cA; const char* nB = has_next ? (const char*)g.Bt + S.boff(nxt, tstep) : cB;
;         for (int t = 0; t < nt; t += 2) {
;             if constexpr (Epi::HAS_MID) { if (t == E.mid_t(nt)) { int fr3 = fr, fq3 = fq; asm volatile("" : "+v"(fr3), "+v"(fq3)); E.mid(acc, cur, wr, wc, fr3, fq3); } }
;             const bool last = (t == nt - 2);
;             const char* a1 = cA + (size_t)(t + 1) * kstep;
;             const char* a2 = last ? nA : cA + (size_t)(t + 2) * kstep; const char* b2 = last ? nB : cB + (size_t)(t + 2) * kstep;
;             const char* a3 = a2 + kstep; const char* b3 = b2 + kstep;
;             PG8_LDB(B0, 0, 0); PG8_SCHED; PG8_LDA(At, 0, 0); PG8_STAGE(PG8_SA(1, 1), a1 + hstep, voffA);
;             PG8_WAIT_L(8); PG8_BAR; PG8_WAIT_L(0); PG8_MMA(0, 0, At, B0); PG8_BAR; PG8_SCHED;
;             PG8_LDB(B1, 0, 1); PG8_STAGE(PG8_SB(0, 0), b2, voffB);
;             PG8_BAR; PG8_WAIT_L(0); PG8_MMA(0, 1, At, B1); PG8_BAR;
;             PG8_LDA(At, 0, 1); PG8_STAGE(PG8_SA(0, 0), a2, voffA);
;             PG8_BAR; PG8_WAIT_L(0); PG8_MMA(1, 0, At, B0); PG8_BAR; PG8_SCHED;
.LBB0_937:
	s_add_u32 s8, s38, 0x30080
	s_addc_u32 s9, s39, 0
	s_add_u32 s35, s36, 0x100
	v_mov_b32_e32 v0, 0
	s_addc_u32 s40, s37, 0
	s_mov_b32 s41, -2
	ds_read_b128 v[144:147], v165
	ds_read_b128 v[168:171], v165 offset:1024
	ds_read_b128 v[172:175], v165 offset:2048
	ds_read_b128 v[176:179], v165 offset:3072
	s_add_u32 s0, s8, 0xfffd0080
	s_addc_u32 s1, s9, -1
	s_cmp_eq_u32 s41, 8
	s_cselect_b32 s39, s31, s1
	s_cselect_b32 s38, s30, s0
	s_cselect_b32 s37, s11, s40
	s_cselect_b32 s36, s10, s35
	s_add_i32 m0, s51, 0xc000
	ds_read_b128 v[180:183], v166
	ds_read_b128 v[188:191], v166 offset:1024
	ds_read_b128 v[194:197], v166 offset:2048
	ds_read_b128 v[198:201], v166 offset:3072
	ds_read_b128 v[202:205], v166 offset:4096
	ds_read_b128 v[206:209], v166 offset:5120
	ds_read_b128 v[210:213], v166 offset:6144
	global_load_lds_dwordx4 v136, s[8:9]
	s_add_i32 m0, s51, 0xe000
	ds_read_b128 v[214:217], v166 offset:7168
	global_load_lds_dwordx4 v138, s[8:9]
	s_waitcnt lgkmcnt(8)
	s_barrier
	s_waitcnt lgkmcnt(0)
	s_setprio 1
	v_mfma_f32_16x16x32_bf16 v[124:127], v[144:147], v[180:183], 0
	v_mfma_f32_16x16x32_bf16 v[120:123], v[172:175], v[180:183], 0
	v_mfma_f32_16x16x32_bf16 v[108:111], v[144:147], v[194:197], 0
	v_mfma_f32_16x16x32_bf16 v[104:107], v[172:175], v[194:197], 0
	v_mfma_f32_16x16x32_bf16 v[92:95], v[144:147], v[202:205], 0
	v_mfma_f32_16x16x32_bf16 v[88:91], v[172:175], v[202:205], 0
	v_mfma_f32_16x16x32_bf16 v[76:79], v[144:147], v[210:213], 0
	v_mfma_f32_16x16x32_bf16 v[72:75], v[172:175], v[210:213], 0
	v_mfma_f32_16x16x32_bf16 v[124:127], v[168:171], v[188:191], v[124:127]
	v_mfma_f32_16x16x32_bf16 v[120:123], v[176:179], v[188:191], v[120:123]
	v_mfma_f32_16x16x32_bf16 v[108:111], v[168:171], v[198:201], v[108:111]
	v_mfma_f32_16x16x32_bf16 v[104:107], v[176:179], v[198:201], v[104:107]
	v_mfma_f32_16x16x32_bf16 v[92:95], v[168:171], v[206:209], v[92:95]
	v_mfma_f32_16x16x32_bf16 v[88:91], v[176:179], v[206:209], v[88:91]
	v_mfma_f32_16x16x32_bf16 v[76:79], v[168:171], v[214:217], v[76:79]
	v_mfma_f32_16x16x32_bf16 v[72:75], v[176:179], v[214:217], v[72:75]
	s_setprio 0
	s_barrier
	s_add_i32 s0, s61, s50
	s_mov_b32 m0, s0
	ds_read_b128 v[218:221], v167
	ds_read_b128 v[222:225], v167 offset:1024
	ds_read_b128 v[226:229], v167 offset:2048
	global_load_lds_dwordx4 v130, s[36:37]
	s_add_i32 m0, s0, 0x2000
	ds_read_b128 v[230:233], v167 offset:3072
	global_load_lds_dwordx4 v134, s[36:37]
	s_barrier
	s_waitcnt lgkmcnt(0)
	s_setprio 1
	v_mfma_f32_16x16x32_bf16 v[116:119], v[218:221], v[180:183], 0
	v_mfma_f32_16x16x32_bf16 v[112:115], v[226:229], v[180:183], 0
	v_mfma_f32_16x16x32_bf16 v[100:103], v[218:221], v[194:197], 0
	v_mfma_f32_16x16x32_bf16 v[96:99], v[226:229], v[194:197], 0
	v_mfma_f32_16x16x32_bf16 v[84:87], v[218:221], v[202:205], 0
	v_mfma_f32_16x16x32_bf16 v[80:83], v[226:229], v[202:205], 0
	v_mfma_f32_16x16x32_bf16 v[68:71], v[218:221], v[210:213], 0
	v_mfma_f32_16x16x32_bf16 v[64:67], v[226:229], v[210:213], 0
	v_mfma_f32_16x16x32_bf16 v[116:119], v[222:225], v[188:191], v[116:119]
	v_mfma_f32_16x16x32_bf16 v[112:115], v[230:233], v[188:191], v[112:115]
	v_mfma_f32_16x16x32_bf16 v[100:103], v[222:225], v[198:201], v[100:103]
	v_mfma_f32_16x16x32_bf16 v[96:99], v[230:233], v[198:201], v[96:99]
	v_mfma_f32_16x16x32_bf16 v[84:87], v[222:225], v[206:209], v[84:87]
	v_mfma_f32_16x16x32_bf16 v[80:83], v[230:233], v[206:209], v[80:83]
	v_mfma_f32_16x16x32_bf16 v[68:71], v[222:225], v[214:217], v[68:71]
	v_mfma_f32_16x16x32_bf16 v[64:67], v[230:233], v[214:217], v[64:67]
	s_setprio 0
	s_mov_b32 m0, s51
	s_barrier
	ds_read_b128 v[180:183], v166 offset:16384
	ds_read_b128 v[188:191], v166 offset:17408
	ds_read_b128 v[194:197], v166 offset:18432
	ds_read_b128 v[198:201], v166 offset:19456
	ds_read_b128 v[202:205], v166 offset:20480
	ds_read_b128 v[206:209], v166 offset:21504
	ds_read_b128 v[210:213], v166 offset:22528
	global_load_lds_dwordx4 v128, s[38:39]
	s_mov_b32 m0, s52
	ds_read_b128 v[214:217], v166 offset:23552
	global_load_lds_dwordx4 v132, s[38:39]
	s_barrier
	s_waitcnt lgkmcnt(0)
	s_setprio 1
	v_mfma_f32_16x16x32_bf16 v[60:63], v[144:147], v[180:183], 0
	v_mfma_f32_16x16x32_bf16 v[56:59], v[172:175], v[180:183], 0
	v_mfma_f32_16x16x32_bf16 v[44:47], v[144:147], v[194:197], 0
	v_mfma_f32_16x16x32_bf16 v[40:43], v[172:175], v[194:197], 0
	v_mfma_f32_16x16x32_bf16 v[28:31], v[144:147], v[202:205], 0
	v_mfma_f32_16x16x32_bf16 v[24:27], v[172:175], v[202:205], 0
	v_mfma_f32_16x16x32_bf16 v[12:15], v[144:147], v[210:213], 0
	v_mfma_f32_16x16x32_bf16 v[8:11], v[172:175], v[210:213], 0
	v_mfma_f32_16x16x32_bf16 v[60:63], v[168:171], v[188:191], v[60:63]
	v_mfma_f32_16x16x32_bf16 v[56:59], v[176:179], v[188:191], v[56:59]
	v_mfma_f32_16x16x32_bf16 v[44:47], v[168:171], v[198:201], v[44:47]
	v_mfma_f32_16x16x32_bf16 v[40:43], v[176:179], v[198:201], v[40:43]
	v_mfma_f32_16x16x32_bf16 v[28:31], v[168:171], v[206:209], v[28:31]
	v_mfma_f32_16x16x32_bf16 v[24:27], v[176:179], v[206:209], v[24:27]
	v_mfma_f32_16x16x32_bf16 v[12:15], v[168:171], v[214:217], v[12:15]
	v_mfma_f32_16x16x32_bf16 v[8:11], v[176:179], v[214:217], v[8:11]
	s_setprio 0
	s_barrier
	s_add_u32 s0, s36, 0x30000
	s_addc_u32 s1, s37, 0
	s_add_i32 s4, s62, s50
	s_mov_b32 m0, s4
	s_nop 0
	global_load_lds_dwordx4 v130, s[0:1]
	s_add_i32 m0, s4, 0x2000
	s_nop 0
	global_load_lds_dwordx4 v134, s[0:1]
	s_waitcnt vmcnt(6)
	s_barrier
; #define PG8_STAGE(bufoff, gbase, voff) do { _Pragma("unroll") for (int _i = 0; _i < 2; ++_i) \
;         __builtin_amdgcn_global_load_lds((const unsigned*)((const char*)(gbase) + (voff)[_i]), (LAS unsigned*)(lds + (bufoff) + ldsw + _i * 8192), 16, 0, 0); } while (0)
; #define PG8_LDA(dst, b, h) do { _Pragma("unroll") for (int m = 0; m < 4; ++m) _Pragma("unroll") for (int k = 0; k < 2; ++k) dst[m][k] = *(const LAS bf16x8*)(lds + PG8_SA(b, h) + aoff + m * 2048 + k * 1024); } while (0)
; #define PG8_LDB(dst, b, h) do { _Pragma("unroll") for (int n = 0; n < 2; ++n) _Pragma("unroll") for (int k = 0; k < 2; ++k) dst[n][k] = *(const LAS bf16x8*)(lds + PG8_SB(b, h) + boff + n * 2048 + k * 1024); } while (0)
; #define PG8_MMA(ai, bj, At, Bt) do { __builtin_amdgcn_s_setprio(1); _Pragma("unroll") for (int m = 0; m < 4; ++m) _Pragma("unroll") for (int n = 0; n < 2; ++n) _Pragma("unroll") for (int k = 0; k < 2; ++k) \
;         acc[ai][bj][m][n] = __builtin_amdgcn_mfma_f32_16x16x32_bf16(Bt[n][k], At[m][k], acc[ai][bj][m][n], 0, 0, 0); __builtin_amdgcn_s_setprio(0); } while (0)
; #define PG8_WAIT_V(n) asm volatile("s_waitcnt vmcnt(" #n ")" ::: "memory")
; #define PG8_WAIT_L(n) asm volatile("s_waitcnt lgkmcnt(" #n ")" ::: "memory")
; #define PG8_BAR __builtin_amdgcn_s_barrier()
; #define PG8_SCHED __builtin_amdgcn_sched_barrier(0)
; template <class Epi, class Sched>
; DI void gemm_phase(LAS unsigned char* lds, const Gemm g, const Sched& S, const Epi& E) {
;     ...
;             PG8_STAGE(PG8_SB(0, 1), b2 + hstep, voffB);
;             PG8_WAIT_V(6); PG8_BAR; PG8_MMA(1, 1, At, B1); PG8_BAR;
;             PG8_LDB(B0, 1, 0); PG8_SCHED; PG8_LDA(At, 1, 0); PG8_STAGE(PG8_SA(0, 1), a2 + hstep, voffA);
;             PG8_WAIT_L(8); PG8_BAR; PG8_WAIT_L(0); PG8_MMA(0, 0, At, B0); PG8_BAR; PG8_SCHED;
;             PG8_LDB(B1, 1, 1); PG8_STAGE(PG8_SB(1, 0), b3, voffB);
;             PG8_BAR; PG8_WAIT_L(0); PG8_MMA(0, 1, At, B1); PG8_BAR;
;             PG8_LDA(At, 1, 1); PG8_STAGE(PG8_SA(1, 0), a3, voffA);
;             PG8_BAR; PG8_WAIT_L(0); PG8_MMA(1, 0, At, B0); PG8_BAR; PG8_SCHED;
	s_setprio 1
	v_mfma_f32_16x16x32_bf16 v[52:55], v[218:221], v[180:183], 0
	v_mfma_f32_16x16x32_bf16 v[48:51], v[226:229], v[180:183], 0
	v_mfma_f32_16x16x32_bf16 v[36:39], v[218:221], v[194:197], 0
	v_mfma_f32_16x16x32_bf16 v[32:35], v[226:229], v[194:197], 0
	v_mfma_f32_16x16x32_bf16 v[20:23], v[218:221], v[202:205], 0
	v_mfma_f32_16x16x32_bf16 v[16:19], v[226:229], v[202:205], 0
	v_mfma_f32_16x16x32_bf16 v[4:7], v[218:221], v[210:213], 0
	v_mfma_f32_16x16x32_bf16 v[0:3], v[226:229], v[210:213], 0
	v_mfma_f32_16x16x32_bf16 v[52:55], v[222:225], v[188:191], v[52:55]
	v_mfma_f32_16x16x32_bf16 v[48:51], v[230:233], v[188:191], v[48:51]
	v_mfma_f32_16x16x32_bf16 v[36:39], v[222:225], v[198:201], v[36:39]
	v_mfma_f32_16x16x32_bf16 v[32:35], v[230:233], v[198:201], v[32:35]
	v_mfma_f32_16x16x32_bf16 v[20:23], v[222:225], v[206:209], v[20:23]
	v_mfma_f32_16x16x32_bf16 v[16:19], v[230:233], v[206:209], v[16:19]
	v_mfma_f32_16x16x32_bf16 v[4:7], v[222:225], v[214:217], v[4:7]
	v_mfma_f32_16x16x32_bf16 v[0:3], v[230:233], v[214:217], v[0:3]
	s_setprio 0
	s_add_i32 s4, 0, 0x18000
	v_add_u32_e32 v148, s4, v164
	s_barrier
	ds_read_b128 v[144:147], v148
	ds_read_b128 v[168:171], v148 offset:1024
	ds_read_b128 v[172:175], v148 offset:2048
	ds_read_b128 v[176:179], v148 offset:3072
	s_add_u32 s0, s38, 0x30000
	s_addc_u32 s1, s39, 0
	s_mov_b32 m0, s53
	ds_read_b128 v[180:183], v166 offset:32768
	ds_read_b128 v[188:191], v166 offset:33792
	ds_read_b128 v[194:197], v166 offset:34816
	ds_read_b128 v[198:201], v166 offset:35840
	ds_read_b128 v[202:205], v166 offset:36864
	ds_read_b128 v[206:209], v166 offset:37888
	ds_read_b128 v[210:213], v166 offset:38912
	global_load_lds_dwordx4 v128, s[0:1]
	s_mov_b32 m0, s54
	ds_read_b128 v[214:217], v166 offset:39936
	global_load_lds_dwordx4 v132, s[0:1]
	s_waitcnt lgkmcnt(8)
	s_barrier
	s_waitcnt lgkmcnt(0)
	s_setprio 1
	v_mfma_f32_16x16x32_bf16 v[124:127], v[144:147], v[180:183], v[124:127]
	v_mfma_f32_16x16x32_bf16 v[120:123], v[172:175], v[180:183], v[120:123]
	v_mfma_f32_16x16x32_bf16 v[108:111], v[144:147], v[194:197], v[108:111]
	v_mfma_f32_16x16x32_bf16 v[104:107], v[172:175], v[194:197], v[104:107]
	v_mfma_f32_16x16x32_bf16 v[92:95], v[144:147], v[202:205], v[92:95]
	v_mfma_f32_16x16x32_bf16 v[88:91], v[172:175], v[202:205], v[88:91]
	v_mfma_f32_16x16x32_bf16 v[76:79], v[144:147], v[210:213], v[76:79]
	v_mfma_f32_16x16x32_bf16 v[72:75], v[172:175], v[210:213], v[72:75]
	v_mfma_f32_16x16x32_bf16 v[124:127], v[168:171], v[188:191], v[124:127]
	v_mfma_f32_16x16x32_bf16 v[120:123], v[176:179], v[188:191], v[120:123]
	v_mfma_f32_16x16x32_bf16 v[108:111], v[168:171], v[198:201], v[108:111]
	v_mfma_f32_16x16x32_bf16 v[104:107], v[176:179], v[198:201], v[104:107]
	v_mfma_f32_16x16x32_bf16 v[92:95], v[168:171], v[206:209], v[92:95]
	v_mfma_f32_16x16x32_bf16 v[88:91], v[176:179], v[206:209], v[88:91]
	v_mfma_f32_16x16x32_bf16 v[76:79], v[168:171], v[214:217], v[76:79]
	v_mfma_f32_16x16x32_bf16 v[72:75], v[176:179], v[214:217], v[72:75]
	s_setprio 0
	s_barrier
	s_add_i32 s5, 0, 0x1c000
	s_add_i32 s0, s4, s50
	v_add_u32_e32 v149, s5, v164
	s_add_i32 m0, s0, 0xffffff80
	ds_read_b128 v[218:221], v149
	ds_read_b128 v[222:225], v149 offset:1024
	ds_read_b128 v[226:229], v149 offset:2048
	global_load_lds_dwordx4 v130, s[36:37] offset:128
	s_add_i32 m0, s0, 0x1f80
	ds_read_b128 v[230:233], v149 offset:3072
	global_load_lds_dwordx4 v134, s[36:37] offset:128
	s_barrier
	s_waitcnt lgkmcnt(0)
	s_setprio 1
	v_mfma_f32_16x16x32_bf16 v[116:119], v[218:221], v[180:183], v[116:119]
	v_mfma_f32_16x16x32_bf16 v[112:115], v[226:229], v[180:183], v[112:115]
	v_mfma_f32_16x16x32_bf16 v[100:103], v[218:221], v[194:197], v[100:103]
	v_mfma_f32_16x16x32_bf16 v[96:99], v[226:229], v[194:197], v[96:99]
	v_mfma_f32_16x16x32_bf16 v[84:87], v[218:221], v[202:205], v[84:87]
	v_mfma_f32_16x16x32_bf16 v[80:83], v[226:229], v[202:205], v[80:83]
	v_mfma_f32_16x16x32_bf16 v[68:71], v[218:221], v[210:213], v[68:71]
	v_mfma_f32_16x16x32_bf16 v[64:67], v[226:229], v[210:213], v[64:67]
	v_mfma_f32_16x16x32_bf16 v[116:119], v[222:225], v[188:191], v[116:119]
	v_mfma_f32_16x16x32_bf16 v[112:115], v[230:233], v[188:191], v[112:115]
	v_mfma_f32_16x16x32_bf16 v[100:103], v[222:225], v[198:201], v[100:103]
	v_mfma_f32_16x16x32_bf16 v[96:99], v[230:233], v[198:201], v[96:99]
	v_mfma_f32_16x16x32_bf16 v[84:87], v[222:225], v[206:209], v[84:87]
	v_mfma_f32_16x16x32_bf16 v[80:83], v[230:233], v[206:209], v[80:83]
	v_mfma_f32_16x16x32_bf16 v[68:71], v[222:225], v[214:217], v[68:71]
	v_mfma_f32_16x16x32_bf16 v[64:67], v[230:233], v[214:217], v[64:67]
	s_setprio 0
	s_add_i32 m0, s57, 0xffffff80
	s_barrier
	ds_read_b128 v[180:183], v166 offset:49152
	ds_read_b128 v[188:191], v166 offset:50176
	ds_read_b128 v[194:197], v166 offset:51200
	ds_read_b128 v[198:201], v166 offset:52224
	ds_read_b128 v[202:205], v166 offset:53248
	ds_read_b128 v[206:209], v166 offset:54272
	ds_read_b128 v[210:213], v166 offset:55296
	global_load_lds_dwordx4 v128, s[38:39] offset:128
	s_add_i32 m0, s58, 0xffffff80
	ds_read_b128 v[214:217], v166 offset:56320
	global_load_lds_dwordx4 v132, s[38:39] offset:128
	s_barrier
; #define PG8_STAGE(bufoff, gbase, voff) do { _Pragma("unroll") for (int _i = 0; _i < 2; ++_i) \
;         __builtin_amdgcn_global_load_lds((const unsigned*)((const char*)(gbase) + (voff)[_i]), (LAS unsigned*)(lds + (bufoff) + ldsw + _i * 8192), 16, 0, 0); } while (0)
; #define PG8_LDA(dst, b, h) do { _Pragma("unroll") for (int m = 0; m < 4; ++m) _Pragma("unroll") for (int k = 0; k < 2; ++k) dst[m][k] = *(const LAS bf16x8*)(lds + PG8_SA(b, h) + aoff + m * 2048 + k * 1024); } while (0)
; #define PG8_LDB(dst, b, h) do { _Pragma("unroll") for (int n = 0; n < 2; ++n) _Pragma("unroll") for (int k = 0; k < 2; ++k) dst[n][k] = *(const LAS bf16x8*)(lds + PG8_SB(b, h) + boff + n * 2048 + k * 1024); } while (0)
; #define PG8_MMA(ai, bj, At, Bt) do { __builtin_amdgcn_s_setprio(1); _Pragma("unroll") for (int m = 0; m < 4; ++m) _Pragma("unroll") for (int n = 0; n < 2; ++n) _Pragma("unroll") for (int k = 0; k < 2; ++k) \
;         acc[ai][bj][m][n] = __builtin_amdgcn_mfma_f32_16x16x32_bf16(Bt[n][k], At[m][k], acc[ai][bj][m][n], 0, 0, 0); __builtin_amdgcn_s_setprio(0); } while (0)
; #define PG8_WAIT_V(n) asm volatile("s_waitcnt vmcnt(" #n ")" ::: "memory")
; #define PG8_WAIT_L(n) asm volatile("s_waitcnt lgkmcnt(" #n ")" ::: "memory")
; #define PG8_BAR __builtin_amdgcn_s_barrier()
; #define PG8_SCHED __builtin_amdgcn_sched_barrier(0)
; template <class Epi, class Sched>
; DI void gemm_phase(LAS unsigned char* lds, const Gemm g, const Sched& S, const Epi& E) {
;     ...
;             const bool last = (t == nt - 2);
;             const char* a1 = cA + (size_t)(t + 1) * kstep;
;             const char* a2 = last ? nA : cA + (size_t)(t + 2) * kstep; const char* b2 = last ? nB : cB + (size_t)(t + 2) * kstep;
;             const char* a3 = a2 + kstep; const char* b3 = b2 + kstep;
;             PG8_LDB(B0, 0, 0); PG8_SCHED; PG8_LDA(At, 0, 0); PG8_STAGE(PG8_SA(1, 1), a1 + hstep, voffA);
;             PG8_WAIT_L(8); PG8_BAR; PG8_WAIT_L(0); PG8_MMA(0, 0, At, B0); PG8_BAR; PG8_SCHED;
;             PG8_LDB(B1, 0, 1); PG8_STAGE(PG8_SB(0, 0), b2, voffB);
;     ...
;             PG8_BAR; PG8_WAIT_L(0); PG8_MMA(1, 0, At, B0); PG8_BAR; PG8_SCHED;
;             PG8_STAGE(PG8_SB(1, 1), b3 + hstep, voffB);
;             PG8_WAIT_V(6); PG8_BAR; PG8_MMA(1, 1, At, B1); PG8_BAR;
	s_waitcnt lgkmcnt(0)
	s_setprio 1
	v_mfma_f32_16x16x32_bf16 v[60:63], v[144:147], v[180:183], v[60:63]
	v_mfma_f32_16x16x32_bf16 v[56:59], v[172:175], v[180:183], v[56:59]
	v_mfma_f32_16x16x32_bf16 v[44:47], v[144:147], v[194:197], v[44:47]
	v_mfma_f32_16x16x32_bf16 v[40:43], v[172:175], v[194:197], v[40:43]
	v_mfma_f32_16x16x32_bf16 v[28:31], v[144:147], v[202:205], v[28:31]
	v_mfma_f32_16x16x32_bf16 v[24:27], v[172:175], v[202:205], v[24:27]
	v_mfma_f32_16x16x32_bf16 v[12:15], v[144:147], v[210:213], v[12:15]
	v_mfma_f32_16x16x32_bf16 v[8:11], v[172:175], v[210:213], v[8:11]
	v_mfma_f32_16x16x32_bf16 v[60:63], v[168:171], v[188:191], v[60:63]
	v_mfma_f32_16x16x32_bf16 v[56:59], v[176:179], v[188:191], v[56:59]
	v_mfma_f32_16x16x32_bf16 v[44:47], v[168:171], v[198:201], v[44:47]
	v_mfma_f32_16x16x32_bf16 v[40:43], v[176:179], v[198:201], v[40:43]
	v_mfma_f32_16x16x32_bf16 v[28:31], v[168:171], v[206:209], v[28:31]
	v_mfma_f32_16x16x32_bf16 v[24:27], v[176:179], v[206:209], v[24:27]
	v_mfma_f32_16x16x32_bf16 v[12:15], v[168:171], v[214:217], v[12:15]
	v_mfma_f32_16x16x32_bf16 v[8:11], v[176:179], v[214:217], v[8:11]
	s_setprio 0
	s_barrier
	s_add_u32 s0, s36, 0x30080
	s_addc_u32 s1, s37, 0
	s_add_i32 s4, s5, s50
	s_mov_b32 m0, s4
	s_nop 0
	global_load_lds_dwordx4 v130, s[0:1]
	s_add_i32 m0, s4, 0x2000
	s_nop 0
	global_load_lds_dwordx4 v134, s[0:1]
	s_waitcnt vmcnt(6)
	s_barrier
	s_setprio 1
	v_mfma_f32_16x16x32_bf16 v[52:55], v[218:221], v[180:183], v[52:55]
	v_mfma_f32_16x16x32_bf16 v[48:51], v[226:229], v[180:183], v[48:51]
	v_mfma_f32_16x16x32_bf16 v[36:39], v[218:221], v[194:197], v[36:39]
	v_mfma_f32_16x16x32_bf16 v[32:35], v[226:229], v[194:197], v[32:35]
	v_mfma_f32_16x16x32_bf16 v[20:23], v[218:221], v[202:205], v[20:23]
	v_mfma_f32_16x16x32_bf16 v[16:19], v[226:229], v[202:205], v[16:19]
	v_mfma_f32_16x16x32_bf16 v[4:7], v[218:221], v[210:213], v[4:7]
	v_mfma_f32_16x16x32_bf16 v[0:3], v[226:229], v[210:213], v[0:3]
	v_mfma_f32_16x16x32_bf16 v[52:55], v[222:225], v[188:191], v[52:55]
	v_mfma_f32_16x16x32_bf16 v[48:51], v[230:233], v[188:191], v[48:51]
	v_mfma_f32_16x16x32_bf16 v[36:39], v[222:225], v[198:201], v[36:39]
	v_mfma_f32_16x16x32_bf16 v[32:35], v[230:233], v[198:201], v[32:35]
	v_mfma_f32_16x16x32_bf16 v[20:23], v[222:225], v[206:209], v[20:23]
	v_mfma_f32_16x16x32_bf16 v[16:19], v[230:233], v[206:209], v[16:19]
	v_mfma_f32_16x16x32_bf16 v[4:7], v[222:225], v[214:217], v[4:7]
	v_mfma_f32_16x16x32_bf16 v[0:3], v[230:233], v[214:217], v[0:3]
	s_setprio 0
	s_add_i32 s41, s41, 2
	s_add_u32 s8, s8, 0x100
	s_addc_u32 s9, s9, 0
	s_add_u32 s35, s35, 0x100
	s_addc_u32 s40, s40, 0
	s_cmp_gt_u32 s41, 9
	s_barrier
	s_cbranch_scc0 .LBB0_938
	s_branch .Lpeel_done_938
.LBB0_938:
	ds_read_b128 v[144:147], v165
	ds_read_b128 v[168:171], v165 offset:1024
	ds_read_b128 v[172:175], v165 offset:2048
	ds_read_b128 v[176:179], v165 offset:3072
	s_add_u32 s0, s8, 0xfffd0080
	s_addc_u32 s1, s9, -1
	s_cmp_eq_u32 s41, 8
	s_cselect_b32 s39, s31, s1
	s_cselect_b32 s38, s30, s0
	s_cselect_b32 s37, s11, s40
	s_cselect_b32 s36, s10, s35
	s_add_i32 m0, s51, 0xc000
	ds_read_b128 v[180:183], v166
	ds_read_b128 v[188:191], v166 offset:1024
	ds_read_b128 v[194:197], v166 offset:2048
	ds_read_b128 v[198:201], v166 offset:3072
	ds_read_b128 v[202:205], v166 offset:4096
	ds_read_b128 v[206:209], v166 offset:5120
	ds_read_b128 v[210:213], v166 offset:6144
	global_load_lds_dwordx4 v136, s[8:9]
	s_add_i32 m0, s51, 0xe000
	ds_read_b128 v[214:217], v166 offset:7168
	global_load_lds_dwordx4 v138, s[8:9]
	s_waitcnt lgkmcnt(8)
	s_barrier
	s_waitcnt lgkmcnt(0)
	s_setprio 1
	v_mfma_f32_16x16x32_bf16 v[124:127], v[144:147], v[180:183], v[124:127]
	v_mfma_f32_16x16x32_bf16 v[120:123], v[172:175], v[180:183], v[120:123]
	v_mfma_f32_16x16x32_bf16 v[108:111], v[144:147], v[194:197], v[108:111]
	v_mfma_f32_16x16x32_bf16 v[104:107], v[172:175], v[194:197], v[104:107]
	v_mfma_f32_16x16x32_bf16 v[92:95], v[144:147], v[202:205], v[92:95]
	v_mfma_f32_16x16x32_bf16 v[88:91], v[172:175], v[202:205], v[88:91]
	v_mfma_f32_16x16x32_bf16 v[76:79], v[144:147], v[210:213], v[76:79]
	v_mfma_f32_16x16x32_bf16 v[72:75], v[172:175], v[210:213], v[72:75]
	v_mfma_f32_16x16x32_bf16 v[124:127], v[168:171], v[188:191], v[124:127]
	v_mfma_f32_16x16x32_bf16 v[120:123], v[176:179], v[188:191], v[120:123]
	v_mfma_f32_16x16x32_bf16 v[108:111], v[168:171], v[198:201], v[108:111]
	v_mfma_f32_16x16x32_bf16 v[104:107], v[176:179], v[198:201], v[104:107]
	v_mfma_f32_16x16x32_bf16 v[92:95], v[168:171], v[206:209], v[92:95]
	v_mfma_f32_16x16x32_bf16 v[88:91], v[176:179], v[206:209], v[88:91]
	v_mfma_f32_16x16x32_bf16 v[76:79], v[168:171], v[214:217], v[76:79]
	v_mfma_f32_16x16x32_bf16 v[72:75], v[176:179], v[214:217], v[72:75]
	s_setprio 0
	s_barrier
	s_add_i32 s0, s61, s50
	s_mov_b32 m0, s0
	ds_read_b128 v[218:221], v167
	ds_read_b128 v[222:225], v167 offset:1024
	ds_read_b128 v[226:229], v167 offset:2048
	global_load_lds_dwordx4 v130, s[36:37]
	s_add_i32 m0, s0, 0x2000
	ds_read_b128 v[230:233], v167 offset:3072
	global_load_lds_dwordx4 v134, s[36:37]
	s_barrier
; #define PG8_STAGE(bufoff, gbase, voff) do { _Pragma("unroll") for (int _i = 0; _i < 2; ++_i) \
;         __builtin_amdgcn_global_load_lds((const unsigned*)((const char*)(gbase) + (voff)[_i]), (LAS unsigned*)(lds + (bufoff) + ldsw + _i * 8192), 16, 0, 0); } while (0)
; #define PG8_LDA(dst, b, h) do { _Pragma("unroll") for (int m = 0; m < 4; ++m) _Pragma("unroll") for (int k = 0; k < 2; ++k) dst[m][k] = *(const LAS bf16x8*)(lds + PG8_SA(b, h) + aoff + m * 2048 + k * 1024); } while (0)
; #define PG8_LDB(dst, b, h) do { _Pragma("unroll") for (int n = 0; n < 2; ++n) _Pragma("unroll") for (int k = 0; k < 2; ++k) dst[n][k] = *(const LAS bf16x8*)(lds + PG8_SB(b, h) + boff + n * 2048 + k * 1024); } while (0)
; #define PG8_MMA(ai, bj, At, Bt) do { __builtin_amdgcn_s_setprio(1); _Pragma("unroll") for (int m = 0; m < 4; ++m) _Pragma("unroll") for (int n = 0; n < 2; ++n) _Pragma("unroll") for (int k = 0; k < 2; ++k) \
;         acc[ai][bj][m][n] = __builtin_amdgcn_mfma_f32_16x16x32_bf16(Bt[n][k], At[m][k], acc[ai][bj][m][n], 0, 0, 0); __builtin_amdgcn_s_setprio(0); } while (0)
; #define PG8_WAIT_V(n) asm volatile("s_waitcnt vmcnt(" #n ")" ::: "memory")
; #define PG8_WAIT_L(n) asm volatile("s_waitcnt lgkmcnt(" #n ")" ::: "memory")
; #define PG8_BAR __builtin_amdgcn_s_barrier()
; #define PG8_SCHED __builtin_amdgcn_sched_barrier(0)
; template <class Epi, class Sched>
; DI void gemm_phase(LAS unsigned char* lds, const Gemm g, const Sched& S, const Epi& E) {
;     ...
;             PG8_BAR; PG8_WAIT_L(0); PG8_MMA(0, 1, At, B1); PG8_BAR;
;             PG8_LDA(At, 0, 1); PG8_STAGE(PG8_SA(0, 0), a2, voffA);
;             PG8_BAR; PG8_WAIT_L(0); PG8_MMA(1, 0, At, B0); PG8_BAR; PG8_SCHED;
;             PG8_STAGE(PG8_SB(0, 1), b2 + hstep, voffB);
;             PG8_WAIT_V(6); PG8_BAR; PG8_MMA(1, 1, At, B1); PG8_BAR;
;             PG8_LDB(B0, 1, 0); PG8_SCHED; PG8_LDA(At, 1, 0); PG8_STAGE(PG8_SA(0, 1), a2 + hstep, voffA);
;             PG8_WAIT_L(8); PG8_BAR; PG8_WAIT_L(0); PG8_MMA(0, 0, At, B0); PG8_BAR; PG8_SCHED;
	s_waitcnt lgkmcnt(0)
	s_setprio 1
	v_mfma_f32_16x16x32_bf16 v[116:119], v[218:221], v[180:183], v[116:119]
	v_mfma_f32_16x16x32_bf16 v[112:115], v[226:229], v[180:183], v[112:115]
	v_mfma_f32_16x16x32_bf16 v[100:103], v[218:221], v[194:197], v[100:103]
	v_mfma_f32_16x16x32_bf16 v[96:99], v[226:229], v[194:197], v[96:99]
	v_mfma_f32_16x16x32_bf16 v[84:87], v[218:221], v[202:205], v[84:87]
	v_mfma_f32_16x16x32_bf16 v[80:83], v[226:229], v[202:205], v[80:83]
	v_mfma_f32_16x16x32_bf16 v[68:71], v[218:221], v[210:213], v[68:71]
	v_mfma_f32_16x16x32_bf16 v[64:67], v[226:229], v[210:213], v[64:67]
	v_mfma_f32_16x16x32_bf16 v[116:119], v[222:225], v[188:191], v[116:119]
	v_mfma_f32_16x16x32_bf16 v[112:115], v[230:233], v[188:191], v[112:115]
	v_mfma_f32_16x16x32_bf16 v[100:103], v[222:225], v[198:201], v[100:103]
	v_mfma_f32_16x16x32_bf16 v[96:99], v[230:233], v[198:201], v[96:99]
	v_mfma_f32_16x16x32_bf16 v[84:87], v[222:225], v[206:209], v[84:87]
	v_mfma_f32_16x16x32_bf16 v[80:83], v[230:233], v[206:209], v[80:83]
	v_mfma_f32_16x16x32_bf16 v[68:71], v[222:225], v[214:217], v[68:71]
	v_mfma_f32_16x16x32_bf16 v[64:67], v[230:233], v[214:217], v[64:67]
	s_setprio 0
	s_mov_b32 m0, s51
	s_barrier
	ds_read_b128 v[180:183], v166 offset:16384
	ds_read_b128 v[188:191], v166 offset:17408
	ds_read_b128 v[194:197], v166 offset:18432
	ds_read_b128 v[198:201], v166 offset:19456
	ds_read_b128 v[202:205], v166 offset:20480
	ds_read_b128 v[206:209], v166 offset:21504
	ds_read_b128 v[210:213], v166 offset:22528
	global_load_lds_dwordx4 v128, s[38:39]
	s_mov_b32 m0, s52
	ds_read_b128 v[214:217], v166 offset:23552
	global_load_lds_dwordx4 v132, s[38:39]
	s_barrier
	s_waitcnt lgkmcnt(0)
	s_setprio 1
	v_mfma_f32_16x16x32_bf16 v[60:63], v[144:147], v[180:183], v[60:63]
	v_mfma_f32_16x16x32_bf16 v[56:59], v[172:175], v[180:183], v[56:59]
	v_mfma_f32_16x16x32_bf16 v[44:47], v[144:147], v[194:197], v[44:47]
	v_mfma_f32_16x16x32_bf16 v[40:43], v[172:175], v[194:197], v[40:43]
	v_mfma_f32_16x16x32_bf16 v[28:31], v[144:147], v[202:205], v[28:31]
	v_mfma_f32_16x16x32_bf16 v[24:27], v[172:175], v[202:205], v[24:27]
	v_mfma_f32_16x16x32_bf16 v[12:15], v[144:147], v[210:213], v[12:15]
	v_mfma_f32_16x16x32_bf16 v[8:11], v[172:175], v[210:213], v[8:11]
	v_mfma_f32_16x16x32_bf16 v[60:63], v[168:171], v[188:191], v[60:63]
	v_mfma_f32_16x16x32_bf16 v[56:59], v[176:179], v[188:191], v[56:59]
	v_mfma_f32_16x16x32_bf16 v[44:47], v[168:171], v[198:201], v[44:47]
	v_mfma_f32_16x16x32_bf16 v[40:43], v[176:179], v[198:201], v[40:43]
	v_mfma_f32_16x16x32_bf16 v[28:31], v[168:171], v[206:209], v[28:31]
	v_mfma_f32_16x16x32_bf16 v[24:27], v[176:179], v[206:209], v[24:27]
	v_mfma_f32_16x16x32_bf16 v[12:15], v[168:171], v[214:217], v[12:15]
	v_mfma_f32_16x16x32_bf16 v[8:11], v[176:179], v[214:217], v[8:11]
	s_setprio 0
	s_barrier
	s_add_u32 s0, s36, 0x30000
	s_addc_u32 s1, s37, 0
	s_add_i32 s4, s62, s50
	s_mov_b32 m0, s4
	s_nop 0
	global_load_lds_dwordx4 v130, s[0:1]
	s_add_i32 m0, s4, 0x2000
	s_nop 0
	global_load_lds_dwordx4 v134, s[0:1]
	s_waitcnt vmcnt(6)
	s_barrier
	s_setprio 1
	v_mfma_f32_16x16x32_bf16 v[52:55], v[218:221], v[180:183], v[52:55]
	v_mfma_f32_16x16x32_bf16 v[48:51], v[226:229], v[180:183], v[48:51]
	v_mfma_f32_16x16x32_bf16 v[36:39], v[218:221], v[194:197], v[36:39]
	v_mfma_f32_16x16x32_bf16 v[32:35], v[226:229], v[194:197], v[32:35]
	v_mfma_f32_16x16x32_bf16 v[20:23], v[218:221], v[202:205], v[20:23]
	v_mfma_f32_16x16x32_bf16 v[16:19], v[226:229], v[202:205], v[16:19]
	v_mfma_f32_16x16x32_bf16 v[4:7], v[218:221], v[210:213], v[4:7]
	v_mfma_f32_16x16x32_bf16 v[0:3], v[226:229], v[210:213], v[0:3]
	v_mfma_f32_16x16x32_bf16 v[52:55], v[222:225], v[188:191], v[52:55]
	v_mfma_f32_16x16x32_bf16 v[48:51], v[230:233], v[188:191], v[48:51]
	v_mfma_f32_16x16x32_bf16 v[36:39], v[222:225], v[198:201], v[36:39]
	v_mfma_f32_16x16x32_bf16 v[32:35], v[230:233], v[198:201], v[32:35]
	v_mfma_f32_16x16x32_bf16 v[20:23], v[222:225], v[206:209], v[20:23]
	v_mfma_f32_16x16x32_bf16 v[16:19], v[230:233], v[206:209], v[16:19]
	v_mfma_f32_16x16x32_bf16 v[4:7], v[222:225], v[214:217], v[4:7]
	v_mfma_f32_16x16x32_bf16 v[0:3], v[230:233], v[214:217], v[0:3]
	s_setprio 0
	s_add_i32 s4, 0, 0x18000
	s_barrier
	ds_read_b128 v[144:147], v148
	ds_read_b128 v[168:171], v148 offset:1024
	ds_read_b128 v[172:175], v148 offset:2048
	ds_read_b128 v[176:179], v148 offset:3072
	s_add_u32 s0, s38, 0x30000
	s_addc_u32 s1, s39, 0
	s_mov_b32 m0, s53
	ds_read_b128 v[180:183], v166 offset:32768
	ds_read_b128 v[188:191], v166 offset:33792
	ds_read_b128 v[194:197], v166 offset:34816
	ds_read_b128 v[198:201], v166 offset:35840
	ds_read_b128 v[202:205], v166 offset:36864
	ds_read_b128 v[206:209], v166 offset:37888
	ds_read_b128 v[210:213], v166 offset:38912
	global_load_lds_dwordx4 v128, s[0:1]
	s_mov_b32 m0, s54
	ds_read_b128 v[214:217], v166 offset:39936
	global_load_lds_dwordx4 v132, s[0:1]
	s_waitcnt lgkmcnt(8)
	s_barrier
; #define PG8_STAGE(bufoff, gbase, voff) do { _Pragma("unroll") for (int _i = 0; _i < 2; ++_i) \
;         __builtin_amdgcn_global_load_lds((const unsigned*)((const char*)(gbase) + (voff)[_i]), (LAS unsigned*)(lds + (bufoff) + ldsw + _i * 8192), 16, 0, 0); } while (0)
; #define PG8_LDA(dst, b, h) do { _Pragma("unroll") for (int m = 0; m < 4; ++m) _Pragma("unroll") for (int k = 0; k < 2; ++k) dst[m][k] = *(const LAS bf16x8*)(lds + PG8_SA(b, h) + aoff + m * 2048 + k * 1024); } while (0)
; #define PG8_LDB(dst, b, h) do { _Pragma("unroll") for (int n = 0; n < 2; ++n) _Pragma("unroll") for (int k = 0; k < 2; ++k) dst[n][k] = *(const LAS bf16x8*)(lds + PG8_SB(b, h) + boff + n * 2048 + k * 1024); } while (0)
; #define PG8_MMA(ai, bj, At, Bt) do { __builtin_amdgcn_s_setprio(1); _Pragma("unroll") for (int m = 0; m < 4; ++m) _Pragma("unroll") for (int n = 0; n < 2; ++n) _Pragma("unroll") for (int k = 0; k < 2; ++k) \
;         acc[ai][bj][m][n] = __builtin_amdgcn_mfma_f32_16x16x32_bf16(Bt[n][k], At[m][k], acc[ai][bj][m][n], 0, 0, 0); __builtin_amdgcn_s_setprio(0); } while (0)
; #define PG8_WAIT_V(n) asm volatile("s_waitcnt vmcnt(" #n ")" ::: "memory")
; #define PG8_WAIT_L(n) asm volatile("s_waitcnt lgkmcnt(" #n ")" ::: "memory")
; #define PG8_BAR __builtin_amdgcn_s_barrier()
; #define PG8_SCHED __builtin_amdgcn_sched_barrier(0)
; template <class Epi, class Sched>
; DI void gemm_phase(LAS unsigned char* lds, const Gemm g, const Sched& S, const Epi& E) {
;     ...
;             PG8_WAIT_L(8); PG8_BAR; PG8_WAIT_L(0); PG8_MMA(0, 0, At, B0); PG8_BAR; PG8_SCHED;
;             PG8_LDB(B1, 1, 1); PG8_STAGE(PG8_SB(1, 0), b3, voffB);
;             PG8_BAR; PG8_WAIT_L(0); PG8_MMA(0, 1, At, B1); PG8_BAR;
;             PG8_LDA(At, 1, 1); PG8_STAGE(PG8_SA(1, 0), a3, voffA);
;             PG8_BAR; PG8_WAIT_L(0); PG8_MMA(1, 0, At, B0); PG8_BAR; PG8_SCHED;
;             PG8_STAGE(PG8_SB(1, 1), b3 + hstep, voffB);
;             PG8_WAIT_V(6); PG8_BAR; PG8_MMA(1, 1, At, B1); PG8_BAR;
	s_waitcnt lgkmcnt(0)
	s_setprio 1
	v_mfma_f32_16x16x32_bf16 v[124:127], v[144:147], v[180:183], v[124:127]
	v_mfma_f32_16x16x32_bf16 v[120:123], v[172:175], v[180:183], v[120:123]
	v_mfma_f32_16x16x32_bf16 v[108:111], v[144:147], v[194:197], v[108:111]
	v_mfma_f32_16x16x32_bf16 v[104:107], v[172:175], v[194:197], v[104:107]
	v_mfma_f32_16x16x32_bf16 v[92:95], v[144:147], v[202:205], v[92:95]
	v_mfma_f32_16x16x32_bf16 v[88:91], v[172:175], v[202:205], v[88:91]
	v_mfma_f32_16x16x32_bf16 v[76:79], v[144:147], v[210:213], v[76:79]
	v_mfma_f32_16x16x32_bf16 v[72:75], v[172:175], v[210:213], v[72:75]
	v_mfma_f32_16x16x32_bf16 v[124:127], v[168:171], v[188:191], v[124:127]
	v_mfma_f32_16x16x32_bf16 v[120:123], v[176:179], v[188:191], v[120:123]
	v_mfma_f32_16x16x32_bf16 v[108:111], v[168:171], v[198:201], v[108:111]
	v_mfma_f32_16x16x32_bf16 v[104:107], v[176:179], v[198:201], v[104:107]
	v_mfma_f32_16x16x32_bf16 v[92:95], v[168:171], v[206:209], v[92:95]
	v_mfma_f32_16x16x32_bf16 v[88:91], v[176:179], v[206:209], v[88:91]
	v_mfma_f32_16x16x32_bf16 v[76:79], v[168:171], v[214:217], v[76:79]
	v_mfma_f32_16x16x32_bf16 v[72:75], v[176:179], v[214:217], v[72:75]
	s_setprio 0
	s_barrier
	s_add_i32 s5, 0, 0x1c000
	s_add_i32 s0, s4, s50
	s_add_i32 m0, s0, 0xffffff80
	ds_read_b128 v[218:221], v149
	ds_read_b128 v[222:225], v149 offset:1024
	ds_read_b128 v[226:229], v149 offset:2048
	global_load_lds_dwordx4 v130, s[36:37] offset:128
	s_add_i32 m0, s0, 0x1f80
	ds_read_b128 v[230:233], v149 offset:3072
	global_load_lds_dwordx4 v134, s[36:37] offset:128
	s_barrier
	s_waitcnt lgkmcnt(0)
	s_setprio 1
	v_mfma_f32_16x16x32_bf16 v[116:119], v[218:221], v[180:183], v[116:119]
	v_mfma_f32_16x16x32_bf16 v[112:115], v[226:229], v[180:183], v[112:115]
	v_mfma_f32_16x16x32_bf16 v[100:103], v[218:221], v[194:197], v[100:103]
	v_mfma_f32_16x16x32_bf16 v[96:99], v[226:229], v[194:197], v[96:99]
	v_mfma_f32_16x16x32_bf16 v[84:87], v[218:221], v[202:205], v[84:87]
	v_mfma_f32_16x16x32_bf16 v[80:83], v[226:229], v[202:205], v[80:83]
	v_mfma_f32_16x16x32_bf16 v[68:71], v[218:221], v[210:213], v[68:71]
	v_mfma_f32_16x16x32_bf16 v[64:67], v[226:229], v[210:213], v[64:67]
	v_mfma_f32_16x16x32_bf16 v[116:119], v[222:225], v[188:191], v[116:119]
	v_mfma_f32_16x16x32_bf16 v[112:115], v[230:233], v[188:191], v[112:115]
	v_mfma_f32_16x16x32_bf16 v[100:103], v[222:225], v[198:201], v[100:103]
	v_mfma_f32_16x16x32_bf16 v[96:99], v[230:233], v[198:201], v[96:99]
	v_mfma_f32_16x16x32_bf16 v[84:87], v[222:225], v[206:209], v[84:87]
	v_mfma_f32_16x16x32_bf16 v[80:83], v[230:233], v[206:209], v[80:83]
	v_mfma_f32_16x16x32_bf16 v[68:71], v[222:225], v[214:217], v[68:71]
	v_mfma_f32_16x16x32_bf16 v[64:67], v[230:233], v[214:217], v[64:67]
	s_setprio 0
	s_add_i32 m0, s57, 0xffffff80
	s_barrier
	ds_read_b128 v[180:183], v166 offset:49152
	ds_read_b128 v[188:191], v166 offset:50176
	ds_read_b128 v[194:197], v166 offset:51200
	ds_read_b128 v[198:201], v166 offset:52224
	ds_read_b128 v[202:205], v166 offset:53248
	ds_read_b128 v[206:209], v166 offset:54272
	ds_read_b128 v[210:213], v166 offset:55296
	global_load_lds_dwordx4 v128, s[38:39] offset:128
	s_add_i32 m0, s58, 0xffffff80
	ds_read_b128 v[214:217], v166 offset:56320
	global_load_lds_dwordx4 v132, s[38:39] offset:128
	s_barrier
	s_waitcnt lgkmcnt(0)
	s_setprio 1
	v_mfma_f32_16x16x32_bf16 v[60:63], v[144:147], v[180:183], v[60:63]
	v_mfma_f32_16x16x32_bf16 v[56:59], v[172:175], v[180:183], v[56:59]
	v_mfma_f32_16x16x32_bf16 v[44:47], v[144:147], v[194:197], v[44:47]
	v_mfma_f32_16x16x32_bf16 v[40:43], v[172:175], v[194:197], v[40:43]
	v_mfma_f32_16x16x32_bf16 v[28:31], v[144:147], v[202:205], v[28:31]
	v_mfma_f32_16x16x32_bf16 v[24:27], v[172:175], v[202:205], v[24:27]
	v_mfma_f32_16x16x32_bf16 v[12:15], v[144:147], v[210:213], v[12:15]
	v_mfma_f32_16x16x32_bf16 v[8:11], v[172:175], v[210:213], v[8:11]
	v_mfma_f32_16x16x32_bf16 v[60:63], v[168:171], v[188:191], v[60:63]
	v_mfma_f32_16x16x32_bf16 v[56:59], v[176:179], v[188:191], v[56:59]
	v_mfma_f32_16x16x32_bf16 v[44:47], v[168:171], v[198:201], v[44:47]
	v_mfma_f32_16x16x32_bf16 v[40:43], v[176:179], v[198:201], v[40:43]
	v_mfma_f32_16x16x32_bf16 v[28:31], v[168:171], v[206:209], v[28:31]
	v_mfma_f32_16x16x32_bf16 v[24:27], v[176:179], v[206:209], v[24:27]
	v_mfma_f32_16x16x32_bf16 v[12:15], v[168:171], v[214:217], v[12:15]
	v_mfma_f32_16x16x32_bf16 v[8:11], v[176:179], v[214:217], v[8:11]
	s_setprio 0
	s_barrier
	s_add_u32 s0, s36, 0x30080
	s_addc_u32 s1, s37, 0
	s_add_i32 s4, s5, s50
	s_mov_b32 m0, s4
	s_nop 0
	global_load_lds_dwordx4 v130, s[0:1]
	s_add_i32 m0, s4, 0x2000
	s_nop 0
	global_load_lds_dwordx4 v134, s[0:1]
	s_waitcnt vmcnt(6)
	s_barrier
	s_setprio 1
	v_mfma_f32_16x16x32_bf16 v[52:55], v[218:221], v[180:183], v[52:55]
	v_mfma_f32_16x16x32_bf16 v[48:51], v[226:229], v[180:183], v[48:51]
	v_mfma_f32_16x16x32_bf16 v[36:39], v[218:221], v[194:197], v[36:39]
	v_mfma_f32_16x16x32_bf16 v[32:35], v[226:229], v[194:197], v[32:35]
	v_mfma_f32_16x16x32_bf16 v[20:23], v[218:221], v[202:205], v[20:23]
	v_mfma_f32_16x16x32_bf16 v[16:19], v[226:229], v[202:205], v[16:19]
	v_mfma_f32_16x16x32_bf16 v[4:7], v[218:221], v[210:213], v[4:7]
	v_mfma_f32_16x16x32_bf16 v[0:3], v[226:229], v[210:213], v[0:3]
	v_mfma_f32_16x16x32_bf16 v[52:55], v[222:225], v[188:191], v[52:55]
	v_mfma_f32_16x16x32_bf16 v[48:51], v[230:233], v[188:191], v[48:51]
	v_mfma_f32_16x16x32_bf16 v[36:39], v[222:225], v[198:201], v[36:39]
	v_mfma_f32_16x16x32_bf16 v[32:35], v[230:233], v[198:201], v[32:35]
	v_mfma_f32_16x16x32_bf16 v[20:23], v[222:225], v[206:209], v[20:23]
	v_mfma_f32_16x16x32_bf16 v[16:19], v[230:233], v[206:209], v[16:19]
	v_mfma_f32_16x16x32_bf16 v[4:7], v[222:225], v[214:217], v[4:7]
	v_mfma_f32_16x16x32_bf16 v[0:3], v[230:233], v[214:217], v[0:3]
	s_setprio 0
	s_add_i32 s41, s41, 2
	s_add_u32 s8, s8, 0x100
	s_addc_u32 s9, s9, 0
	s_add_u32 s35, s35, 0x100
	s_addc_u32 s40, s40, 0
	s_cmp_gt_u32 s41, 9
	s_barrier
	s_cbranch_scc0 .LBB0_938

;     DI size_t aoff(const Unit& u, size_t tstep) const { return (size_t)u.pm * tstep; }
;     DI size_t boff(const Unit& u, size_t tstep) const { return (size_t)u.pn * tstep; }
;     DI bool next(int i, Unit& u) const { const long L = (long)i * G + c; if (L >= np) return false; u.pm = pmv; u.pn = (int)(L % nN); u.ks = (int)(L / nN); return true; }
;     DI size_t aoff(const Unit& u, size_t) const { return (size_t)u.ks * kbytes; }
;     DI size_t boff(const Unit& u, size_t tstep) const { return (size_t)u.pn * tstep + (size_t)u.ks * kbytes; }
;     DI bool next(int i, Unit& u) const { Unit t; if (!S.next(i / 3, t)) return false; u.pm = t.pm; u.pn = t.pn; u.ks = i % 3; return true; }
;     DI size_t aoff(const Unit& u, size_t tstep) const { return (u.ks < 2 ? offU : offOA) + (size_t)u.pm * tstep; }
; #define PG8_LDA(dst, b, h) do { _Pragma("unroll") for (int m = 0; m < 4; ++m) _Pragma("unroll") for (int k = 0; k < 2; ++k) dst[m][k] = *(const LAS bf16x8*)(lds + PG8_SA(b, h) + aoff + m * 2048 + k * 1024); } while (0)
; template <class Epi, class Sched>
; DI void gemm_phase(LAS unsigned char* lds, const Gemm g, const Sched& S, const Epi& E) {
;     ...
;         const bool has_next = S.next(ui + 1, nxt);
;         const char* nA = has_next ? (const char*)g.A + S.aoff(nxt, tstep) : cA; const char* nB = has_next ? (const char*)g.Bt + S.boff(nxt, tstep) : cB;
;         for (int t = 0; t < nt; t += 2) {
;             if constexpr (Epi::HAS_MID) { if (t == E.mid_t(nt)) { int fr3 = fr, fq3 = fq; asm volatile("" : "+v"(fr3), "+v"(fq3)); E.mid(acc, cur, wr, wc, fr3, fq3); } }
;             const bool last = (t == nt - 2);
;             const char* a1 = cA + (size_t)(t + 1) * kstep;
;             const char* a2 = last ? nA : cA + (size_t)(t + 2) * kstep; const char* b2 = last ? nB : cB + (size_t)(t + 2) * kstep;
;             const char* a3 = a2 + kstep; const char* b3 = b2 + kstep;
;             PG8_LDB(B0, 0, 0); PG8_SCHED; PG8_LDA(At, 0, 0); PG8_STAGE(PG8_SA(1, 1), a1 + hstep, voffA);
;             PG8_WAIT_L(8); PG8_BAR; PG8_WAIT_L(0); PG8_MMA(0, 0, At, B0); PG8_BAR; PG8_SCHED;
;             PG8_LDB(B1, 0, 1); PG8_STAGE(PG8_SB(0, 0), b2, voffB);
;             PG8_BAR; PG8_WAIT_L(0); PG8_MMA(0, 1, At, B1); PG8_BAR;
;             PG8_LDA(At, 0, 1); PG8_STAGE(PG8_SA(0, 0), a2, voffA);
;             PG8_BAR; PG8_WAIT_L(0); PG8_MMA(1, 0, At, B0); PG8_BAR; PG8_SCHED;
.LBB0_983:
	s_ashr_i32 s31, s30, 31
	s_lshl_b64 s[0:1], s[30:31], 18
	v_cmp_lt_i64_e32 vcc, s[36:37], v[142:143]
	s_add_u32 s36, s51, s0
	s_addc_u32 s37, s52, s1
	s_and_b64 s[0:1], vcc, exec
	s_cselect_b32 s9, s37, s43
	s_cselect_b32 s31, s36, s42
	s_ashr_i32 s29, s28, 31
	s_lshl_b64 s[0:1], s[28:29], 18
	s_add_u32 s38, s53, s0
	s_addc_u32 s39, s54, s1
	s_and_b64 s[0:1], vcc, exec
	s_cselect_b32 s29, s39, s45
	s_cselect_b32 s34, s38, s44
	s_add_u32 s42, s42, 0x20080
	s_addc_u32 s43, s43, 0
	s_add_u32 s35, s44, 0x100
	v_mov_b32_e32 v0, 0
	s_addc_u32 s41, s45, 0
	s_mov_b32 s79, -2
	ds_read_b128 v[146:149], v156
	ds_read_b128 v[150:153], v156 offset:1024
	ds_read_b128 v[160:163], v156 offset:2048
	ds_read_b128 v[164:167], v156 offset:3072
	s_add_u32 s0, s42, 0xfffe0080
	s_addc_u32 s1, s43, -1
	s_cmp_eq_u32 s79, 4
	s_cselect_b32 s47, s9, s1
	s_cselect_b32 s46, s31, s0
	s_cselect_b32 s45, s29, s41
	s_cselect_b32 s44, s34, s35
	s_add_i32 m0, s55, 0xc000
	ds_read_b128 v[168:171], v158
	ds_read_b128 v[172:175], v158 offset:1024
	ds_read_b128 v[176:179], v158 offset:2048
	ds_read_b128 v[180:183], v158 offset:3072
	ds_read_b128 v[188:191], v158 offset:4096
	ds_read_b128 v[194:197], v158 offset:5120
	ds_read_b128 v[198:201], v158 offset:6144
	global_load_lds_dwordx4 v138, s[42:43]
	s_add_i32 m0, s55, 0xe000
	ds_read_b128 v[202:205], v158 offset:7168
	global_load_lds_dwordx4 v140, s[42:43]
	s_waitcnt lgkmcnt(8)
	s_barrier
	s_waitcnt lgkmcnt(0)
	s_setprio 1
	v_mfma_f32_16x16x32_bf16 v[124:127], v[146:149], v[168:171], 0
	v_mfma_f32_16x16x32_bf16 v[120:123], v[160:163], v[168:171], 0
	v_mfma_f32_16x16x32_bf16 v[108:111], v[146:149], v[176:179], 0
	v_mfma_f32_16x16x32_bf16 v[104:107], v[160:163], v[176:179], 0
	v_mfma_f32_16x16x32_bf16 v[92:95], v[146:149], v[188:191], 0
	v_mfma_f32_16x16x32_bf16 v[88:91], v[160:163], v[188:191], 0
	v_mfma_f32_16x16x32_bf16 v[76:79], v[146:149], v[198:201], 0
	v_mfma_f32_16x16x32_bf16 v[72:75], v[160:163], v[198:201], 0
	v_mfma_f32_16x16x32_bf16 v[124:127], v[150:153], v[172:175], v[124:127]
	v_mfma_f32_16x16x32_bf16 v[120:123], v[164:167], v[172:175], v[120:123]
	v_mfma_f32_16x16x32_bf16 v[108:111], v[150:153], v[180:183], v[108:111]
	v_mfma_f32_16x16x32_bf16 v[104:107], v[164:167], v[180:183], v[104:107]
	v_mfma_f32_16x16x32_bf16 v[92:95], v[150:153], v[194:197], v[92:95]
	v_mfma_f32_16x16x32_bf16 v[88:91], v[164:167], v[194:197], v[88:91]
	v_mfma_f32_16x16x32_bf16 v[76:79], v[150:153], v[202:205], v[76:79]
	v_mfma_f32_16x16x32_bf16 v[72:75], v[164:167], v[202:205], v[72:75]
	s_setprio 0
	s_barrier
	s_add_i32 s0, s66, s50
	s_mov_b32 m0, s0
	ds_read_b128 v[206:209], v159
	ds_read_b128 v[210:213], v159 offset:1024
	ds_read_b128 v[214:217], v159 offset:2048
	global_load_lds_dwordx4 v130, s[44:45]
	s_add_i32 m0, s0, 0x2000
	ds_read_b128 v[218:221], v159 offset:3072
	global_load_lds_dwordx4 v134, s[44:45]
	s_barrier
	s_waitcnt lgkmcnt(0)
	s_setprio 1
	v_mfma_f32_16x16x32_bf16 v[116:119], v[206:209], v[168:171], 0
	v_mfma_f32_16x16x32_bf16 v[112:115], v[214:217], v[168:171], 0
	v_mfma_f32_16x16x32_bf16 v[100:103], v[206:209], v[176:179], 0
	v_mfma_f32_16x16x32_bf16 v[96:99], v[214:217], v[176:179], 0
	v_mfma_f32_16x16x32_bf16 v[84:87], v[206:209], v[188:191], 0
	v_mfma_f32_16x16x32_bf16 v[80:83], v[214:217], v[188:191], 0
	v_mfma_f32_16x16x32_bf16 v[68:71], v[206:209], v[198:201], 0
	v_mfma_f32_16x16x32_bf16 v[64:67], v[214:217], v[198:201], 0
	v_mfma_f32_16x16x32_bf16 v[116:119], v[210:213], v[172:175], v[116:119]
	v_mfma_f32_16x16x32_bf16 v[112:115], v[218:221], v[172:175], v[112:115]
	v_mfma_f32_16x16x32_bf16 v[100:103], v[210:213], v[180:183], v[100:103]
	v_mfma_f32_16x16x32_bf16 v[96:99], v[218:221], v[180:183], v[96:99]
	v_mfma_f32_16x16x32_bf16 v[84:87], v[210:213], v[194:197], v[84:87]
	v_mfma_f32_16x16x32_bf16 v[80:83], v[218:221], v[194:197], v[80:83]
	v_mfma_f32_16x16x32_bf16 v[68:71], v[210:213], v[202:205], v[68:71]
	v_mfma_f32_16x16x32_bf16 v[64:67], v[218:221], v[202:205], v[64:67]
	s_setprio 0
	s_mov_b32 m0, s55
	s_barrier
	ds_read_b128 v[168:171], v158 offset:16384
	ds_read_b128 v[172:175], v158 offset:17408
	ds_read_b128 v[176:179], v158 offset:18432
	ds_read_b128 v[180:183], v158 offset:19456
	ds_read_b128 v[188:191], v158 offset:20480
	ds_read_b128 v[194:197], v158 offset:21504
	ds_read_b128 v[198:201], v158 offset:22528
	global_load_lds_dwordx4 v128, s[46:47]
	s_mov_b32 m0, s56
	ds_read_b128 v[202:205], v158 offset:23552
	global_load_lds_dwordx4 v132, s[46:47]
	s_barrier
	s_waitcnt lgkmcnt(0)
	s_setprio 1
	v_mfma_f32_16x16x32_bf16 v[60:63], v[146:149], v[168:171], 0
	v_mfma_f32_16x16x32_bf16 v[56:59], v[160:163], v[168:171], 0
	v_mfma_f32_16x16x32_bf16 v[44:47], v[146:149], v[176:179], 0
	v_mfma_f32_16x16x32_bf16 v[40:43], v[160:163], v[176:179], 0
	v_mfma_f32_16x16x32_bf16 v[28:31], v[146:149], v[188:191], 0
	v_mfma_f32_16x16x32_bf16 v[24:27], v[160:163], v[188:191], 0
	v_mfma_f32_16x16x32_bf16 v[12:15], v[146:149], v[198:201], 0
	v_mfma_f32_16x16x32_bf16 v[8:11], v[160:163], v[198:201], 0
	v_mfma_f32_16x16x32_bf16 v[60:63], v[150:153], v[172:175], v[60:63]
	v_mfma_f32_16x16x32_bf16 v[56:59], v[164:167], v[172:175], v[56:59]
	v_mfma_f32_16x16x32_bf16 v[44:47], v[150:153], v[180:183], v[44:47]
	v_mfma_f32_16x16x32_bf16 v[40:43], v[164:167], v[180:183], v[40:43]
	v_mfma_f32_16x16x32_bf16 v[28:31], v[150:153], v[194:197], v[28:31]
	v_mfma_f32_16x16x32_bf16 v[24:27], v[164:167], v[194:197], v[24:27]
	v_mfma_f32_16x16x32_bf16 v[12:15], v[150:153], v[202:205], v[12:15]
	v_mfma_f32_16x16x32_bf16 v[8:11], v[164:167], v[202:205], v[8:11]
	s_setprio 0
	s_barrier
; #define PG8_STAGE(bufoff, gbase, voff) do { _Pragma("unroll") for (int _i = 0; _i < 2; ++_i) \
;         __builtin_amdgcn_global_load_lds((const unsigned*)((const char*)(gbase) + (voff)[_i]), (LAS unsigned*)(lds + (bufoff) + ldsw + _i * 8192), 16, 0, 0); } while (0)
; #define PG8_LDA(dst, b, h) do { _Pragma("unroll") for (int m = 0; m < 4; ++m) _Pragma("unroll") for (int k = 0; k < 2; ++k) dst[m][k] = *(const LAS bf16x8*)(lds + PG8_SA(b, h) + aoff + m * 2048 + k * 1024); } while (0)
; #define PG8_LDB(dst, b, h) do { _Pragma("unroll") for (int n = 0; n < 2; ++n) _Pragma("unroll") for (int k = 0; k < 2; ++k) dst[n][k] = *(const LAS bf16x8*)(lds + PG8_SB(b, h) + boff + n * 2048 + k * 1024); } while (0)
; #define PG8_MMA(ai, bj, At, Bt) do { __builtin_amdgcn_s_setprio(1); _Pragma("unroll") for (int m = 0; m < 4; ++m) _Pragma("unroll") for (int n = 0; n < 2; ++n) _Pragma("unroll") for (int k = 0; k < 2; ++k) \
;         acc[ai][bj][m][n] = __builtin_amdgcn_mfma_f32_16x16x32_bf16(Bt[n][k], At[m][k], acc[ai][bj][m][n], 0, 0, 0); __builtin_amdgcn_s_setprio(0); } while (0)
; #define PG8_WAIT_V(n) asm volatile("s_waitcnt vmcnt(" #n ")" ::: "memory")
; #define PG8_WAIT_L(n) asm volatile("s_waitcnt lgkmcnt(" #n ")" ::: "memory")
; #define PG8_BAR __builtin_amdgcn_s_barrier()
; #define PG8_SCHED __builtin_amdgcn_sched_barrier(0)
; template <class Epi, class Sched>
; DI void gemm_phase(LAS unsigned char* lds, const Gemm g, const Sched& S, const Epi& E) {
;     ...
;             PG8_STAGE(PG8_SB(0, 1), b2 + hstep, voffB);
;             PG8_WAIT_V(6); PG8_BAR; PG8_MMA(1, 1, At, B1); PG8_BAR;
;             PG8_LDB(B0, 1, 0); PG8_SCHED; PG8_LDA(At, 1, 0); PG8_STAGE(PG8_SA(0, 1), a2 + hstep, voffA);
;             PG8_WAIT_L(8); PG8_BAR; PG8_WAIT_L(0); PG8_MMA(0, 0, At, B0); PG8_BAR; PG8_SCHED;
;             PG8_LDB(B1, 1, 1); PG8_STAGE(PG8_SB(1, 0), b3, voffB);
;             PG8_BAR; PG8_WAIT_L(0); PG8_MMA(0, 1, At, B1); PG8_BAR;
;             PG8_LDA(At, 1, 1); PG8_STAGE(PG8_SA(1, 0), a3, voffA);
;             PG8_BAR; PG8_WAIT_L(0); PG8_MMA(1, 0, At, B0); PG8_BAR; PG8_SCHED;
	s_add_u32 s0, s44, 0x20000
	s_addc_u32 s1, s45, 0
	s_add_i32 s4, s67, s50
	s_mov_b32 m0, s4
	s_nop 0
	global_load_lds_dwordx4 v130, s[0:1]
	s_add_i32 m0, s4, 0x2000
	s_nop 0
	global_load_lds_dwordx4 v134, s[0:1]
	s_waitcnt vmcnt(6)
	s_barrier
	s_setprio 1
	v_mfma_f32_16x16x32_bf16 v[52:55], v[206:209], v[168:171], 0
	v_mfma_f32_16x16x32_bf16 v[48:51], v[214:217], v[168:171], 0
	v_mfma_f32_16x16x32_bf16 v[36:39], v[206:209], v[176:179], 0
	v_mfma_f32_16x16x32_bf16 v[32:35], v[214:217], v[176:179], 0
	v_mfma_f32_16x16x32_bf16 v[20:23], v[206:209], v[188:191], 0
	v_mfma_f32_16x16x32_bf16 v[16:19], v[214:217], v[188:191], 0
	v_mfma_f32_16x16x32_bf16 v[4:7], v[206:209], v[198:201], 0
	v_mfma_f32_16x16x32_bf16 v[0:3], v[214:217], v[198:201], 0
	v_mfma_f32_16x16x32_bf16 v[52:55], v[210:213], v[172:175], v[52:55]
	v_mfma_f32_16x16x32_bf16 v[48:51], v[218:221], v[172:175], v[48:51]
	v_mfma_f32_16x16x32_bf16 v[36:39], v[210:213], v[180:183], v[36:39]
	v_mfma_f32_16x16x32_bf16 v[32:35], v[218:221], v[180:183], v[32:35]
	v_mfma_f32_16x16x32_bf16 v[20:23], v[210:213], v[194:197], v[20:23]
	v_mfma_f32_16x16x32_bf16 v[16:19], v[218:221], v[194:197], v[16:19]
	v_mfma_f32_16x16x32_bf16 v[4:7], v[210:213], v[202:205], v[4:7]
	v_mfma_f32_16x16x32_bf16 v[0:3], v[218:221], v[202:205], v[0:3]
	s_setprio 0
	s_add_i32 s4, 0, 0x18000
	v_add_u32_e32 v222, s4, v157
	s_barrier
	ds_read_b128 v[146:149], v222
	ds_read_b128 v[150:153], v222 offset:1024
	ds_read_b128 v[160:163], v222 offset:2048
	ds_read_b128 v[164:167], v222 offset:3072
	s_add_u32 s0, s46, 0x20000
	s_addc_u32 s1, s47, 0
	s_mov_b32 m0, s57
	ds_read_b128 v[168:171], v158 offset:32768
	ds_read_b128 v[172:175], v158 offset:33792
	ds_read_b128 v[176:179], v158 offset:34816
	ds_read_b128 v[180:183], v158 offset:35840
	ds_read_b128 v[188:191], v158 offset:36864
	ds_read_b128 v[194:197], v158 offset:37888
	ds_read_b128 v[198:201], v158 offset:38912
	global_load_lds_dwordx4 v128, s[0:1]
	s_mov_b32 m0, s58
	ds_read_b128 v[202:205], v158 offset:39936
	global_load_lds_dwordx4 v132, s[0:1]
	s_waitcnt lgkmcnt(8)
	s_barrier
	s_waitcnt lgkmcnt(0)
	s_setprio 1
	v_mfma_f32_16x16x32_bf16 v[124:127], v[146:149], v[168:171], v[124:127]
	v_mfma_f32_16x16x32_bf16 v[120:123], v[160:163], v[168:171], v[120:123]
	v_mfma_f32_16x16x32_bf16 v[108:111], v[146:149], v[176:179], v[108:111]
	v_mfma_f32_16x16x32_bf16 v[104:107], v[160:163], v[176:179], v[104:107]
	v_mfma_f32_16x16x32_bf16 v[92:95], v[146:149], v[188:191], v[92:95]
	v_mfma_f32_16x16x32_bf16 v[88:91], v[160:163], v[188:191], v[88:91]
	v_mfma_f32_16x16x32_bf16 v[76:79], v[146:149], v[198:201], v[76:79]
	v_mfma_f32_16x16x32_bf16 v[72:75], v[160:163], v[198:201], v[72:75]
	v_mfma_f32_16x16x32_bf16 v[124:127], v[150:153], v[172:175], v[124:127]
	v_mfma_f32_16x16x32_bf16 v[120:123], v[164:167], v[172:175], v[120:123]
	v_mfma_f32_16x16x32_bf16 v[108:111], v[150:153], v[180:183], v[108:111]
	v_mfma_f32_16x16x32_bf16 v[104:107], v[164:167], v[180:183], v[104:107]
	v_mfma_f32_16x16x32_bf16 v[92:95], v[150:153], v[194:197], v[92:95]
	v_mfma_f32_16x16x32_bf16 v[88:91], v[164:167], v[194:197], v[88:91]
	v_mfma_f32_16x16x32_bf16 v[76:79], v[150:153], v[202:205], v[76:79]
	v_mfma_f32_16x16x32_bf16 v[72:75], v[164:167], v[202:205], v[72:75]
	s_setprio 0
	s_barrier
	s_add_i32 s5, 0, 0x1c000
	s_add_i32 s0, s4, s50
	v_add_u32_e32 v223, s5, v157
	s_add_i32 m0, s0, 0xffffff80
	ds_read_b128 v[206:209], v223
	ds_read_b128 v[210:213], v223 offset:1024
	ds_read_b128 v[214:217], v223 offset:2048
	global_load_lds_dwordx4 v130, s[44:45] offset:128
	s_add_i32 m0, s0, 0x1f80
	ds_read_b128 v[218:221], v223 offset:3072
	global_load_lds_dwordx4 v134, s[44:45] offset:128
	s_barrier
	s_waitcnt lgkmcnt(0)
	s_setprio 1
	v_mfma_f32_16x16x32_bf16 v[116:119], v[206:209], v[168:171], v[116:119]
	v_mfma_f32_16x16x32_bf16 v[112:115], v[214:217], v[168:171], v[112:115]
	v_mfma_f32_16x16x32_bf16 v[100:103], v[206:209], v[176:179], v[100:103]
	v_mfma_f32_16x16x32_bf16 v[96:99], v[214:217], v[176:179], v[96:99]
	v_mfma_f32_16x16x32_bf16 v[84:87], v[206:209], v[188:191], v[84:87]
	v_mfma_f32_16x16x32_bf16 v[80:83], v[214:217], v[188:191], v[80:83]
	v_mfma_f32_16x16x32_bf16 v[68:71], v[206:209], v[198:201], v[68:71]
	v_mfma_f32_16x16x32_bf16 v[64:67], v[214:217], v[198:201], v[64:67]
	v_mfma_f32_16x16x32_bf16 v[116:119], v[210:213], v[172:175], v[116:119]
	v_mfma_f32_16x16x32_bf16 v[112:115], v[218:221], v[172:175], v[112:115]
	v_mfma_f32_16x16x32_bf16 v[100:103], v[210:213], v[180:183], v[100:103]
	v_mfma_f32_16x16x32_bf16 v[96:99], v[218:221], v[180:183], v[96:99]
	v_mfma_f32_16x16x32_bf16 v[84:87], v[210:213], v[194:197], v[84:87]
	v_mfma_f32_16x16x32_bf16 v[80:83], v[218:221], v[194:197], v[80:83]
	v_mfma_f32_16x16x32_bf16 v[68:71], v[210:213], v[202:205], v[68:71]
	v_mfma_f32_16x16x32_bf16 v[64:67], v[218:221], v[202:205], v[64:67]
	s_setprio 0
	s_add_i32 m0, s62, 0xffffff80
	s_barrier
	ds_read_b128 v[168:171], v158 offset:49152
	ds_read_b128 v[172:175], v158 offset:50176
	ds_read_b128 v[176:179], v158 offset:51200
	ds_read_b128 v[180:183], v158 offset:52224
	ds_read_b128 v[188:191], v158 offset:53248
	ds_read_b128 v[194:197], v158 offset:54272
	ds_read_b128 v[198:201], v158 offset:55296
	global_load_lds_dwordx4 v128, s[46:47] offset:128
	s_add_i32 m0, s63, 0xffffff80
	ds_read_b128 v[202:205], v158 offset:56320
	global_load_lds_dwordx4 v132, s[46:47] offset:128
	s_barrier
; #define PG8_STAGE(bufoff, gbase, voff) do { _Pragma("unroll") for (int _i = 0; _i < 2; ++_i) \
;         __builtin_amdgcn_global_load_lds((const unsigned*)((const char*)(gbase) + (voff)[_i]), (LAS unsigned*)(lds + (bufoff) + ldsw + _i * 8192), 16, 0, 0); } while (0)
; #define PG8_LDA(dst, b, h) do { _Pragma("unroll") for (int m = 0; m < 4; ++m) _Pragma("unroll") for (int k = 0; k < 2; ++k) dst[m][k] = *(const LAS bf16x8*)(lds + PG8_SA(b, h) + aoff + m * 2048 + k * 1024); } while (0)
; #define PG8_LDB(dst, b, h) do { _Pragma("unroll") for (int n = 0; n < 2; ++n) _Pragma("unroll") for (int k = 0; k < 2; ++k) dst[n][k] = *(const LAS bf16x8*)(lds + PG8_SB(b, h) + boff + n * 2048 + k * 1024); } while (0)
; #define PG8_MMA(ai, bj, At, Bt) do { __builtin_amdgcn_s_setprio(1); _Pragma("unroll") for (int m = 0; m < 4; ++m) _Pragma("unroll") for (int n = 0; n < 2; ++n) _Pragma("unroll") for (int k = 0; k < 2; ++k) \
;         acc[ai][bj][m][n] = __builtin_amdgcn_mfma_f32_16x16x32_bf16(Bt[n][k], At[m][k], acc[ai][bj][m][n], 0, 0, 0); __builtin_amdgcn_s_setprio(0); } while (0)
; #define PG8_WAIT_V(n) asm volatile("s_waitcnt vmcnt(" #n ")" ::: "memory")
; #define PG8_WAIT_L(n) asm volatile("s_waitcnt lgkmcnt(" #n ")" ::: "memory")
; #define PG8_BAR __builtin_amdgcn_s_barrier()
; #define PG8_SCHED __builtin_amdgcn_sched_barrier(0)
; template <class Epi, class Sched>
; DI void gemm_phase(LAS unsigned char* lds, const Gemm g, const Sched& S, const Epi& E) {
;     ...
;             const bool last = (t == nt - 2);
;             const char* a1 = cA + (size_t)(t + 1) * kstep;
;             const char* a2 = last ? nA : cA + (size_t)(t + 2) * kstep; const char* b2 = last ? nB : cB + (size_t)(t + 2) * kstep;
;             const char* a3 = a2 + kstep; const char* b3 = b2 + kstep;
;             PG8_LDB(B0, 0, 0); PG8_SCHED; PG8_LDA(At, 0, 0); PG8_STAGE(PG8_SA(1, 1), a1 + hstep, voffA);
;             PG8_WAIT_L(8); PG8_BAR; PG8_WAIT_L(0); PG8_MMA(0, 0, At, B0); PG8_BAR; PG8_SCHED;
;             PG8_LDB(B1, 0, 1); PG8_STAGE(PG8_SB(0, 0), b2, voffB);
;     ...
;             PG8_BAR; PG8_WAIT_L(0); PG8_MMA(1, 0, At, B0); PG8_BAR; PG8_SCHED;
;             PG8_STAGE(PG8_SB(1, 1), b3 + hstep, voffB);
;             PG8_WAIT_V(6); PG8_BAR; PG8_MMA(1, 1, At, B1); PG8_BAR;
	s_waitcnt lgkmcnt(0)
	s_setprio 1
	v_mfma_f32_16x16x32_bf16 v[60:63], v[146:149], v[168:171], v[60:63]
	v_mfma_f32_16x16x32_bf16 v[56:59], v[160:163], v[168:171], v[56:59]
	v_mfma_f32_16x16x32_bf16 v[44:47], v[146:149], v[176:179], v[44:47]
	v_mfma_f32_16x16x32_bf16 v[40:43], v[160:163], v[176:179], v[40:43]
	v_mfma_f32_16x16x32_bf16 v[28:31], v[146:149], v[188:191], v[28:31]
	v_mfma_f32_16x16x32_bf16 v[24:27], v[160:163], v[188:191], v[24:27]
	v_mfma_f32_16x16x32_bf16 v[12:15], v[146:149], v[198:201], v[12:15]
	v_mfma_f32_16x16x32_bf16 v[8:11], v[160:163], v[198:201], v[8:11]
	v_mfma_f32_16x16x32_bf16 v[60:63], v[150:153], v[172:175], v[60:63]
	v_mfma_f32_16x16x32_bf16 v[56:59], v[164:167], v[172:175], v[56:59]
	v_mfma_f32_16x16x32_bf16 v[44:47], v[150:153], v[180:183], v[44:47]
	v_mfma_f32_16x16x32_bf16 v[40:43], v[164:167], v[180:183], v[40:43]
	v_mfma_f32_16x16x32_bf16 v[28:31], v[150:153], v[194:197], v[28:31]
	v_mfma_f32_16x16x32_bf16 v[24:27], v[164:167], v[194:197], v[24:27]
	v_mfma_f32_16x16x32_bf16 v[12:15], v[150:153], v[202:205], v[12:15]
	v_mfma_f32_16x16x32_bf16 v[8:11], v[164:167], v[202:205], v[8:11]
	s_setprio 0
	s_barrier
	s_add_u32 s0, s44, 0x20080
	s_addc_u32 s1, s45, 0
	s_add_i32 s4, s5, s50
	s_mov_b32 m0, s4
	s_nop 0
	global_load_lds_dwordx4 v130, s[0:1]
	v_lshl_add_u64 v[146:147], s[0:1], 0, v[134:135]
	s_add_i32 m0, s4, 0x2000
	s_nop 0
	global_load_lds_dwordx4 v134, s[0:1]
	s_waitcnt vmcnt(6)
	s_barrier
	s_setprio 1
	v_mfma_f32_16x16x32_bf16 v[52:55], v[206:209], v[168:171], v[52:55]
	v_mfma_f32_16x16x32_bf16 v[48:51], v[214:217], v[168:171], v[48:51]
	v_mfma_f32_16x16x32_bf16 v[36:39], v[206:209], v[176:179], v[36:39]
	v_mfma_f32_16x16x32_bf16 v[32:35], v[214:217], v[176:179], v[32:35]
	v_mfma_f32_16x16x32_bf16 v[20:23], v[206:209], v[188:191], v[20:23]
	v_mfma_f32_16x16x32_bf16 v[16:19], v[214:217], v[188:191], v[16:19]
	v_mfma_f32_16x16x32_bf16 v[4:7], v[206:209], v[198:201], v[4:7]
	v_mfma_f32_16x16x32_bf16 v[0:3], v[214:217], v[198:201], v[0:3]
	v_mfma_f32_16x16x32_bf16 v[52:55], v[210:213], v[172:175], v[52:55]
	v_mfma_f32_16x16x32_bf16 v[48:51], v[218:221], v[172:175], v[48:51]
	v_mfma_f32_16x16x32_bf16 v[36:39], v[210:213], v[180:183], v[36:39]
	v_mfma_f32_16x16x32_bf16 v[32:35], v[218:221], v[180:183], v[32:35]
	v_mfma_f32_16x16x32_bf16 v[20:23], v[210:213], v[194:197], v[20:23]
	v_mfma_f32_16x16x32_bf16 v[16:19], v[218:221], v[194:197], v[16:19]
	v_mfma_f32_16x16x32_bf16 v[4:7], v[210:213], v[202:205], v[4:7]
	v_mfma_f32_16x16x32_bf16 v[0:3], v[218:221], v[202:205], v[0:3]
	s_setprio 0
	s_add_i32 s79, s79, 2
	s_add_u32 s42, s42, 0x100
	s_addc_u32 s43, s43, 0
	s_add_u32 s35, s35, 0x100
	s_addc_u32 s41, s41, 0
	s_cmp_gt_u32 s79, 5
	s_barrier
	s_cbranch_scc0 .LBB0_984
	s_branch .Lpeel_done_984
.LBB0_984:
	ds_read_b128 v[146:149], v156
	ds_read_b128 v[150:153], v156 offset:1024
	ds_read_b128 v[160:163], v156 offset:2048
	ds_read_b128 v[164:167], v156 offset:3072
	s_add_u32 s0, s42, 0xfffe0080
	s_addc_u32 s1, s43, -1
	s_cmp_eq_u32 s79, 4
	s_cselect_b32 s47, s9, s1
	s_cselect_b32 s46, s31, s0
	s_cselect_b32 s45, s29, s41
	s_cselect_b32 s44, s34, s35
	s_add_i32 m0, s55, 0xc000
	ds_read_b128 v[168:171], v158
	ds_read_b128 v[172:175], v158 offset:1024
	ds_read_b128 v[176:179], v158 offset:2048
	ds_read_b128 v[180:183], v158 offset:3072
	ds_read_b128 v[188:191], v158 offset:4096
	ds_read_b128 v[194:197], v158 offset:5120
	ds_read_b128 v[198:201], v158 offset:6144
	global_load_lds_dwordx4 v138, s[42:43]
	s_add_i32 m0, s55, 0xe000
	ds_read_b128 v[202:205], v158 offset:7168
	global_load_lds_dwordx4 v140, s[42:43]
	s_waitcnt lgkmcnt(8)
	s_barrier
	s_waitcnt lgkmcnt(0)
	s_setprio 1
	v_mfma_f32_16x16x32_bf16 v[124:127], v[146:149], v[168:171], v[124:127]
	v_mfma_f32_16x16x32_bf16 v[120:123], v[160:163], v[168:171], v[120:123]
	v_mfma_f32_16x16x32_bf16 v[108:111], v[146:149], v[176:179], v[108:111]
	v_mfma_f32_16x16x32_bf16 v[104:107], v[160:163], v[176:179], v[104:107]
	v_mfma_f32_16x16x32_bf16 v[92:95], v[146:149], v[188:191], v[92:95]
	v_mfma_f32_16x16x32_bf16 v[88:91], v[160:163], v[188:191], v[88:91]
	v_mfma_f32_16x16x32_bf16 v[76:79], v[146:149], v[198:201], v[76:79]
	v_mfma_f32_16x16x32_bf16 v[72:75], v[160:163], v[198:201], v[72:75]
	v_mfma_f32_16x16x32_bf16 v[124:127], v[150:153], v[172:175], v[124:127]
	v_mfma_f32_16x16x32_bf16 v[120:123], v[164:167], v[172:175], v[120:123]
	v_mfma_f32_16x16x32_bf16 v[108:111], v[150:153], v[180:183], v[108:111]
	v_mfma_f32_16x16x32_bf16 v[104:107], v[164:167], v[180:183], v[104:107]
	v_mfma_f32_16x16x32_bf16 v[92:95], v[150:153], v[194:197], v[92:95]
	v_mfma_f32_16x16x32_bf16 v[88:91], v[164:167], v[194:197], v[88:91]
	v_mfma_f32_16x16x32_bf16 v[76:79], v[150:153], v[202:205], v[76:79]
	v_mfma_f32_16x16x32_bf16 v[72:75], v[164:167], v[202:205], v[72:75]
	s_setprio 0
	s_barrier
	s_add_i32 s0, s66, s50
	s_mov_b32 m0, s0
	ds_read_b128 v[206:209], v159
	ds_read_b128 v[210:213], v159 offset:1024
	ds_read_b128 v[214:217], v159 offset:2048
	global_load_lds_dwordx4 v130, s[44:45]
	s_add_i32 m0, s0, 0x2000
	ds_read_b128 v[218:221], v159 offset:3072
	global_load_lds_dwordx4 v134, s[44:45]
	s_barrier
; #define PG8_STAGE(bufoff, gbase, voff) do { _Pragma("unroll") for (int _i = 0; _i < 2; ++_i) \
;         __builtin_amdgcn_global_load_lds((const unsigned*)((const char*)(gbase) + (voff)[_i]), (LAS unsigned*)(lds + (bufoff) + ldsw + _i * 8192), 16, 0, 0); } while (0)
; #define PG8_LDA(dst, b, h) do { _Pragma("unroll") for (int m = 0; m < 4; ++m) _Pragma("unroll") for (int k = 0; k < 2; ++k) dst[m][k] = *(const LAS bf16x8*)(lds + PG8_SA(b, h) + aoff + m * 2048 + k * 1024); } while (0)
; #define PG8_LDB(dst, b, h) do { _Pragma("unroll") for (int n = 0; n < 2; ++n) _Pragma("unroll") for (int k = 0; k < 2; ++k) dst[n][k] = *(const LAS bf16x8*)(lds + PG8_SB(b, h) + boff + n * 2048 + k * 1024); } while (0)
; #define PG8_MMA(ai, bj, At, Bt) do { __builtin_amdgcn_s_setprio(1); _Pragma("unroll") for (int m = 0; m < 4; ++m) _Pragma("unroll") for (int n = 0; n < 2; ++n) _Pragma("unroll") for (int k = 0; k < 2; ++k) \
;         acc[ai][bj][m][n] = __builtin_amdgcn_mfma_f32_16x16x32_bf16(Bt[n][k], At[m][k], acc[ai][bj][m][n], 0, 0, 0); __builtin_amdgcn_s_setprio(0); } while (0)
; #define PG8_WAIT_V(n) asm volatile("s_waitcnt vmcnt(" #n ")" ::: "memory")
; #define PG8_WAIT_L(n) asm volatile("s_waitcnt lgkmcnt(" #n ")" ::: "memory")
; #define PG8_BAR __builtin_amdgcn_s_barrier()
; #define PG8_SCHED __builtin_amdgcn_sched_barrier(0)
; template <class Epi, class Sched>
; DI void gemm_phase(LAS unsigned char* lds, const Gemm g, const Sched& S, const Epi& E) {
;     ...
;             PG8_BAR; PG8_WAIT_L(0); PG8_MMA(0, 1, At, B1); PG8_BAR;
;             PG8_LDA(At, 0, 1); PG8_STAGE(PG8_SA(0, 0), a2, voffA);
;             PG8_BAR; PG8_WAIT_L(0); PG8_MMA(1, 0, At, B0); PG8_BAR; PG8_SCHED;
;             PG8_STAGE(PG8_SB(0, 1), b2 + hstep, voffB);
;             PG8_WAIT_V(6); PG8_BAR; PG8_MMA(1, 1, At, B1); PG8_BAR;
;             PG8_LDB(B0, 1, 0); PG8_SCHED; PG8_LDA(At, 1, 0); PG8_STAGE(PG8_SA(0, 1), a2 + hstep, voffA);
;             PG8_WAIT_L(8); PG8_BAR; PG8_WAIT_L(0); PG8_MMA(0, 0, At, B0); PG8_BAR; PG8_SCHED;
	s_waitcnt lgkmcnt(0)
	s_setprio 1
	v_mfma_f32_16x16x32_bf16 v[116:119], v[206:209], v[168:171], v[116:119]
	v_mfma_f32_16x16x32_bf16 v[112:115], v[214:217], v[168:171], v[112:115]
	v_mfma_f32_16x16x32_bf16 v[100:103], v[206:209], v[176:179], v[100:103]
	v_mfma_f32_16x16x32_bf16 v[96:99], v[214:217], v[176:179], v[96:99]
	v_mfma_f32_16x16x32_bf16 v[84:87], v[206:209], v[188:191], v[84:87]
	v_mfma_f32_16x16x32_bf16 v[80:83], v[214:217], v[188:191], v[80:83]
	v_mfma_f32_16x16x32_bf16 v[68:71], v[206:209], v[198:201], v[68:71]
	v_mfma_f32_16x16x32_bf16 v[64:67], v[214:217], v[198:201], v[64:67]
	v_mfma_f32_16x16x32_bf16 v[116:119], v[210:213], v[172:175], v[116:119]
	v_mfma_f32_16x16x32_bf16 v[112:115], v[218:221], v[172:175], v[112:115]
	v_mfma_f32_16x16x32_bf16 v[100:103], v[210:213], v[180:183], v[100:103]
	v_mfma_f32_16x16x32_bf16 v[96:99], v[218:221], v[180:183], v[96:99]
	v_mfma_f32_16x16x32_bf16 v[84:87], v[210:213], v[194:197], v[84:87]
	v_mfma_f32_16x16x32_bf16 v[80:83], v[218:221], v[194:197], v[80:83]
	v_mfma_f32_16x16x32_bf16 v[68:71], v[210:213], v[202:205], v[68:71]
	v_mfma_f32_16x16x32_bf16 v[64:67], v[218:221], v[202:205], v[64:67]
	s_setprio 0
	s_mov_b32 m0, s55
	s_barrier
	ds_read_b128 v[168:171], v158 offset:16384
	ds_read_b128 v[172:175], v158 offset:17408
	ds_read_b128 v[176:179], v158 offset:18432
	ds_read_b128 v[180:183], v158 offset:19456
	ds_read_b128 v[188:191], v158 offset:20480
	ds_read_b128 v[194:197], v158 offset:21504
	ds_read_b128 v[198:201], v158 offset:22528
	global_load_lds_dwordx4 v128, s[46:47]
	s_mov_b32 m0, s56
	ds_read_b128 v[202:205], v158 offset:23552
	global_load_lds_dwordx4 v132, s[46:47]
	s_barrier
	s_waitcnt lgkmcnt(0)
	s_setprio 1
	v_mfma_f32_16x16x32_bf16 v[60:63], v[146:149], v[168:171], v[60:63]
	v_mfma_f32_16x16x32_bf16 v[56:59], v[160:163], v[168:171], v[56:59]
	v_mfma_f32_16x16x32_bf16 v[44:47], v[146:149], v[176:179], v[44:47]
	v_mfma_f32_16x16x32_bf16 v[40:43], v[160:163], v[176:179], v[40:43]
	v_mfma_f32_16x16x32_bf16 v[28:31], v[146:149], v[188:191], v[28:31]
	v_mfma_f32_16x16x32_bf16 v[24:27], v[160:163], v[188:191], v[24:27]
	v_mfma_f32_16x16x32_bf16 v[12:15], v[146:149], v[198:201], v[12:15]
	v_mfma_f32_16x16x32_bf16 v[8:11], v[160:163], v[198:201], v[8:11]
	v_mfma_f32_16x16x32_bf16 v[60:63], v[150:153], v[172:175], v[60:63]
	v_mfma_f32_16x16x32_bf16 v[56:59], v[164:167], v[172:175], v[56:59]
	v_mfma_f32_16x16x32_bf16 v[44:47], v[150:153], v[180:183], v[44:47]
	v_mfma_f32_16x16x32_bf16 v[40:43], v[164:167], v[180:183], v[40:43]
	v_mfma_f32_16x16x32_bf16 v[28:31], v[150:153], v[194:197], v[28:31]
	v_mfma_f32_16x16x32_bf16 v[24:27], v[164:167], v[194:197], v[24:27]
	v_mfma_f32_16x16x32_bf16 v[12:15], v[150:153], v[202:205], v[12:15]
	v_mfma_f32_16x16x32_bf16 v[8:11], v[164:167], v[202:205], v[8:11]
	s_setprio 0
	s_barrier
	s_add_u32 s0, s44, 0x20000
	s_addc_u32 s1, s45, 0
	s_add_i32 s4, s67, s50
	s_mov_b32 m0, s4
	s_nop 0
	global_load_lds_dwordx4 v130, s[0:1]
	s_add_i32 m0, s4, 0x2000
	s_nop 0
	global_load_lds_dwordx4 v134, s[0:1]
	s_waitcnt vmcnt(6)
	s_barrier
	s_setprio 1
	v_mfma_f32_16x16x32_bf16 v[52:55], v[206:209], v[168:171], v[52:55]
	v_mfma_f32_16x16x32_bf16 v[48:51], v[214:217], v[168:171], v[48:51]
	v_mfma_f32_16x16x32_bf16 v[36:39], v[206:209], v[176:179], v[36:39]
	v_mfma_f32_16x16x32_bf16 v[32:35], v[214:217], v[176:179], v[32:35]
	v_mfma_f32_16x16x32_bf16 v[20:23], v[206:209], v[188:191], v[20:23]
	v_mfma_f32_16x16x32_bf16 v[16:19], v[214:217], v[188:191], v[16:19]
	v_mfma_f32_16x16x32_bf16 v[4:7], v[206:209], v[198:201], v[4:7]
	v_mfma_f32_16x16x32_bf16 v[0:3], v[214:217], v[198:201], v[0:3]
	v_mfma_f32_16x16x32_bf16 v[52:55], v[210:213], v[172:175], v[52:55]
	v_mfma_f32_16x16x32_bf16 v[48:51], v[218:221], v[172:175], v[48:51]
	v_mfma_f32_16x16x32_bf16 v[36:39], v[210:213], v[180:183], v[36:39]
	v_mfma_f32_16x16x32_bf16 v[32:35], v[218:221], v[180:183], v[32:35]
	v_mfma_f32_16x16x32_bf16 v[20:23], v[210:213], v[194:197], v[20:23]
	v_mfma_f32_16x16x32_bf16 v[16:19], v[218:221], v[194:197], v[16:19]
	v_mfma_f32_16x16x32_bf16 v[4:7], v[210:213], v[202:205], v[4:7]
	v_mfma_f32_16x16x32_bf16 v[0:3], v[218:221], v[202:205], v[0:3]
	s_setprio 0
	s_add_i32 s4, 0, 0x18000
	s_barrier
	ds_read_b128 v[146:149], v222
	ds_read_b128 v[150:153], v222 offset:1024
	ds_read_b128 v[160:163], v222 offset:2048
	ds_read_b128 v[164:167], v222 offset:3072
	s_add_u32 s0, s46, 0x20000
	s_addc_u32 s1, s47, 0
	s_mov_b32 m0, s57
	ds_read_b128 v[168:171], v158 offset:32768
	ds_read_b128 v[172:175], v158 offset:33792
	ds_read_b128 v[176:179], v158 offset:34816
	ds_read_b128 v[180:183], v158 offset:35840
	ds_read_b128 v[188:191], v158 offset:36864
	ds_read_b128 v[194:197], v158 offset:37888
	ds_read_b128 v[198:201], v158 offset:38912
	global_load_lds_dwordx4 v128, s[0:1]
	s_mov_b32 m0, s58
	ds_read_b128 v[202:205], v158 offset:39936
	global_load_lds_dwordx4 v132, s[0:1]
	s_waitcnt lgkmcnt(8)
	s_barrier
; #define PG8_STAGE(bufoff, gbase, voff) do { _Pragma("unroll") for (int _i = 0; _i < 2; ++_i) \
;         __builtin_amdgcn_global_load_lds((const unsigned*)((const char*)(gbase) + (voff)[_i]), (LAS unsigned*)(lds + (bufoff) + ldsw + _i * 8192), 16, 0, 0); } while (0)
; #define PG8_LDA(dst, b, h) do { _Pragma("unroll") for (int m = 0; m < 4; ++m) _Pragma("unroll") for (int k = 0; k < 2; ++k) dst[m][k] = *(const LAS bf16x8*)(lds + PG8_SA(b, h) + aoff + m * 2048 + k * 1024); } while (0)
; #define PG8_LDB(dst, b, h) do { _Pragma("unroll") for (int n = 0; n < 2; ++n) _Pragma("unroll") for (int k = 0; k < 2; ++k) dst[n][k] = *(const LAS bf16x8*)(lds + PG8_SB(b, h) + boff + n * 2048 + k * 1024); } while (0)
; #define PG8_MMA(ai, bj, At, Bt) do { __builtin_amdgcn_s_setprio(1); _Pragma("unroll") for (int m = 0; m < 4; ++m) _Pragma("unroll") for (int n = 0; n < 2; ++n) _Pragma("unroll") for (int k = 0; k < 2; ++k) \
;         acc[ai][bj][m][n] = __builtin_amdgcn_mfma_f32_16x16x32_bf16(Bt[n][k], At[m][k], acc[ai][bj][m][n], 0, 0, 0); __builtin_amdgcn_s_setprio(0); } while (0)
; #define PG8_WAIT_V(n) asm volatile("s_waitcnt vmcnt(" #n ")" ::: "memory")
; #define PG8_WAIT_L(n) asm volatile("s_waitcnt lgkmcnt(" #n ")" ::: "memory")
; #define PG8_BAR __builtin_amdgcn_s_barrier()
; #define PG8_SCHED __builtin_amdgcn_sched_barrier(0)
; template <class Epi, class Sched>
; DI void gemm_phase(LAS unsigned char* lds, const Gemm g, const Sched& S, const Epi& E) {
;     ...
;             PG8_WAIT_L(8); PG8_BAR; PG8_WAIT_L(0); PG8_MMA(0, 0, At, B0); PG8_BAR; PG8_SCHED;
;             PG8_LDB(B1, 1, 1); PG8_STAGE(PG8_SB(1, 0), b3, voffB);
;             PG8_BAR; PG8_WAIT_L(0); PG8_MMA(0, 1, At, B1); PG8_BAR;
;             PG8_LDA(At, 1, 1); PG8_STAGE(PG8_SA(1, 0), a3, voffA);
;             PG8_BAR; PG8_WAIT_L(0); PG8_MMA(1, 0, At, B0); PG8_BAR; PG8_SCHED;
;             PG8_STAGE(PG8_SB(1, 1), b3 + hstep, voffB);
;             PG8_WAIT_V(6); PG8_BAR; PG8_MMA(1, 1, At, B1); PG8_BAR;
	s_waitcnt lgkmcnt(0)
	s_setprio 1
	v_mfma_f32_16x16x32_bf16 v[124:127], v[146:149], v[168:171], v[124:127]
	v_mfma_f32_16x16x32_bf16 v[120:123], v[160:163], v[168:171], v[120:123]
	v_mfma_f32_16x16x32_bf16 v[108:111], v[146:149], v[176:179], v[108:111]
	v_mfma_f32_16x16x32_bf16 v[104:107], v[160:163], v[176:179], v[104:107]
	v_mfma_f32_16x16x32_bf16 v[92:95], v[146:149], v[188:191], v[92:95]
	v_mfma_f32_16x16x32_bf16 v[88:91], v[160:163], v[188:191], v[88:91]
	v_mfma_f32_16x16x32_bf16 v[76:79], v[146:149], v[198:201], v[76:79]
	v_mfma_f32_16x16x32_bf16 v[72:75], v[160:163], v[198:201], v[72:75]
	v_mfma_f32_16x16x32_bf16 v[124:127], v[150:153], v[172:175], v[124:127]
	v_mfma_f32_16x16x32_bf16 v[120:123], v[164:167], v[172:175], v[120:123]
	v_mfma_f32_16x16x32_bf16 v[108:111], v[150:153], v[180:183], v[108:111]
	v_mfma_f32_16x16x32_bf16 v[104:107], v[164:167], v[180:183], v[104:107]
	v_mfma_f32_16x16x32_bf16 v[92:95], v[150:153], v[194:197], v[92:95]
	v_mfma_f32_16x16x32_bf16 v[88:91], v[164:167], v[194:197], v[88:91]
	v_mfma_f32_16x16x32_bf16 v[76:79], v[150:153], v[202:205], v[76:79]
	v_mfma_f32_16x16x32_bf16 v[72:75], v[164:167], v[202:205], v[72:75]
	s_setprio 0
	s_barrier
	s_add_i32 s5, 0, 0x1c000
	s_add_i32 s0, s4, s50
	s_add_i32 m0, s0, 0xffffff80
	ds_read_b128 v[206:209], v223
	ds_read_b128 v[210:213], v223 offset:1024
	ds_read_b128 v[214:217], v223 offset:2048
	global_load_lds_dwordx4 v130, s[44:45] offset:128
	s_add_i32 m0, s0, 0x1f80
	ds_read_b128 v[218:221], v223 offset:3072
	global_load_lds_dwordx4 v134, s[44:45] offset:128
	s_barrier
	s_waitcnt lgkmcnt(0)
	s_setprio 1
	v_mfma_f32_16x16x32_bf16 v[116:119], v[206:209], v[168:171], v[116:119]
	v_mfma_f32_16x16x32_bf16 v[112:115], v[214:217], v[168:171], v[112:115]
	v_mfma_f32_16x16x32_bf16 v[100:103], v[206:209], v[176:179], v[100:103]
	v_mfma_f32_16x16x32_bf16 v[96:99], v[214:217], v[176:179], v[96:99]
	v_mfma_f32_16x16x32_bf16 v[84:87], v[206:209], v[188:191], v[84:87]
	v_mfma_f32_16x16x32_bf16 v[80:83], v[214:217], v[188:191], v[80:83]
	v_mfma_f32_16x16x32_bf16 v[68:71], v[206:209], v[198:201], v[68:71]
	v_mfma_f32_16x16x32_bf16 v[64:67], v[214:217], v[198:201], v[64:67]
	v_mfma_f32_16x16x32_bf16 v[116:119], v[210:213], v[172:175], v[116:119]
	v_mfma_f32_16x16x32_bf16 v[112:115], v[218:221], v[172:175], v[112:115]
	v_mfma_f32_16x16x32_bf16 v[100:103], v[210:213], v[180:183], v[100:103]
	v_mfma_f32_16x16x32_bf16 v[96:99], v[218:221], v[180:183], v[96:99]
	v_mfma_f32_16x16x32_bf16 v[84:87], v[210:213], v[194:197], v[84:87]
	v_mfma_f32_16x16x32_bf16 v[80:83], v[218:221], v[194:197], v[80:83]
	v_mfma_f32_16x16x32_bf16 v[68:71], v[210:213], v[202:205], v[68:71]
	v_mfma_f32_16x16x32_bf16 v[64:67], v[218:221], v[202:205], v[64:67]
	s_setprio 0
	s_add_i32 m0, s62, 0xffffff80
	s_barrier
	ds_read_b128 v[168:171], v158 offset:49152
	ds_read_b128 v[172:175], v158 offset:50176
	ds_read_b128 v[176:179], v158 offset:51200
	ds_read_b128 v[180:183], v158 offset:52224
	ds_read_b128 v[188:191], v158 offset:53248
	ds_read_b128 v[194:197], v158 offset:54272
	ds_read_b128 v[198:201], v158 offset:55296
	global_load_lds_dwordx4 v128, s[46:47] offset:128
	s_add_i32 m0, s63, 0xffffff80
	ds_read_b128 v[202:205], v158 offset:56320
	global_load_lds_dwordx4 v132, s[46:47] offset:128
	s_barrier
	s_waitcnt lgkmcnt(0)
	s_setprio 1
	v_mfma_f32_16x16x32_bf16 v[60:63], v[146:149], v[168:171], v[60:63]
	v_mfma_f32_16x16x32_bf16 v[56:59], v[160:163], v[168:171], v[56:59]
	v_mfma_f32_16x16x32_bf16 v[44:47], v[146:149], v[176:179], v[44:47]
	v_mfma_f32_16x16x32_bf16 v[40:43], v[160:163], v[176:179], v[40:43]
	v_mfma_f32_16x16x32_bf16 v[28:31], v[146:149], v[188:191], v[28:31]
	v_mfma_f32_16x16x32_bf16 v[24:27], v[160:163], v[188:191], v[24:27]
	v_mfma_f32_16x16x32_bf16 v[12:15], v[146:149], v[198:201], v[12:15]
	v_mfma_f32_16x16x32_bf16 v[8:11], v[160:163], v[198:201], v[8:11]
	v_mfma_f32_16x16x32_bf16 v[60:63], v[150:153], v[172:175], v[60:63]
	v_mfma_f32_16x16x32_bf16 v[56:59], v[164:167], v[172:175], v[56:59]
	v_mfma_f32_16x16x32_bf16 v[44:47], v[150:153], v[180:183], v[44:47]
	v_mfma_f32_16x16x32_bf16 v[40:43], v[164:167], v[180:183], v[40:43]
	v_mfma_f32_16x16x32_bf16 v[28:31], v[150:153], v[194:197], v[28:31]
	v_mfma_f32_16x16x32_bf16 v[24:27], v[164:167], v[194:197], v[24:27]
	v_mfma_f32_16x16x32_bf16 v[12:15], v[150:153], v[202:205], v[12:15]
	v_mfma_f32_16x16x32_bf16 v[8:11], v[164:167], v[202:205], v[8:11]
	s_setprio 0
	s_barrier
	s_add_u32 s0, s44, 0x20080
	s_addc_u32 s1, s45, 0
	s_add_i32 s4, s5, s50
	s_mov_b32 m0, s4
	s_nop 0
	global_load_lds_dwordx4 v130, s[0:1]
	v_lshl_add_u64 v[146:147], s[0:1], 0, v[134:135]
	s_add_i32 m0, s4, 0x2000
	s_nop 0
	global_load_lds_dwordx4 v134, s[0:1]
	s_waitcnt vmcnt(6)
	s_barrier
	s_setprio 1
	v_mfma_f32_16x16x32_bf16 v[52:55], v[206:209], v[168:171], v[52:55]
	v_mfma_f32_16x16x32_bf16 v[48:51], v[214:217], v[168:171], v[48:51]
	v_mfma_f32_16x16x32_bf16 v[36:39], v[206:209], v[176:179], v[36:39]
	v_mfma_f32_16x16x32_bf16 v[32:35], v[214:217], v[176:179], v[32:35]
	v_mfma_f32_16x16x32_bf16 v[20:23], v[206:209], v[188:191], v[20:23]
	v_mfma_f32_16x16x32_bf16 v[16:19], v[214:217], v[188:191], v[16:19]
	v_mfma_f32_16x16x32_bf16 v[4:7], v[206:209], v[198:201], v[4:7]
	v_mfma_f32_16x16x32_bf16 v[0:3], v[214:217], v[198:201], v[0:3]
	v_mfma_f32_16x16x32_bf16 v[52:55], v[210:213], v[172:175], v[52:55]
	v_mfma_f32_16x16x32_bf16 v[48:51], v[218:221], v[172:175], v[48:51]
	v_mfma_f32_16x16x32_bf16 v[36:39], v[210:213], v[180:183], v[36:39]
	v_mfma_f32_16x16x32_bf16 v[32:35], v[218:221], v[180:183], v[32:35]
	v_mfma_f32_16x16x32_bf16 v[20:23], v[210:213], v[194:197], v[20:23]
	v_mfma_f32_16x16x32_bf16 v[16:19], v[218:221], v[194:197], v[16:19]
	v_mfma_f32_16x16x32_bf16 v[4:7], v[210:213], v[202:205], v[4:7]
	v_mfma_f32_16x16x32_bf16 v[0:3], v[218:221], v[202:205], v[0:3]
	s_setprio 0
	s_add_i32 s79, s79, 2
	s_add_u32 s42, s42, 0x100
	s_addc_u32 s43, s43, 0
	s_add_u32 s35, s35, 0x100
	s_addc_u32 s41, s41, 0
	s_cmp_gt_u32 s79, 5
	s_barrier
	s_cbranch_scc0 .LBB0_984

;     DI size_t aoff(const Unit& u, size_t tstep) const { return (size_t)u.pm * tstep; }
;     DI size_t boff(const Unit& u, size_t tstep) const { return (size_t)u.pn * tstep; }
;     DI bool next(int i, Unit& u) const { const long L = (long)i * G + c; if (L >= np) return false; u.pm = pmv; u.pn = (int)(L % nN); u.ks = (int)(L / nN); return true; }
;     DI size_t aoff(const Unit& u, size_t) const { return (size_t)u.ks * kbytes; }
;     DI size_t boff(const Unit& u, size_t tstep) const { return (size_t)u.pn * tstep + (size_t)u.ks * kbytes; }
;     DI bool next(int i, Unit& u) const { Unit t; if (!S.next(i / 3, t)) return false; u.pm = t.pm; u.pn = t.pn; u.ks = i % 3; return true; }
;     DI size_t aoff(const Unit& u, size_t tstep) const { return (u.ks < 2 ? offU : offOA) + (size_t)u.pm * tstep; }
; #define PG8_LDA(dst, b, h) do { _Pragma("unroll") for (int m = 0; m < 4; ++m) _Pragma("unroll") for (int k = 0; k < 2; ++k) dst[m][k] = *(const LAS bf16x8*)(lds + PG8_SA(b, h) + aoff + m * 2048 + k * 1024); } while (0)
; template <class Epi, class Sched>
; DI void gemm_phase(LAS unsigned char* lds, const Gemm g, const Sched& S, const Epi& E) {
;     ...
;         const bool has_next = S.next(ui + 1, nxt);
;         const char* nA = has_next ? (const char*)g.A + S.aoff(nxt, tstep) : cA; const char* nB = has_next ? (const char*)g.Bt + S.boff(nxt, tstep) : cB;
;         for (int t = 0; t < nt; t += 2) {
;             if constexpr (Epi::HAS_MID) { if (t == E.mid_t(nt)) { int fr3 = fr, fq3 = fq; asm volatile("" : "+v"(fr3), "+v"(fq3)); E.mid(acc, cur, wr, wc, fr3, fq3); } }
;             const bool last = (t == nt - 2);
;             const char* a1 = cA + (size_t)(t + 1) * kstep;
;             const char* a2 = last ? nA : cA + (size_t)(t + 2) * kstep; const char* b2 = last ? nB : cB + (size_t)(t + 2) * kstep;
;             const char* a3 = a2 + kstep; const char* b3 = b2 + kstep;
;             PG8_LDB(B0, 0, 0); PG8_SCHED; PG8_LDA(At, 0, 0); PG8_STAGE(PG8_SA(1, 1), a1 + hstep, voffA);
;             PG8_WAIT_L(8); PG8_BAR; PG8_WAIT_L(0); PG8_MMA(0, 0, At, B0); PG8_BAR; PG8_SCHED;
;             PG8_LDB(B1, 0, 1); PG8_STAGE(PG8_SB(0, 0), b2, voffB);
;             PG8_BAR; PG8_WAIT_L(0); PG8_MMA(0, 1, At, B1); PG8_BAR;
;             PG8_LDA(At, 0, 1); PG8_STAGE(PG8_SA(0, 0), a2, voffA);
;             PG8_BAR; PG8_WAIT_L(0); PG8_MMA(1, 0, At, B0); PG8_BAR; PG8_SCHED;
.LBB0_1667:
	s_ashr_i32 s29, s28, 31
	s_lshl_b64 s[0:1], s[28:29], 20
	s_add_u32 s30, s45, s0
	v_cmp_lt_i64_e32 vcc, s[8:9], v[140:141]
	s_addc_u32 s31, s46, s1
	s_and_b64 s[0:1], vcc, exec
	s_cselect_b32 s29, s31, s43
	s_cselect_b32 s35, s30, s42
	s_ashr_i32 s19, s18, 31
	s_lshl_b64 s[0:1], s[18:19], 20
	s_add_u32 s36, s47, s0
	s_addc_u32 s37, s48, s1
	s_and_b64 s[0:1], vcc, exec
	s_cselect_b32 s19, s37, s41
	s_cselect_b32 s65, s36, s40
	s_add_u32 s8, s42, 0x80080
	s_addc_u32 s9, s43, 0
	s_add_u32 s66, s40, 0x100
	v_mov_b32_e32 v8, 0
	s_addc_u32 s67, s41, 0
	s_mov_b32 s68, -2
	ds_read_b128 v[144:147], v149
	ds_read_b128 v[156:159], v149 offset:1024
	ds_read_b128 v[160:163], v149 offset:2048
	ds_read_b128 v[164:167], v149 offset:3072
	s_add_u32 s0, s8, 0xfff80080
	s_addc_u32 s1, s9, -1
	s_cmp_eq_u32 s68, 28
	s_cselect_b32 s43, s29, s1
	s_cselect_b32 s42, s35, s0
	s_cselect_b32 s41, s19, s67
	s_cselect_b32 s40, s65, s66
	s_add_i32 m0, s39, 0xc000
	ds_read_b128 v[168:171], v150
	ds_read_b128 v[172:175], v150 offset:1024
	ds_read_b128 v[176:179], v150 offset:2048
	ds_read_b128 v[180:183], v150 offset:3072
	ds_read_b128 v[188:191], v150 offset:4096
	ds_read_b128 v[206:209], v150 offset:5120
	ds_read_b128 v[210:213], v150 offset:6144
	global_load_lds_dwordx4 v136, s[8:9]
	s_add_i32 m0, s39, 0xe000
	ds_read_b128 v[214:217], v150 offset:7168
	global_load_lds_dwordx4 v138, s[8:9]
	s_waitcnt lgkmcnt(8)
	s_barrier
	s_waitcnt lgkmcnt(0)
	s_setprio 1
	v_mfma_f32_16x16x32_bf16 v[116:119], v[144:147], v[168:171], 0
	v_mfma_f32_16x16x32_bf16 v[112:115], v[160:163], v[168:171], 0
	v_mfma_f32_16x16x32_bf16 v[100:103], v[144:147], v[176:179], 0
	v_mfma_f32_16x16x32_bf16 v[96:99], v[160:163], v[176:179], 0
	v_mfma_f32_16x16x32_bf16 v[84:87], v[144:147], v[188:191], 0
	v_mfma_f32_16x16x32_bf16 v[80:83], v[160:163], v[188:191], 0
	v_mfma_f32_16x16x32_bf16 v[68:71], v[144:147], v[210:213], 0
	v_mfma_f32_16x16x32_bf16 v[64:67], v[160:163], v[210:213], 0
	v_mfma_f32_16x16x32_bf16 v[116:119], v[156:159], v[172:175], v[116:119]
	v_mfma_f32_16x16x32_bf16 v[112:115], v[164:167], v[172:175], v[112:115]
	v_mfma_f32_16x16x32_bf16 v[100:103], v[156:159], v[180:183], v[100:103]
	v_mfma_f32_16x16x32_bf16 v[96:99], v[164:167], v[180:183], v[96:99]
	v_mfma_f32_16x16x32_bf16 v[84:87], v[156:159], v[206:209], v[84:87]
	v_mfma_f32_16x16x32_bf16 v[80:83], v[164:167], v[206:209], v[80:83]
	v_mfma_f32_16x16x32_bf16 v[68:71], v[156:159], v[214:217], v[68:71]
	v_mfma_f32_16x16x32_bf16 v[64:67], v[164:167], v[214:217], v[64:67]
	s_setprio 0
	s_barrier
	s_add_i32 s0, s61, s50
	s_mov_b32 m0, s0
	ds_read_b128 v[218:221], v151
	ds_read_b128 v[222:225], v151 offset:1024
	ds_read_b128 v[226:229], v151 offset:2048
	global_load_lds_dwordx4 v130, s[40:41]
	s_add_i32 m0, s0, 0x2000
	ds_read_b128 v[230:233], v151 offset:3072
	global_load_lds_dwordx4 v134, s[40:41]
	s_barrier
	s_waitcnt lgkmcnt(0)
	s_setprio 1
	v_mfma_f32_16x16x32_bf16 v[124:127], v[218:221], v[168:171], 0
	v_mfma_f32_16x16x32_bf16 v[120:123], v[226:229], v[168:171], 0
	v_mfma_f32_16x16x32_bf16 v[108:111], v[218:221], v[176:179], 0
	v_mfma_f32_16x16x32_bf16 v[104:107], v[226:229], v[176:179], 0
	v_mfma_f32_16x16x32_bf16 v[92:95], v[218:221], v[188:191], 0
	v_mfma_f32_16x16x32_bf16 v[88:91], v[226:229], v[188:191], 0
	v_mfma_f32_16x16x32_bf16 v[76:79], v[218:221], v[210:213], 0
	v_mfma_f32_16x16x32_bf16 v[72:75], v[226:229], v[210:213], 0
	v_mfma_f32_16x16x32_bf16 v[124:127], v[222:225], v[172:175], v[124:127]
	v_mfma_f32_16x16x32_bf16 v[120:123], v[230:233], v[172:175], v[120:123]
	v_mfma_f32_16x16x32_bf16 v[108:111], v[222:225], v[180:183], v[108:111]
	v_mfma_f32_16x16x32_bf16 v[104:107], v[230:233], v[180:183], v[104:107]
	v_mfma_f32_16x16x32_bf16 v[92:95], v[222:225], v[206:209], v[92:95]
	v_mfma_f32_16x16x32_bf16 v[88:91], v[230:233], v[206:209], v[88:91]
	v_mfma_f32_16x16x32_bf16 v[76:79], v[222:225], v[214:217], v[76:79]
	v_mfma_f32_16x16x32_bf16 v[72:75], v[230:233], v[214:217], v[72:75]
	s_setprio 0
	s_mov_b32 m0, s39
	s_barrier
	ds_read_b128 v[168:171], v150 offset:16384
	ds_read_b128 v[172:175], v150 offset:17408
	ds_read_b128 v[176:179], v150 offset:18432
	ds_read_b128 v[180:183], v150 offset:19456
	ds_read_b128 v[188:191], v150 offset:20480
	ds_read_b128 v[206:209], v150 offset:21504
	ds_read_b128 v[210:213], v150 offset:22528
	global_load_lds_dwordx4 v128, s[42:43]
	s_mov_b32 m0, s51
	ds_read_b128 v[214:217], v150 offset:23552
	global_load_lds_dwordx4 v132, s[42:43]
	s_barrier
	s_waitcnt lgkmcnt(0)
	s_setprio 1
	v_mfma_f32_16x16x32_bf16 v[52:55], v[144:147], v[168:171], 0
	v_mfma_f32_16x16x32_bf16 v[48:51], v[160:163], v[168:171], 0
	v_mfma_f32_16x16x32_bf16 v[36:39], v[144:147], v[176:179], 0
	v_mfma_f32_16x16x32_bf16 v[32:35], v[160:163], v[176:179], 0
	v_mfma_f32_16x16x32_bf16 v[20:23], v[144:147], v[188:191], 0
	v_mfma_f32_16x16x32_bf16 v[16:19], v[160:163], v[188:191], 0
	v_mfma_f32_16x16x32_bf16 v[4:7], v[144:147], v[210:213], 0
	v_mfma_f32_16x16x32_bf16 v[0:3], v[160:163], v[210:213], 0
	v_mfma_f32_16x16x32_bf16 v[52:55], v[156:159], v[172:175], v[52:55]
	v_mfma_f32_16x16x32_bf16 v[48:51], v[164:167], v[172:175], v[48:51]
	v_mfma_f32_16x16x32_bf16 v[36:39], v[156:159], v[180:183], v[36:39]
	v_mfma_f32_16x16x32_bf16 v[32:35], v[164:167], v[180:183], v[32:35]
	v_mfma_f32_16x16x32_bf16 v[20:23], v[156:159], v[206:209], v[20:23]
	v_mfma_f32_16x16x32_bf16 v[16:19], v[164:167], v[206:209], v[16:19]
	v_mfma_f32_16x16x32_bf16 v[4:7], v[156:159], v[214:217], v[4:7]
	v_mfma_f32_16x16x32_bf16 v[0:3], v[164:167], v[214:217], v[0:3]
	s_setprio 0
	s_barrier
; #define PG8_STAGE(bufoff, gbase, voff) do { _Pragma("unroll") for (int _i = 0; _i < 2; ++_i) \
;         __builtin_amdgcn_global_load_lds((const unsigned*)((const char*)(gbase) + (voff)[_i]), (LAS unsigned*)(lds + (bufoff) + ldsw + _i * 8192), 16, 0, 0); } while (0)
; #define PG8_LDA(dst, b, h) do { _Pragma("unroll") for (int m = 0; m < 4; ++m) _Pragma("unroll") for (int k = 0; k < 2; ++k) dst[m][k] = *(const LAS bf16x8*)(lds + PG8_SA(b, h) + aoff + m * 2048 + k * 1024); } while (0)
; #define PG8_LDB(dst, b, h) do { _Pragma("unroll") for (int n = 0; n < 2; ++n) _Pragma("unroll") for (int k = 0; k < 2; ++k) dst[n][k] = *(const LAS bf16x8*)(lds + PG8_SB(b, h) + boff + n * 2048 + k * 1024); } while (0)
; #define PG8_MMA(ai, bj, At, Bt) do { __builtin_amdgcn_s_setprio(1); _Pragma("unroll") for (int m = 0; m < 4; ++m) _Pragma("unroll") for (int n = 0; n < 2; ++n) _Pragma("unroll") for (int k = 0; k < 2; ++k) \
;         acc[ai][bj][m][n] = __builtin_amdgcn_mfma_f32_16x16x32_bf16(Bt[n][k], At[m][k], acc[ai][bj][m][n], 0, 0, 0); __builtin_amdgcn_s_setprio(0); } while (0)
; #define PG8_WAIT_V(n) asm volatile("s_waitcnt vmcnt(" #n ")" ::: "memory")
; #define PG8_WAIT_L(n) asm volatile("s_waitcnt lgkmcnt(" #n ")" ::: "memory")
; #define PG8_BAR __builtin_amdgcn_s_barrier()
; #define PG8_SCHED __builtin_amdgcn_sched_barrier(0)
; template <class Epi, class Sched>
; DI void gemm_phase(LAS unsigned char* lds, const Gemm g, const Sched& S, const Epi& E) {
;     ...
;             PG8_STAGE(PG8_SB(0, 1), b2 + hstep, voffB);
;             PG8_WAIT_V(6); PG8_BAR; PG8_MMA(1, 1, At, B1); PG8_BAR;
;             PG8_LDB(B0, 1, 0); PG8_SCHED; PG8_LDA(At, 1, 0); PG8_STAGE(PG8_SA(0, 1), a2 + hstep, voffA);
;             PG8_WAIT_L(8); PG8_BAR; PG8_WAIT_L(0); PG8_MMA(0, 0, At, B0); PG8_BAR; PG8_SCHED;
;             PG8_LDB(B1, 1, 1); PG8_STAGE(PG8_SB(1, 0), b3, voffB);
;             PG8_BAR; PG8_WAIT_L(0); PG8_MMA(0, 1, At, B1); PG8_BAR;
;             PG8_LDA(At, 1, 1); PG8_STAGE(PG8_SA(1, 0), a3, voffA);
;             PG8_BAR; PG8_WAIT_L(0); PG8_MMA(1, 0, At, B0); PG8_BAR; PG8_SCHED;
	s_add_u32 s0, s40, 0x80000
	s_addc_u32 s1, s41, 0
	s_add_i32 s4, s62, s50
	s_mov_b32 m0, s4
	s_nop 0
	global_load_lds_dwordx4 v130, s[0:1]
	s_add_i32 m0, s4, 0x2000
	s_nop 0
	global_load_lds_dwordx4 v134, s[0:1]
	s_waitcnt vmcnt(6)
	s_barrier
	s_setprio 1
	v_mfma_f32_16x16x32_bf16 v[60:63], v[218:221], v[168:171], 0
	v_mfma_f32_16x16x32_bf16 v[56:59], v[226:229], v[168:171], 0
	v_mfma_f32_16x16x32_bf16 v[44:47], v[218:221], v[176:179], 0
	v_mfma_f32_16x16x32_bf16 v[40:43], v[226:229], v[176:179], 0
	v_mfma_f32_16x16x32_bf16 v[28:31], v[218:221], v[188:191], 0
	v_mfma_f32_16x16x32_bf16 v[24:27], v[226:229], v[188:191], 0
	v_mfma_f32_16x16x32_bf16 v[12:15], v[218:221], v[210:213], 0
	v_mfma_f32_16x16x32_bf16 v[8:11], v[226:229], v[210:213], 0
	v_mfma_f32_16x16x32_bf16 v[60:63], v[222:225], v[172:175], v[60:63]
	v_mfma_f32_16x16x32_bf16 v[56:59], v[230:233], v[172:175], v[56:59]
	v_mfma_f32_16x16x32_bf16 v[44:47], v[222:225], v[180:183], v[44:47]
	v_mfma_f32_16x16x32_bf16 v[40:43], v[230:233], v[180:183], v[40:43]
	v_mfma_f32_16x16x32_bf16 v[28:31], v[222:225], v[206:209], v[28:31]
	v_mfma_f32_16x16x32_bf16 v[24:27], v[230:233], v[206:209], v[24:27]
	v_mfma_f32_16x16x32_bf16 v[12:15], v[222:225], v[214:217], v[12:15]
	v_mfma_f32_16x16x32_bf16 v[8:11], v[230:233], v[214:217], v[8:11]
	s_setprio 0
	s_add_i32 s4, 0, 0x18000
	v_add_u32_e32 v202, s4, v148
	s_barrier
	ds_read_b128 v[144:147], v202
	ds_read_b128 v[156:159], v202 offset:1024
	ds_read_b128 v[160:163], v202 offset:2048
	ds_read_b128 v[164:167], v202 offset:3072
	s_add_u32 s0, s42, 0x80000
	s_addc_u32 s1, s43, 0
	s_mov_b32 m0, s52
	ds_read_b128 v[168:171], v150 offset:32768
	ds_read_b128 v[172:175], v150 offset:33792
	ds_read_b128 v[176:179], v150 offset:34816
	ds_read_b128 v[180:183], v150 offset:35840
	ds_read_b128 v[188:191], v150 offset:36864
	ds_read_b128 v[206:209], v150 offset:37888
	ds_read_b128 v[210:213], v150 offset:38912
	global_load_lds_dwordx4 v128, s[0:1]
	s_mov_b32 m0, s53
	ds_read_b128 v[214:217], v150 offset:39936
	global_load_lds_dwordx4 v132, s[0:1]
	s_waitcnt lgkmcnt(8)
	s_barrier
	s_waitcnt lgkmcnt(0)
	s_setprio 1
	v_mfma_f32_16x16x32_bf16 v[116:119], v[144:147], v[168:171], v[116:119]
	v_mfma_f32_16x16x32_bf16 v[112:115], v[160:163], v[168:171], v[112:115]
	v_mfma_f32_16x16x32_bf16 v[100:103], v[144:147], v[176:179], v[100:103]
	v_mfma_f32_16x16x32_bf16 v[96:99], v[160:163], v[176:179], v[96:99]
	v_mfma_f32_16x16x32_bf16 v[84:87], v[144:147], v[188:191], v[84:87]
	v_mfma_f32_16x16x32_bf16 v[80:83], v[160:163], v[188:191], v[80:83]
	v_mfma_f32_16x16x32_bf16 v[68:71], v[144:147], v[210:213], v[68:71]
	v_mfma_f32_16x16x32_bf16 v[64:67], v[160:163], v[210:213], v[64:67]
	v_mfma_f32_16x16x32_bf16 v[116:119], v[156:159], v[172:175], v[116:119]
	v_mfma_f32_16x16x32_bf16 v[112:115], v[164:167], v[172:175], v[112:115]
	v_mfma_f32_16x16x32_bf16 v[100:103], v[156:159], v[180:183], v[100:103]
	v_mfma_f32_16x16x32_bf16 v[96:99], v[164:167], v[180:183], v[96:99]
	v_mfma_f32_16x16x32_bf16 v[84:87], v[156:159], v[206:209], v[84:87]
	v_mfma_f32_16x16x32_bf16 v[80:83], v[164:167], v[206:209], v[80:83]
	v_mfma_f32_16x16x32_bf16 v[68:71], v[156:159], v[214:217], v[68:71]
	v_mfma_f32_16x16x32_bf16 v[64:67], v[164:167], v[214:217], v[64:67]
	s_setprio 0
	s_barrier
	s_add_i32 s5, 0, 0x1c000
	s_add_i32 s0, s4, s50
	v_add_u32_e32 v203, s5, v148
	s_add_i32 m0, s0, 0xffffff80
	ds_read_b128 v[218:221], v203
	ds_read_b128 v[222:225], v203 offset:1024
	ds_read_b128 v[226:229], v203 offset:2048
	global_load_lds_dwordx4 v130, s[40:41] offset:128
	s_add_i32 m0, s0, 0x1f80
	ds_read_b128 v[230:233], v203 offset:3072
	global_load_lds_dwordx4 v134, s[40:41] offset:128
	s_barrier
	s_waitcnt lgkmcnt(0)
	s_setprio 1
	v_mfma_f32_16x16x32_bf16 v[124:127], v[218:221], v[168:171], v[124:127]
	v_mfma_f32_16x16x32_bf16 v[120:123], v[226:229], v[168:171], v[120:123]
	v_mfma_f32_16x16x32_bf16 v[108:111], v[218:221], v[176:179], v[108:111]
	v_mfma_f32_16x16x32_bf16 v[104:107], v[226:229], v[176:179], v[104:107]
	v_mfma_f32_16x16x32_bf16 v[92:95], v[218:221], v[188:191], v[92:95]
	v_mfma_f32_16x16x32_bf16 v[88:91], v[226:229], v[188:191], v[88:91]
	v_mfma_f32_16x16x32_bf16 v[76:79], v[218:221], v[210:213], v[76:79]
	v_mfma_f32_16x16x32_bf16 v[72:75], v[226:229], v[210:213], v[72:75]
	v_mfma_f32_16x16x32_bf16 v[124:127], v[222:225], v[172:175], v[124:127]
	v_mfma_f32_16x16x32_bf16 v[120:123], v[230:233], v[172:175], v[120:123]
	v_mfma_f32_16x16x32_bf16 v[108:111], v[222:225], v[180:183], v[108:111]
	v_mfma_f32_16x16x32_bf16 v[104:107], v[230:233], v[180:183], v[104:107]
	v_mfma_f32_16x16x32_bf16 v[92:95], v[222:225], v[206:209], v[92:95]
	v_mfma_f32_16x16x32_bf16 v[88:91], v[230:233], v[206:209], v[88:91]
	v_mfma_f32_16x16x32_bf16 v[76:79], v[222:225], v[214:217], v[76:79]
	v_mfma_f32_16x16x32_bf16 v[72:75], v[230:233], v[214:217], v[72:75]
	s_setprio 0
	s_add_i32 m0, s57, 0xffffff80
	s_barrier
	ds_read_b128 v[168:171], v150 offset:49152
	ds_read_b128 v[172:175], v150 offset:50176
	ds_read_b128 v[176:179], v150 offset:51200
	ds_read_b128 v[180:183], v150 offset:52224
	ds_read_b128 v[188:191], v150 offset:53248
	ds_read_b128 v[206:209], v150 offset:54272
	ds_read_b128 v[210:213], v150 offset:55296
	global_load_lds_dwordx4 v128, s[42:43] offset:128
	s_add_i32 m0, s58, 0xffffff80
	ds_read_b128 v[214:217], v150 offset:56320
	global_load_lds_dwordx4 v132, s[42:43] offset:128
	s_barrier
; #define PG8_STAGE(bufoff, gbase, voff) do { _Pragma("unroll") for (int _i = 0; _i < 2; ++_i) \
;         __builtin_amdgcn_global_load_lds((const unsigned*)((const char*)(gbase) + (voff)[_i]), (LAS unsigned*)(lds + (bufoff) + ldsw + _i * 8192), 16, 0, 0); } while (0)
; #define PG8_LDA(dst, b, h) do { _Pragma("unroll") for (int m = 0; m < 4; ++m) _Pragma("unroll") for (int k = 0; k < 2; ++k) dst[m][k] = *(const LAS bf16x8*)(lds + PG8_SA(b, h) + aoff + m * 2048 + k * 1024); } while (0)
; #define PG8_LDB(dst, b, h) do { _Pragma("unroll") for (int n = 0; n < 2; ++n) _Pragma("unroll") for (int k = 0; k < 2; ++k) dst[n][k] = *(const LAS bf16x8*)(lds + PG8_SB(b, h) + boff + n * 2048 + k * 1024); } while (0)
; #define PG8_MMA(ai, bj, At, Bt) do { __builtin_amdgcn_s_setprio(1); _Pragma("unroll") for (int m = 0; m < 4; ++m) _Pragma("unroll") for (int n = 0; n < 2; ++n) _Pragma("unroll") for (int k = 0; k < 2; ++k) \
;         acc[ai][bj][m][n] = __builtin_amdgcn_mfma_f32_16x16x32_bf16(Bt[n][k], At[m][k], acc[ai][bj][m][n], 0, 0, 0); __builtin_amdgcn_s_setprio(0); } while (0)
; #define PG8_WAIT_V(n) asm volatile("s_waitcnt vmcnt(" #n ")" ::: "memory")
; #define PG8_WAIT_L(n) asm volatile("s_waitcnt lgkmcnt(" #n ")" ::: "memory")
; #define PG8_BAR __builtin_amdgcn_s_barrier()
; #define PG8_SCHED __builtin_amdgcn_sched_barrier(0)
; template <class Epi, class Sched>
; DI void gemm_phase(LAS unsigned char* lds, const Gemm g, const Sched& S, const Epi& E) {
;     ...
;             const bool last = (t == nt - 2);
;             const char* a1 = cA + (size_t)(t + 1) * kstep;
;             const char* a2 = last ? nA : cA + (size_t)(t + 2) * kstep; const char* b2 = last ? nB : cB + (size_t)(t + 2) * kstep;
;             const char* a3 = a2 + kstep; const char* b3 = b2 + kstep;
;             PG8_LDB(B0, 0, 0); PG8_SCHED; PG8_LDA(At, 0, 0); PG8_STAGE(PG8_SA(1, 1), a1 + hstep, voffA);
;             PG8_WAIT_L(8); PG8_BAR; PG8_WAIT_L(0); PG8_MMA(0, 0, At, B0); PG8_BAR; PG8_SCHED;
;             PG8_LDB(B1, 0, 1); PG8_STAGE(PG8_SB(0, 0), b2, voffB);
;     ...
;             PG8_BAR; PG8_WAIT_L(0); PG8_MMA(1, 0, At, B0); PG8_BAR; PG8_SCHED;
;             PG8_STAGE(PG8_SB(1, 1), b3 + hstep, voffB);
;             PG8_WAIT_V(6); PG8_BAR; PG8_MMA(1, 1, At, B1); PG8_BAR;
	s_waitcnt lgkmcnt(0)
	s_setprio 1
	v_mfma_f32_16x16x32_bf16 v[52:55], v[144:147], v[168:171], v[52:55]
	v_mfma_f32_16x16x32_bf16 v[48:51], v[160:163], v[168:171], v[48:51]
	v_mfma_f32_16x16x32_bf16 v[36:39], v[144:147], v[176:179], v[36:39]
	v_mfma_f32_16x16x32_bf16 v[32:35], v[160:163], v[176:179], v[32:35]
	v_mfma_f32_16x16x32_bf16 v[20:23], v[144:147], v[188:191], v[20:23]
	v_mfma_f32_16x16x32_bf16 v[16:19], v[160:163], v[188:191], v[16:19]
	v_mfma_f32_16x16x32_bf16 v[4:7], v[144:147], v[210:213], v[4:7]
	v_mfma_f32_16x16x32_bf16 v[0:3], v[160:163], v[210:213], v[0:3]
	v_mfma_f32_16x16x32_bf16 v[52:55], v[156:159], v[172:175], v[52:55]
	v_mfma_f32_16x16x32_bf16 v[48:51], v[164:167], v[172:175], v[48:51]
	v_mfma_f32_16x16x32_bf16 v[36:39], v[156:159], v[180:183], v[36:39]
	v_mfma_f32_16x16x32_bf16 v[32:35], v[164:167], v[180:183], v[32:35]
	v_mfma_f32_16x16x32_bf16 v[20:23], v[156:159], v[206:209], v[20:23]
	v_mfma_f32_16x16x32_bf16 v[16:19], v[164:167], v[206:209], v[16:19]
	v_mfma_f32_16x16x32_bf16 v[4:7], v[156:159], v[214:217], v[4:7]
	v_mfma_f32_16x16x32_bf16 v[0:3], v[164:167], v[214:217], v[0:3]
	s_setprio 0
	s_barrier
	s_add_u32 s0, s40, 0x80080
	s_addc_u32 s1, s41, 0
	s_add_i32 s4, s5, s50
	s_mov_b32 m0, s4
	s_nop 0
	global_load_lds_dwordx4 v130, s[0:1]
	s_add_i32 m0, s4, 0x2000
	s_nop 0
	global_load_lds_dwordx4 v134, s[0:1]
	s_waitcnt vmcnt(6)
	s_barrier
	s_setprio 1
	v_mfma_f32_16x16x32_bf16 v[60:63], v[218:221], v[168:171], v[60:63]
	v_mfma_f32_16x16x32_bf16 v[56:59], v[226:229], v[168:171], v[56:59]
	v_mfma_f32_16x16x32_bf16 v[44:47], v[218:221], v[176:179], v[44:47]
	v_mfma_f32_16x16x32_bf16 v[40:43], v[226:229], v[176:179], v[40:43]
	v_mfma_f32_16x16x32_bf16 v[28:31], v[218:221], v[188:191], v[28:31]
	v_mfma_f32_16x16x32_bf16 v[24:27], v[226:229], v[188:191], v[24:27]
	v_mfma_f32_16x16x32_bf16 v[12:15], v[218:221], v[210:213], v[12:15]
	v_mfma_f32_16x16x32_bf16 v[8:11], v[226:229], v[210:213], v[8:11]
	v_mfma_f32_16x16x32_bf16 v[60:63], v[222:225], v[172:175], v[60:63]
	v_mfma_f32_16x16x32_bf16 v[56:59], v[230:233], v[172:175], v[56:59]
	v_mfma_f32_16x16x32_bf16 v[44:47], v[222:225], v[180:183], v[44:47]
	v_mfma_f32_16x16x32_bf16 v[40:43], v[230:233], v[180:183], v[40:43]
	v_mfma_f32_16x16x32_bf16 v[28:31], v[222:225], v[206:209], v[28:31]
	v_mfma_f32_16x16x32_bf16 v[24:27], v[230:233], v[206:209], v[24:27]
	v_mfma_f32_16x16x32_bf16 v[12:15], v[222:225], v[214:217], v[12:15]
	v_mfma_f32_16x16x32_bf16 v[8:11], v[230:233], v[214:217], v[8:11]
	s_setprio 0
	s_add_i32 s68, s68, 2
	s_add_u32 s8, s8, 0x100
	s_addc_u32 s9, s9, 0
	s_add_u32 s66, s66, 0x100
	s_addc_u32 s67, s67, 0
	s_cmp_gt_u32 s68, 29
	s_barrier
	s_cbranch_scc0 .LBB0_1668
	s_branch .Lpeel_done_1668
.LBB0_1668:
	ds_read_b128 v[144:147], v149
	ds_read_b128 v[156:159], v149 offset:1024
	ds_read_b128 v[160:163], v149 offset:2048
	ds_read_b128 v[164:167], v149 offset:3072
	s_add_u32 s0, s8, 0xfff80080
	s_addc_u32 s1, s9, -1
	s_cmp_eq_u32 s68, 28
	s_cselect_b32 s43, s29, s1
	s_cselect_b32 s42, s35, s0
	s_cselect_b32 s41, s19, s67
	s_cselect_b32 s40, s65, s66
	s_add_i32 m0, s39, 0xc000
	ds_read_b128 v[168:171], v150
	ds_read_b128 v[172:175], v150 offset:1024
	ds_read_b128 v[176:179], v150 offset:2048
	ds_read_b128 v[180:183], v150 offset:3072
	ds_read_b128 v[188:191], v150 offset:4096
	ds_read_b128 v[206:209], v150 offset:5120
	ds_read_b128 v[210:213], v150 offset:6144
	global_load_lds_dwordx4 v136, s[8:9]
	s_add_i32 m0, s39, 0xe000
	ds_read_b128 v[214:217], v150 offset:7168
	global_load_lds_dwordx4 v138, s[8:9]
	s_waitcnt lgkmcnt(8)
	s_barrier
	s_waitcnt lgkmcnt(0)
	s_setprio 1
	v_mfma_f32_16x16x32_bf16 v[116:119], v[144:147], v[168:171], v[116:119]
	v_mfma_f32_16x16x32_bf16 v[112:115], v[160:163], v[168:171], v[112:115]
	v_mfma_f32_16x16x32_bf16 v[100:103], v[144:147], v[176:179], v[100:103]
	v_mfma_f32_16x16x32_bf16 v[96:99], v[160:163], v[176:179], v[96:99]
	v_mfma_f32_16x16x32_bf16 v[84:87], v[144:147], v[188:191], v[84:87]
	v_mfma_f32_16x16x32_bf16 v[80:83], v[160:163], v[188:191], v[80:83]
	v_mfma_f32_16x16x32_bf16 v[68:71], v[144:147], v[210:213], v[68:71]
	v_mfma_f32_16x16x32_bf16 v[64:67], v[160:163], v[210:213], v[64:67]
	v_mfma_f32_16x16x32_bf16 v[116:119], v[156:159], v[172:175], v[116:119]
	v_mfma_f32_16x16x32_bf16 v[112:115], v[164:167], v[172:175], v[112:115]
	v_mfma_f32_16x16x32_bf16 v[100:103], v[156:159], v[180:183], v[100:103]
	v_mfma_f32_16x16x32_bf16 v[96:99], v[164:167], v[180:183], v[96:99]
	v_mfma_f32_16x16x32_bf16 v[84:87], v[156:159], v[206:209], v[84:87]
	v_mfma_f32_16x16x32_bf16 v[80:83], v[164:167], v[206:209], v[80:83]
	v_mfma_f32_16x16x32_bf16 v[68:71], v[156:159], v[214:217], v[68:71]
	v_mfma_f32_16x16x32_bf16 v[64:67], v[164:167], v[214:217], v[64:67]
	s_setprio 0
	s_barrier
	s_add_i32 s0, s61, s50
	s_mov_b32 m0, s0
	ds_read_b128 v[218:221], v151
	ds_read_b128 v[222:225], v151 offset:1024
	ds_read_b128 v[226:229], v151 offset:2048
	global_load_lds_dwordx4 v130, s[40:41]
	s_add_i32 m0, s0, 0x2000
	ds_read_b128 v[230:233], v151 offset:3072
	global_load_lds_dwordx4 v134, s[40:41]
	s_barrier
; #define PG8_STAGE(bufoff, gbase, voff) do { _Pragma("unroll") for (int _i = 0; _i < 2; ++_i) \
;         __builtin_amdgcn_global_load_lds((const unsigned*)((const char*)(gbase) + (voff)[_i]), (LAS unsigned*)(lds + (bufoff) + ldsw + _i * 8192), 16, 0, 0); } while (0)
; #define PG8_LDA(dst, b, h) do { _Pragma("unroll") for (int m = 0; m < 4; ++m) _Pragma("unroll") for (int k = 0; k < 2; ++k) dst[m][k] = *(const LAS bf16x8*)(lds + PG8_SA(b, h) + aoff + m * 2048 + k * 1024); } while (0)
; #define PG8_LDB(dst, b, h) do { _Pragma("unroll") for (int n = 0; n < 2; ++n) _Pragma("unroll") for (int k = 0; k < 2; ++k) dst[n][k] = *(const LAS bf16x8*)(lds + PG8_SB(b, h) + boff + n * 2048 + k * 1024); } while (0)
; #define PG8_MMA(ai, bj, At, Bt) do { __builtin_amdgcn_s_setprio(1); _Pragma("unroll") for (int m = 0; m < 4; ++m) _Pragma("unroll") for (int n = 0; n < 2; ++n) _Pragma("unroll") for (int k = 0; k < 2; ++k) \
;         acc[ai][bj][m][n] = __builtin_amdgcn_mfma_f32_16x16x32_bf16(Bt[n][k], At[m][k], acc[ai][bj][m][n], 0, 0, 0); __builtin_amdgcn_s_setprio(0); } while (0)
; #define PG8_WAIT_V(n) asm volatile("s_waitcnt vmcnt(" #n ")" ::: "memory")
; #define PG8_WAIT_L(n) asm volatile("s_waitcnt lgkmcnt(" #n ")" ::: "memory")
; #define PG8_BAR __builtin_amdgcn_s_barrier()
; #define PG8_SCHED __builtin_amdgcn_sched_barrier(0)
; template <class Epi, class Sched>
; DI void gemm_phase(LAS unsigned char* lds, const Gemm g, const Sched& S, const Epi& E) {
;     ...
;             PG8_BAR; PG8_WAIT_L(0); PG8_MMA(0, 1, At, B1); PG8_BAR;
;             PG8_LDA(At, 0, 1); PG8_STAGE(PG8_SA(0, 0), a2, voffA);
;             PG8_BAR; PG8_WAIT_L(0); PG8_MMA(1, 0, At, B0); PG8_BAR; PG8_SCHED;
;             PG8_STAGE(PG8_SB(0, 1), b2 + hstep, voffB);
;             PG8_WAIT_V(6); PG8_BAR; PG8_MMA(1, 1, At, B1); PG8_BAR;
;             PG8_LDB(B0, 1, 0); PG8_SCHED; PG8_LDA(At, 1, 0); PG8_STAGE(PG8_SA(0, 1), a2 + hstep, voffA);
;             PG8_WAIT_L(8); PG8_BAR; PG8_WAIT_L(0); PG8_MMA(0, 0, At, B0); PG8_BAR; PG8_SCHED;
	s_waitcnt lgkmcnt(0)
	s_setprio 1
	v_mfma_f32_16x16x32_bf16 v[124:127], v[218:221], v[168:171], v[124:127]
	v_mfma_f32_16x16x32_bf16 v[120:123], v[226:229], v[168:171], v[120:123]
	v_mfma_f32_16x16x32_bf16 v[108:111], v[218:221], v[176:179], v[108:111]
	v_mfma_f32_16x16x32_bf16 v[104:107], v[226:229], v[176:179], v[104:107]
	v_mfma_f32_16x16x32_bf16 v[92:95], v[218:221], v[188:191], v[92:95]
	v_mfma_f32_16x16x32_bf16 v[88:91], v[226:229], v[188:191], v[88:91]
	v_mfma_f32_16x16x32_bf16 v[76:79], v[218:221], v[210:213], v[76:79]
	v_mfma_f32_16x16x32_bf16 v[72:75], v[226:229], v[210:213], v[72:75]
	v_mfma_f32_16x16x32_bf16 v[124:127], v[222:225], v[172:175], v[124:127]
	v_mfma_f32_16x16x32_bf16 v[120:123], v[230:233], v[172:175], v[120:123]
	v_mfma_f32_16x16x32_bf16 v[108:111], v[222:225], v[180:183], v[108:111]
	v_mfma_f32_16x16x32_bf16 v[104:107], v[230:233], v[180:183], v[104:107]
	v_mfma_f32_16x16x32_bf16 v[92:95], v[222:225], v[206:209], v[92:95]
	v_mfma_f32_16x16x32_bf16 v[88:91], v[230:233], v[206:209], v[88:91]
	v_mfma_f32_16x16x32_bf16 v[76:79], v[222:225], v[214:217], v[76:79]
	v_mfma_f32_16x16x32_bf16 v[72:75], v[230:233], v[214:217], v[72:75]
	s_setprio 0
	s_mov_b32 m0, s39
	s_barrier
	ds_read_b128 v[168:171], v150 offset:16384
	ds_read_b128 v[172:175], v150 offset:17408
	ds_read_b128 v[176:179], v150 offset:18432
	ds_read_b128 v[180:183], v150 offset:19456
	ds_read_b128 v[188:191], v150 offset:20480
	ds_read_b128 v[206:209], v150 offset:21504
	ds_read_b128 v[210:213], v150 offset:22528
	global_load_lds_dwordx4 v128, s[42:43]
	s_mov_b32 m0, s51
	ds_read_b128 v[214:217], v150 offset:23552
	global_load_lds_dwordx4 v132, s[42:43]
	s_barrier
	s_waitcnt lgkmcnt(0)
	s_setprio 1
	v_mfma_f32_16x16x32_bf16 v[52:55], v[144:147], v[168:171], v[52:55]
	v_mfma_f32_16x16x32_bf16 v[48:51], v[160:163], v[168:171], v[48:51]
	v_mfma_f32_16x16x32_bf16 v[36:39], v[144:147], v[176:179], v[36:39]
	v_mfma_f32_16x16x32_bf16 v[32:35], v[160:163], v[176:179], v[32:35]
	v_mfma_f32_16x16x32_bf16 v[20:23], v[144:147], v[188:191], v[20:23]
	v_mfma_f32_16x16x32_bf16 v[16:19], v[160:163], v[188:191], v[16:19]
	v_mfma_f32_16x16x32_bf16 v[4:7], v[144:147], v[210:213], v[4:7]
	v_mfma_f32_16x16x32_bf16 v[0:3], v[160:163], v[210:213], v[0:3]
	v_mfma_f32_16x16x32_bf16 v[52:55], v[156:159], v[172:175], v[52:55]
	v_mfma_f32_16x16x32_bf16 v[48:51], v[164:167], v[172:175], v[48:51]
	v_mfma_f32_16x16x32_bf16 v[36:39], v[156:159], v[180:183], v[36:39]
	v_mfma_f32_16x16x32_bf16 v[32:35], v[164:167], v[180:183], v[32:35]
	v_mfma_f32_16x16x32_bf16 v[20:23], v[156:159], v[206:209], v[20:23]
	v_mfma_f32_16x16x32_bf16 v[16:19], v[164:167], v[206:209], v[16:19]
	v_mfma_f32_16x16x32_bf16 v[4:7], v[156:159], v[214:217], v[4:7]
	v_mfma_f32_16x16x32_bf16 v[0:3], v[164:167], v[214:217], v[0:3]
	s_setprio 0
	s_barrier
	s_add_u32 s0, s40, 0x80000
	s_addc_u32 s1, s41, 0
	s_add_i32 s4, s62, s50
	s_mov_b32 m0, s4
	s_nop 0
	global_load_lds_dwordx4 v130, s[0:1]
	s_add_i32 m0, s4, 0x2000
	s_nop 0
	global_load_lds_dwordx4 v134, s[0:1]
	s_waitcnt vmcnt(6)
	s_barrier
	s_setprio 1
	v_mfma_f32_16x16x32_bf16 v[60:63], v[218:221], v[168:171], v[60:63]
	v_mfma_f32_16x16x32_bf16 v[56:59], v[226:229], v[168:171], v[56:59]
	v_mfma_f32_16x16x32_bf16 v[44:47], v[218:221], v[176:179], v[44:47]
	v_mfma_f32_16x16x32_bf16 v[40:43], v[226:229], v[176:179], v[40:43]
	v_mfma_f32_16x16x32_bf16 v[28:31], v[218:221], v[188:191], v[28:31]
	v_mfma_f32_16x16x32_bf16 v[24:27], v[226:229], v[188:191], v[24:27]
	v_mfma_f32_16x16x32_bf16 v[12:15], v[218:221], v[210:213], v[12:15]
	v_mfma_f32_16x16x32_bf16 v[8:11], v[226:229], v[210:213], v[8:11]
	v_mfma_f32_16x16x32_bf16 v[60:63], v[222:225], v[172:175], v[60:63]
	v_mfma_f32_16x16x32_bf16 v[56:59], v[230:233], v[172:175], v[56:59]
	v_mfma_f32_16x16x32_bf16 v[44:47], v[222:225], v[180:183], v[44:47]
	v_mfma_f32_16x16x32_bf16 v[40:43], v[230:233], v[180:183], v[40:43]
	v_mfma_f32_16x16x32_bf16 v[28:31], v[222:225], v[206:209], v[28:31]
	v_mfma_f32_16x16x32_bf16 v[24:27], v[230:233], v[206:209], v[24:27]
	v_mfma_f32_16x16x32_bf16 v[12:15], v[222:225], v[214:217], v[12:15]
	v_mfma_f32_16x16x32_bf16 v[8:11], v[230:233], v[214:217], v[8:11]
	s_setprio 0
	s_add_i32 s4, 0, 0x18000
	s_barrier
	ds_read_b128 v[144:147], v202
	ds_read_b128 v[156:159], v202 offset:1024
	ds_read_b128 v[160:163], v202 offset:2048
	ds_read_b128 v[164:167], v202 offset:3072
	s_add_u32 s0, s42, 0x80000
	s_addc_u32 s1, s43, 0
	s_mov_b32 m0, s52
	ds_read_b128 v[168:171], v150 offset:32768
	ds_read_b128 v[172:175], v150 offset:33792
	ds_read_b128 v[176:179], v150 offset:34816
	ds_read_b128 v[180:183], v150 offset:35840
	ds_read_b128 v[188:191], v150 offset:36864
	ds_read_b128 v[206:209], v150 offset:37888
	ds_read_b128 v[210:213], v150 offset:38912
	global_load_lds_dwordx4 v128, s[0:1]
	s_mov_b32 m0, s53
	ds_read_b128 v[214:217], v150 offset:39936
	global_load_lds_dwordx4 v132, s[0:1]
	s_waitcnt lgkmcnt(8)
	s_barrier
; #define PG8_STAGE(bufoff, gbase, voff) do { _Pragma("unroll") for (int _i = 0; _i < 2; ++_i) \
;         __builtin_amdgcn_global_load_lds((const unsigned*)((const char*)(gbase) + (voff)[_i]), (LAS unsigned*)(lds + (bufoff) + ldsw + _i * 8192), 16, 0, 0); } while (0)
; #define PG8_LDA(dst, b, h) do { _Pragma("unroll") for (int m = 0; m < 4; ++m) _Pragma("unroll") for (int k = 0; k < 2; ++k) dst[m][k] = *(const LAS bf16x8*)(lds + PG8_SA(b, h) + aoff + m * 2048 + k * 1024); } while (0)
; #define PG8_LDB(dst, b, h) do { _Pragma("unroll") for (int n = 0; n < 2; ++n) _Pragma("unroll") for (int k = 0; k < 2; ++k) dst[n][k] = *(const LAS bf16x8*)(lds + PG8_SB(b, h) + boff + n * 2048 + k * 1024); } while (0)
; #define PG8_MMA(ai, bj, At, Bt) do { __builtin_amdgcn_s_setprio(1); _Pragma("unroll") for (int m = 0; m < 4; ++m) _Pragma("unroll") for (int n = 0; n < 2; ++n) _Pragma("unroll") for (int k = 0; k < 2; ++k) \
;         acc[ai][bj][m][n] = __builtin_amdgcn_mfma_f32_16x16x32_bf16(Bt[n][k], At[m][k], acc[ai][bj][m][n], 0, 0, 0); __builtin_amdgcn_s_setprio(0); } while (0)
; #define PG8_WAIT_V(n) asm volatile("s_waitcnt vmcnt(" #n ")" ::: "memory")
; #define PG8_WAIT_L(n) asm volatile("s_waitcnt lgkmcnt(" #n ")" ::: "memory")
; #define PG8_BAR __builtin_amdgcn_s_barrier()
; #define PG8_SCHED __builtin_amdgcn_sched_barrier(0)
; template <class Epi, class Sched>
; DI void gemm_phase(LAS unsigned char* lds, const Gemm g, const Sched& S, const Epi& E) {
;     ...
;             PG8_WAIT_L(8); PG8_BAR; PG8_WAIT_L(0); PG8_MMA(0, 0, At, B0); PG8_BAR; PG8_SCHED;
;             PG8_LDB(B1, 1, 1); PG8_STAGE(PG8_SB(1, 0), b3, voffB);
;             PG8_BAR; PG8_WAIT_L(0); PG8_MMA(0, 1, At, B1); PG8_BAR;
;             PG8_LDA(At, 1, 1); PG8_STAGE(PG8_SA(1, 0), a3, voffA);
;             PG8_BAR; PG8_WAIT_L(0); PG8_MMA(1, 0, At, B0); PG8_BAR; PG8_SCHED;
;             PG8_STAGE(PG8_SB(1, 1), b3 + hstep, voffB);
;             PG8_WAIT_V(6); PG8_BAR; PG8_MMA(1, 1, At, B1); PG8_BAR;
	s_waitcnt lgkmcnt(0)
	s_setprio 1
	v_mfma_f32_16x16x32_bf16 v[116:119], v[144:147], v[168:171], v[116:119]
	v_mfma_f32_16x16x32_bf16 v[112:115], v[160:163], v[168:171], v[112:115]
	v_mfma_f32_16x16x32_bf16 v[100:103], v[144:147], v[176:179], v[100:103]
	v_mfma_f32_16x16x32_bf16 v[96:99], v[160:163], v[176:179], v[96:99]
	v_mfma_f32_16x16x32_bf16 v[84:87], v[144:147], v[188:191], v[84:87]
	v_mfma_f32_16x16x32_bf16 v[80:83], v[160:163], v[188:191], v[80:83]
	v_mfma_f32_16x16x32_bf16 v[68:71], v[144:147], v[210:213], v[68:71]
	v_mfma_f32_16x16x32_bf16 v[64:67], v[160:163], v[210:213], v[64:67]
	v_mfma_f32_16x16x32_bf16 v[116:119], v[156:159], v[172:175], v[116:119]
	v_mfma_f32_16x16x32_bf16 v[112:115], v[164:167], v[172:175], v[112:115]
	v_mfma_f32_16x16x32_bf16 v[100:103], v[156:159], v[180:183], v[100:103]
	v_mfma_f32_16x16x32_bf16 v[96:99], v[164:167], v[180:183], v[96:99]
	v_mfma_f32_16x16x32_bf16 v[84:87], v[156:159], v[206:209], v[84:87]
	v_mfma_f32_16x16x32_bf16 v[80:83], v[164:167], v[206:209], v[80:83]
	v_mfma_f32_16x16x32_bf16 v[68:71], v[156:159], v[214:217], v[68:71]
	v_mfma_f32_16x16x32_bf16 v[64:67], v[164:167], v[214:217], v[64:67]
	s_setprio 0
	s_barrier
	s_add_i32 s5, 0, 0x1c000
	s_add_i32 s0, s4, s50
	s_add_i32 m0, s0, 0xffffff80
	ds_read_b128 v[218:221], v203
	ds_read_b128 v[222:225], v203 offset:1024
	ds_read_b128 v[226:229], v203 offset:2048
	global_load_lds_dwordx4 v130, s[40:41] offset:128
	s_add_i32 m0, s0, 0x1f80
	ds_read_b128 v[230:233], v203 offset:3072
	global_load_lds_dwordx4 v134, s[40:41] offset:128
	s_barrier
	s_waitcnt lgkmcnt(0)
	s_setprio 1
	v_mfma_f32_16x16x32_bf16 v[124:127], v[218:221], v[168:171], v[124:127]
	v_mfma_f32_16x16x32_bf16 v[120:123], v[226:229], v[168:171], v[120:123]
	v_mfma_f32_16x16x32_bf16 v[108:111], v[218:221], v[176:179], v[108:111]
	v_mfma_f32_16x16x32_bf16 v[104:107], v[226:229], v[176:179], v[104:107]
	v_mfma_f32_16x16x32_bf16 v[92:95], v[218:221], v[188:191], v[92:95]
	v_mfma_f32_16x16x32_bf16 v[88:91], v[226:229], v[188:191], v[88:91]
	v_mfma_f32_16x16x32_bf16 v[76:79], v[218:221], v[210:213], v[76:79]
	v_mfma_f32_16x16x32_bf16 v[72:75], v[226:229], v[210:213], v[72:75]
	v_mfma_f32_16x16x32_bf16 v[124:127], v[222:225], v[172:175], v[124:127]
	v_mfma_f32_16x16x32_bf16 v[120:123], v[230:233], v[172:175], v[120:123]
	v_mfma_f32_16x16x32_bf16 v[108:111], v[222:225], v[180:183], v[108:111]
	v_mfma_f32_16x16x32_bf16 v[104:107], v[230:233], v[180:183], v[104:107]
	v_mfma_f32_16x16x32_bf16 v[92:95], v[222:225], v[206:209], v[92:95]
	v_mfma_f32_16x16x32_bf16 v[88:91], v[230:233], v[206:209], v[88:91]
	v_mfma_f32_16x16x32_bf16 v[76:79], v[222:225], v[214:217], v[76:79]
	v_mfma_f32_16x16x32_bf16 v[72:75], v[230:233], v[214:217], v[72:75]
	s_setprio 0
	s_add_i32 m0, s57, 0xffffff80
	s_barrier
	ds_read_b128 v[168:171], v150 offset:49152
	ds_read_b128 v[172:175], v150 offset:50176
	ds_read_b128 v[176:179], v150 offset:51200
	ds_read_b128 v[180:183], v150 offset:52224
	ds_read_b128 v[188:191], v150 offset:53248
	ds_read_b128 v[206:209], v150 offset:54272
	ds_read_b128 v[210:213], v150 offset:55296
	global_load_lds_dwordx4 v128, s[42:43] offset:128
	s_add_i32 m0, s58, 0xffffff80
	ds_read_b128 v[214:217], v150 offset:56320
	global_load_lds_dwordx4 v132, s[42:43] offset:128
	s_barrier
	s_waitcnt lgkmcnt(0)
	s_setprio 1
	v_mfma_f32_16x16x32_bf16 v[52:55], v[144:147], v[168:171], v[52:55]
	v_mfma_f32_16x16x32_bf16 v[48:51], v[160:163], v[168:171], v[48:51]
	v_mfma_f32_16x16x32_bf16 v[36:39], v[144:147], v[176:179], v[36:39]
	v_mfma_f32_16x16x32_bf16 v[32:35], v[160:163], v[176:179], v[32:35]
	v_mfma_f32_16x16x32_bf16 v[20:23], v[144:147], v[188:191], v[20:23]
	v_mfma_f32_16x16x32_bf16 v[16:19], v[160:163], v[188:191], v[16:19]
	v_mfma_f32_16x16x32_bf16 v[4:7], v[144:147], v[210:213], v[4:7]
	v_mfma_f32_16x16x32_bf16 v[0:3], v[160:163], v[210:213], v[0:3]
	v_mfma_f32_16x16x32_bf16 v[52:55], v[156:159], v[172:175], v[52:55]
	v_mfma_f32_16x16x32_bf16 v[48:51], v[164:167], v[172:175], v[48:51]
	v_mfma_f32_16x16x32_bf16 v[36:39], v[156:159], v[180:183], v[36:39]
	v_mfma_f32_16x16x32_bf16 v[32:35], v[164:167], v[180:183], v[32:35]
	v_mfma_f32_16x16x32_bf16 v[20:23], v[156:159], v[206:209], v[20:23]
	v_mfma_f32_16x16x32_bf16 v[16:19], v[164:167], v[206:209], v[16:19]
	v_mfma_f32_16x16x32_bf16 v[4:7], v[156:159], v[214:217], v[4:7]
	v_mfma_f32_16x16x32_bf16 v[0:3], v[164:167], v[214:217], v[0:3]
	s_setprio 0
	s_barrier
	s_add_u32 s0, s40, 0x80080
	s_addc_u32 s1, s41, 0
	s_add_i32 s4, s5, s50
	s_mov_b32 m0, s4
	s_nop 0
	global_load_lds_dwordx4 v130, s[0:1]
	s_add_i32 m0, s4, 0x2000
	s_nop 0
	global_load_lds_dwordx4 v134, s[0:1]
	s_waitcnt vmcnt(6)
	s_barrier
	s_setprio 1
	v_mfma_f32_16x16x32_bf16 v[60:63], v[218:221], v[168:171], v[60:63]
	v_mfma_f32_16x16x32_bf16 v[56:59], v[226:229], v[168:171], v[56:59]
	v_mfma_f32_16x16x32_bf16 v[44:47], v[218:221], v[176:179], v[44:47]
	v_mfma_f32_16x16x32_bf16 v[40:43], v[226:229], v[176:179], v[40:43]
	v_mfma_f32_16x16x32_bf16 v[28:31], v[218:221], v[188:191], v[28:31]
	v_mfma_f32_16x16x32_bf16 v[24:27], v[226:229], v[188:191], v[24:27]
	v_mfma_f32_16x16x32_bf16 v[12:15], v[218:221], v[210:213], v[12:15]
	v_mfma_f32_16x16x32_bf16 v[8:11], v[226:229], v[210:213], v[8:11]
	v_mfma_f32_16x16x32_bf16 v[60:63], v[222:225], v[172:175], v[60:63]
	v_mfma_f32_16x16x32_bf16 v[56:59], v[230:233], v[172:175], v[56:59]
	v_mfma_f32_16x16x32_bf16 v[44:47], v[222:225], v[180:183], v[44:47]
	v_mfma_f32_16x16x32_bf16 v[40:43], v[230:233], v[180:183], v[40:43]
	v_mfma_f32_16x16x32_bf16 v[28:31], v[222:225], v[206:209], v[28:31]
	v_mfma_f32_16x16x32_bf16 v[24:27], v[230:233], v[206:209], v[24:27]
	v_mfma_f32_16x16x32_bf16 v[12:15], v[222:225], v[214:217], v[12:15]
	v_mfma_f32_16x16x32_bf16 v[8:11], v[230:233], v[214:217], v[8:11]
	s_setprio 0
	s_add_i32 s68, s68, 2
	s_add_u32 s8, s8, 0x100
	s_addc_u32 s9, s9, 0
	s_add_u32 s66, s66, 0x100
	s_addc_u32 s67, s67, 0
	s_cmp_gt_u32 s68, 29
	s_barrier
	s_cbranch_scc0 .LBB0_1668

;     DI size_t aoff(const Unit& u, size_t tstep) const { return (size_t)u.pm * tstep; }
;     DI size_t boff(const Unit& u, size_t tstep) const { return (size_t)u.pn * tstep; }
;     DI bool next(int i, Unit& u) const { const long L = (long)i * G + c; if (L >= np) return false; u.pm = pmv; u.pn = (int)(L % nN); u.ks = (int)(L / nN); return true; }
;     DI size_t aoff(const Unit& u, size_t) const { return (size_t)u.ks * kbytes; }
;     DI size_t boff(const Unit& u, size_t tstep) const { return (size_t)u.pn * tstep + (size_t)u.ks * kbytes; }
;     DI bool next(int i, Unit& u) const { Unit t; if (!S.next(i / 3, t)) return false; u.pm = t.pm; u.pn = t.pn; u.ks = i % 3; return true; }
;     DI size_t aoff(const Unit& u, size_t tstep) const { return (u.ks < 2 ? offU : offOA) + (size_t)u.pm * tstep; }
; #define PG8_WAIT_L(n) asm volatile("s_waitcnt lgkmcnt(" #n ")" ::: "memory")
; #define PG8_BAR __builtin_amdgcn_s_barrier()
; template <class Epi, class Sched>
; DI void gemm_phase(LAS unsigned char* lds, const Gemm g, const Sched& S, const Epi& E) {
;     ...
;         const bool has_next = S.next(ui + 1, nxt);
;         const char* nA = has_next ? (const char*)g.A + S.aoff(nxt, tstep) : cA; const char* nB = has_next ? (const char*)g.Bt + S.boff(nxt, tstep) : cB;
;         for (int t = 0; t < nt; t += 2) {
;             if constexpr (Epi::HAS_MID) { if (t == E.mid_t(nt)) { int fr3 = fr, fq3 = fq; asm volatile("" : "+v"(fr3), "+v"(fq3)); E.mid(acc, cur, wr, wc, fr3, fq3); } }
;             const bool last = (t == nt - 2);
;             const char* a1 = cA + (size_t)(t + 1) * kstep;
;             const char* a2 = last ? nA : cA + (size_t)(t + 2) * kstep; const char* b2 = last ? nB : cB + (size_t)(t + 2) * kstep;
;             const char* a3 = a2 + kstep; const char* b3 = b2 + kstep;
;             PG8_LDB(B0, 0, 0); PG8_SCHED; PG8_LDA(At, 0, 0); PG8_STAGE(PG8_SA(1, 1), a1 + hstep, voffA);
;             PG8_WAIT_L(8); PG8_BAR; PG8_WAIT_L(0); PG8_MMA(0, 0, At, B0); PG8_BAR; PG8_SCHED;
;             PG8_LDB(B1, 0, 1); PG8_STAGE(PG8_SB(0, 0), b2, voffB);
;             PG8_BAR; PG8_WAIT_L(0); PG8_MMA(0, 1, At, B1); PG8_BAR;
;             PG8_LDA(At, 0, 1); PG8_STAGE(PG8_SA(0, 0), a2, voffA);
;             PG8_BAR; PG8_WAIT_L(0); PG8_MMA(1, 0, At, B0); PG8_BAR; PG8_SCHED;
;             PG8_STAGE(PG8_SB(0, 1), b2 + hstep, voffB);
.LBB0_1745:
	s_add_u32 s38, s38, 0x160080
	s_addc_u32 s39, s39, 0
	s_add_u32 s35, s40, 0x100
	v_mov_b32_e32 v0, 0
	s_addc_u32 s67, s41, 0
	s_mov_b32 s68, -2
	s_waitcnt lgkmcnt(0)
	ds_read_b128 v[144:147], v155
	ds_read_b128 v[160:163], v155 offset:1024
	ds_read_b128 v[164:167], v155 offset:2048
	ds_read_b128 v[168:171], v155 offset:3072
	s_add_u32 s0, s38, 0xffea0080
	s_addc_u32 s1, s39, -1
	s_cmpk_eq_i32 s68, 0x54
	s_cselect_b32 s43, s9, s1
	s_cselect_b32 s42, s8, s0
	s_cselect_b32 s41, s11, s67
	s_cselect_b32 s40, s10, s35
	s_add_i32 m0, s52, 0xc000
	ds_read_b128 v[172:175], v156
	ds_read_b128 v[176:179], v156 offset:1024
	ds_read_b128 v[180:183], v156 offset:2048
	ds_read_b128 v[188:191], v156 offset:3072
	ds_read_b128 v[206:209], v156 offset:4096
	ds_read_b128 v[210:213], v156 offset:5120
	ds_read_b128 v[214:217], v156 offset:6144
	global_load_lds_dwordx4 v136, s[38:39]
	s_add_i32 m0, s52, 0xe000
	ds_read_b128 v[218:221], v156 offset:7168
	global_load_lds_dwordx4 v138, s[38:39]
	s_waitcnt lgkmcnt(8)
	s_barrier
	s_waitcnt lgkmcnt(0)
	s_setprio 1
	v_mfma_f32_16x16x32_bf16 v[124:127], v[144:147], v[172:175], 0
	v_mfma_f32_16x16x32_bf16 v[120:123], v[164:167], v[172:175], 0
	v_mfma_f32_16x16x32_bf16 v[108:111], v[144:147], v[180:183], 0
	v_mfma_f32_16x16x32_bf16 v[104:107], v[164:167], v[180:183], 0
	v_mfma_f32_16x16x32_bf16 v[92:95], v[144:147], v[206:209], 0
	v_mfma_f32_16x16x32_bf16 v[88:91], v[164:167], v[206:209], 0
	v_mfma_f32_16x16x32_bf16 v[76:79], v[144:147], v[214:217], 0
	v_mfma_f32_16x16x32_bf16 v[72:75], v[164:167], v[214:217], 0
	v_mfma_f32_16x16x32_bf16 v[124:127], v[160:163], v[176:179], v[124:127]
	v_mfma_f32_16x16x32_bf16 v[120:123], v[168:171], v[176:179], v[120:123]
	v_mfma_f32_16x16x32_bf16 v[108:111], v[160:163], v[188:191], v[108:111]
	v_mfma_f32_16x16x32_bf16 v[104:107], v[168:171], v[188:191], v[104:107]
	v_mfma_f32_16x16x32_bf16 v[92:95], v[160:163], v[210:213], v[92:95]
	v_mfma_f32_16x16x32_bf16 v[88:91], v[168:171], v[210:213], v[88:91]
	v_mfma_f32_16x16x32_bf16 v[76:79], v[160:163], v[218:221], v[76:79]
	v_mfma_f32_16x16x32_bf16 v[72:75], v[168:171], v[218:221], v[72:75]
	s_setprio 0
	s_barrier
	s_add_i32 s0, s61, s51
	s_mov_b32 m0, s0
	ds_read_b128 v[222:225], v157
	ds_read_b128 v[226:229], v157 offset:1024
	ds_read_b128 v[230:233], v157 offset:2048
	global_load_lds_dwordx4 v130, s[40:41]
	s_add_i32 m0, s0, 0x2000
	ds_read_b128 v[234:237], v157 offset:3072
	global_load_lds_dwordx4 v134, s[40:41]
	s_barrier
	s_waitcnt lgkmcnt(0)
	s_setprio 1
	v_mfma_f32_16x16x32_bf16 v[116:119], v[222:225], v[172:175], 0
	v_mfma_f32_16x16x32_bf16 v[112:115], v[230:233], v[172:175], 0
	v_mfma_f32_16x16x32_bf16 v[100:103], v[222:225], v[180:183], 0
	v_mfma_f32_16x16x32_bf16 v[96:99], v[230:233], v[180:183], 0
	v_mfma_f32_16x16x32_bf16 v[84:87], v[222:225], v[206:209], 0
	v_mfma_f32_16x16x32_bf16 v[80:83], v[230:233], v[206:209], 0
	v_mfma_f32_16x16x32_bf16 v[68:71], v[222:225], v[214:217], 0
	v_mfma_f32_16x16x32_bf16 v[64:67], v[230:233], v[214:217], 0
	v_mfma_f32_16x16x32_bf16 v[116:119], v[226:229], v[176:179], v[116:119]
	v_mfma_f32_16x16x32_bf16 v[112:115], v[234:237], v[176:179], v[112:115]
	v_mfma_f32_16x16x32_bf16 v[100:103], v[226:229], v[188:191], v[100:103]
	v_mfma_f32_16x16x32_bf16 v[96:99], v[234:237], v[188:191], v[96:99]
	v_mfma_f32_16x16x32_bf16 v[84:87], v[226:229], v[210:213], v[84:87]
	v_mfma_f32_16x16x32_bf16 v[80:83], v[234:237], v[210:213], v[80:83]
	v_mfma_f32_16x16x32_bf16 v[68:71], v[226:229], v[218:221], v[68:71]
	v_mfma_f32_16x16x32_bf16 v[64:67], v[234:237], v[218:221], v[64:67]
	s_setprio 0
	s_mov_b32 m0, s52
	s_barrier
	ds_read_b128 v[172:175], v156 offset:16384
	ds_read_b128 v[176:179], v156 offset:17408
	ds_read_b128 v[180:183], v156 offset:18432
	ds_read_b128 v[188:191], v156 offset:19456
	ds_read_b128 v[206:209], v156 offset:20480
	ds_read_b128 v[210:213], v156 offset:21504
	ds_read_b128 v[214:217], v156 offset:22528
	global_load_lds_dwordx4 v128, s[42:43]
	s_mov_b32 m0, s53
	ds_read_b128 v[218:221], v156 offset:23552
	global_load_lds_dwordx4 v132, s[42:43]
	s_barrier
	s_waitcnt lgkmcnt(0)
	s_setprio 1
	v_mfma_f32_16x16x32_bf16 v[60:63], v[144:147], v[172:175], 0
	v_mfma_f32_16x16x32_bf16 v[56:59], v[164:167], v[172:175], 0
	v_mfma_f32_16x16x32_bf16 v[44:47], v[144:147], v[180:183], 0
	v_mfma_f32_16x16x32_bf16 v[40:43], v[164:167], v[180:183], 0
	v_mfma_f32_16x16x32_bf16 v[28:31], v[144:147], v[206:209], 0
	v_mfma_f32_16x16x32_bf16 v[24:27], v[164:167], v[206:209], 0
	v_mfma_f32_16x16x32_bf16 v[12:15], v[144:147], v[214:217], 0
	v_mfma_f32_16x16x32_bf16 v[8:11], v[164:167], v[214:217], 0
	v_mfma_f32_16x16x32_bf16 v[60:63], v[160:163], v[176:179], v[60:63]
	v_mfma_f32_16x16x32_bf16 v[56:59], v[168:171], v[176:179], v[56:59]
	v_mfma_f32_16x16x32_bf16 v[44:47], v[160:163], v[188:191], v[44:47]
	v_mfma_f32_16x16x32_bf16 v[40:43], v[168:171], v[188:191], v[40:43]
	v_mfma_f32_16x16x32_bf16 v[28:31], v[160:163], v[210:213], v[28:31]
	v_mfma_f32_16x16x32_bf16 v[24:27], v[168:171], v[210:213], v[24:27]
	v_mfma_f32_16x16x32_bf16 v[12:15], v[160:163], v[218:221], v[12:15]
	v_mfma_f32_16x16x32_bf16 v[8:11], v[168:171], v[218:221], v[8:11]
	s_setprio 0
	s_barrier
	s_add_u32 s0, s40, 0x160000
	s_addc_u32 s1, s41, 0
	s_add_i32 s4, s62, s51
	s_mov_b32 m0, s4
	s_nop 0
	global_load_lds_dwordx4 v130, s[0:1]
	s_add_i32 m0, s4, 0x2000
	s_nop 0
	global_load_lds_dwordx4 v134, s[0:1]
	s_waitcnt vmcnt(6)
	s_barrier
; #define PG8_STAGE(bufoff, gbase, voff) do { _Pragma("unroll") for (int _i = 0; _i < 2; ++_i) \
;         __builtin_amdgcn_global_load_lds((const unsigned*)((const char*)(gbase) + (voff)[_i]), (LAS unsigned*)(lds + (bufoff) + ldsw + _i * 8192), 16, 0, 0); } while (0)
; #define PG8_LDA(dst, b, h) do { _Pragma("unroll") for (int m = 0; m < 4; ++m) _Pragma("unroll") for (int k = 0; k < 2; ++k) dst[m][k] = *(const LAS bf16x8*)(lds + PG8_SA(b, h) + aoff + m * 2048 + k * 1024); } while (0)
; #define PG8_LDB(dst, b, h) do { _Pragma("unroll") for (int n = 0; n < 2; ++n) _Pragma("unroll") for (int k = 0; k < 2; ++k) dst[n][k] = *(const LAS bf16x8*)(lds + PG8_SB(b, h) + boff + n * 2048 + k * 1024); } while (0)
; #define PG8_MMA(ai, bj, At, Bt) do { __builtin_amdgcn_s_setprio(1); _Pragma("unroll") for (int m = 0; m < 4; ++m) _Pragma("unroll") for (int n = 0; n < 2; ++n) _Pragma("unroll") for (int k = 0; k < 2; ++k) \
;         acc[ai][bj][m][n] = __builtin_amdgcn_mfma_f32_16x16x32_bf16(Bt[n][k], At[m][k], acc[ai][bj][m][n], 0, 0, 0); __builtin_amdgcn_s_setprio(0); } while (0)
; #define PG8_WAIT_V(n) asm volatile("s_waitcnt vmcnt(" #n ")" ::: "memory")
; #define PG8_WAIT_L(n) asm volatile("s_waitcnt lgkmcnt(" #n ")" ::: "memory")
; #define PG8_BAR __builtin_amdgcn_s_barrier()
; #define PG8_SCHED __builtin_amdgcn_sched_barrier(0)
; template <class Epi, class Sched>
; DI void gemm_phase(LAS unsigned char* lds, const Gemm g, const Sched& S, const Epi& E) {
;     ...
;             PG8_STAGE(PG8_SB(0, 1), b2 + hstep, voffB);
;             PG8_WAIT_V(6); PG8_BAR; PG8_MMA(1, 1, At, B1); PG8_BAR;
;             PG8_LDB(B0, 1, 0); PG8_SCHED; PG8_LDA(At, 1, 0); PG8_STAGE(PG8_SA(0, 1), a2 + hstep, voffA);
;             PG8_WAIT_L(8); PG8_BAR; PG8_WAIT_L(0); PG8_MMA(0, 0, At, B0); PG8_BAR; PG8_SCHED;
;             PG8_LDB(B1, 1, 1); PG8_STAGE(PG8_SB(1, 0), b3, voffB);
;             PG8_BAR; PG8_WAIT_L(0); PG8_MMA(0, 1, At, B1); PG8_BAR;
;             PG8_LDA(At, 1, 1); PG8_STAGE(PG8_SA(1, 0), a3, voffA);
;             PG8_BAR; PG8_WAIT_L(0); PG8_MMA(1, 0, At, B0); PG8_BAR; PG8_SCHED;
	s_setprio 1
	v_mfma_f32_16x16x32_bf16 v[52:55], v[222:225], v[172:175], 0
	v_mfma_f32_16x16x32_bf16 v[48:51], v[230:233], v[172:175], 0
	v_mfma_f32_16x16x32_bf16 v[36:39], v[222:225], v[180:183], 0
	v_mfma_f32_16x16x32_bf16 v[32:35], v[230:233], v[180:183], 0
	v_mfma_f32_16x16x32_bf16 v[20:23], v[222:225], v[206:209], 0
	v_mfma_f32_16x16x32_bf16 v[16:19], v[230:233], v[206:209], 0
	v_mfma_f32_16x16x32_bf16 v[4:7], v[222:225], v[214:217], 0
	v_mfma_f32_16x16x32_bf16 v[0:3], v[230:233], v[214:217], 0
	v_mfma_f32_16x16x32_bf16 v[52:55], v[226:229], v[176:179], v[52:55]
	v_mfma_f32_16x16x32_bf16 v[48:51], v[234:237], v[176:179], v[48:51]
	v_mfma_f32_16x16x32_bf16 v[36:39], v[226:229], v[188:191], v[36:39]
	v_mfma_f32_16x16x32_bf16 v[32:35], v[234:237], v[188:191], v[32:35]
	v_mfma_f32_16x16x32_bf16 v[20:23], v[226:229], v[210:213], v[20:23]
	v_mfma_f32_16x16x32_bf16 v[16:19], v[234:237], v[210:213], v[16:19]
	v_mfma_f32_16x16x32_bf16 v[4:7], v[226:229], v[218:221], v[4:7]
	v_mfma_f32_16x16x32_bf16 v[0:3], v[234:237], v[218:221], v[0:3]
	s_setprio 0
	s_add_i32 s4, 0, 0x18000
	v_add_u32_e32 v202, s4, v154
	s_barrier
	ds_read_b128 v[144:147], v202
	ds_read_b128 v[160:163], v202 offset:1024
	ds_read_b128 v[164:167], v202 offset:2048
	ds_read_b128 v[168:171], v202 offset:3072
	s_add_u32 s0, s42, 0x160000
	s_addc_u32 s1, s43, 0
	s_mov_b32 m0, s54
	ds_read_b128 v[172:175], v156 offset:32768
	ds_read_b128 v[176:179], v156 offset:33792
	ds_read_b128 v[180:183], v156 offset:34816
	ds_read_b128 v[188:191], v156 offset:35840
	ds_read_b128 v[206:209], v156 offset:36864
	ds_read_b128 v[210:213], v156 offset:37888
	ds_read_b128 v[214:217], v156 offset:38912
	global_load_lds_dwordx4 v128, s[0:1]
	s_mov_b32 m0, s55
	ds_read_b128 v[218:221], v156 offset:39936
	global_load_lds_dwordx4 v132, s[0:1]
	s_waitcnt lgkmcnt(8)
	s_barrier
	s_waitcnt lgkmcnt(0)
	s_setprio 1
	v_mfma_f32_16x16x32_bf16 v[124:127], v[144:147], v[172:175], v[124:127]
	v_mfma_f32_16x16x32_bf16 v[120:123], v[164:167], v[172:175], v[120:123]
	v_mfma_f32_16x16x32_bf16 v[108:111], v[144:147], v[180:183], v[108:111]
	v_mfma_f32_16x16x32_bf16 v[104:107], v[164:167], v[180:183], v[104:107]
	v_mfma_f32_16x16x32_bf16 v[92:95], v[144:147], v[206:209], v[92:95]
	v_mfma_f32_16x16x32_bf16 v[88:91], v[164:167], v[206:209], v[88:91]
	v_mfma_f32_16x16x32_bf16 v[76:79], v[144:147], v[214:217], v[76:79]
	v_mfma_f32_16x16x32_bf16 v[72:75], v[164:167], v[214:217], v[72:75]
	v_mfma_f32_16x16x32_bf16 v[124:127], v[160:163], v[176:179], v[124:127]
	v_mfma_f32_16x16x32_bf16 v[120:123], v[168:171], v[176:179], v[120:123]
	v_mfma_f32_16x16x32_bf16 v[108:111], v[160:163], v[188:191], v[108:111]
	v_mfma_f32_16x16x32_bf16 v[104:107], v[168:171], v[188:191], v[104:107]
	v_mfma_f32_16x16x32_bf16 v[92:95], v[160:163], v[210:213], v[92:95]
	v_mfma_f32_16x16x32_bf16 v[88:91], v[168:171], v[210:213], v[88:91]
	v_mfma_f32_16x16x32_bf16 v[76:79], v[160:163], v[218:221], v[76:79]
	v_mfma_f32_16x16x32_bf16 v[72:75], v[168:171], v[218:221], v[72:75]
	s_setprio 0
	s_barrier
	s_add_i32 s5, 0, 0x1c000
	s_add_i32 s0, s4, s51
	v_add_u32_e32 v203, s5, v154
	s_add_i32 m0, s0, 0xffffff80
	ds_read_b128 v[222:225], v203
	ds_read_b128 v[226:229], v203 offset:1024
	ds_read_b128 v[230:233], v203 offset:2048
	global_load_lds_dwordx4 v130, s[40:41] offset:128
	s_add_i32 m0, s0, 0x1f80
	ds_read_b128 v[234:237], v203 offset:3072
	global_load_lds_dwordx4 v134, s[40:41] offset:128
	s_barrier
	s_waitcnt lgkmcnt(0)
	s_setprio 1
	v_mfma_f32_16x16x32_bf16 v[116:119], v[222:225], v[172:175], v[116:119]
	v_mfma_f32_16x16x32_bf16 v[112:115], v[230:233], v[172:175], v[112:115]
	v_mfma_f32_16x16x32_bf16 v[100:103], v[222:225], v[180:183], v[100:103]
	v_mfma_f32_16x16x32_bf16 v[96:99], v[230:233], v[180:183], v[96:99]
	v_mfma_f32_16x16x32_bf16 v[84:87], v[222:225], v[206:209], v[84:87]
	v_mfma_f32_16x16x32_bf16 v[80:83], v[230:233], v[206:209], v[80:83]
	v_mfma_f32_16x16x32_bf16 v[68:71], v[222:225], v[214:217], v[68:71]
	v_mfma_f32_16x16x32_bf16 v[64:67], v[230:233], v[214:217], v[64:67]
	v_mfma_f32_16x16x32_bf16 v[116:119], v[226:229], v[176:179], v[116:119]
	v_mfma_f32_16x16x32_bf16 v[112:115], v[234:237], v[176:179], v[112:115]
	v_mfma_f32_16x16x32_bf16 v[100:103], v[226:229], v[188:191], v[100:103]
	v_mfma_f32_16x16x32_bf16 v[96:99], v[234:237], v[188:191], v[96:99]
	v_mfma_f32_16x16x32_bf16 v[84:87], v[226:229], v[210:213], v[84:87]
	v_mfma_f32_16x16x32_bf16 v[80:83], v[234:237], v[210:213], v[80:83]
	v_mfma_f32_16x16x32_bf16 v[68:71], v[226:229], v[218:221], v[68:71]
	v_mfma_f32_16x16x32_bf16 v[64:67], v[234:237], v[218:221], v[64:67]
	s_setprio 0
	s_add_i32 m0, s59, 0xffffff80
	s_barrier
	ds_read_b128 v[172:175], v156 offset:49152
	ds_read_b128 v[176:179], v156 offset:50176
	ds_read_b128 v[180:183], v156 offset:51200
	ds_read_b128 v[188:191], v156 offset:52224
	ds_read_b128 v[206:209], v156 offset:53248
	ds_read_b128 v[210:213], v156 offset:54272
	ds_read_b128 v[214:217], v156 offset:55296
	global_load_lds_dwordx4 v128, s[42:43] offset:128
	s_add_i32 m0, s60, 0xffffff80
	ds_read_b128 v[218:221], v156 offset:56320
	global_load_lds_dwordx4 v132, s[42:43] offset:128
	s_barrier
; #define PG8_STAGE(bufoff, gbase, voff) do { _Pragma("unroll") for (int _i = 0; _i < 2; ++_i) \
;         __builtin_amdgcn_global_load_lds((const unsigned*)((const char*)(gbase) + (voff)[_i]), (LAS unsigned*)(lds + (bufoff) + ldsw + _i * 8192), 16, 0, 0); } while (0)
; #define PG8_LDA(dst, b, h) do { _Pragma("unroll") for (int m = 0; m < 4; ++m) _Pragma("unroll") for (int k = 0; k < 2; ++k) dst[m][k] = *(const LAS bf16x8*)(lds + PG8_SA(b, h) + aoff + m * 2048 + k * 1024); } while (0)
; #define PG8_LDB(dst, b, h) do { _Pragma("unroll") for (int n = 0; n < 2; ++n) _Pragma("unroll") for (int k = 0; k < 2; ++k) dst[n][k] = *(const LAS bf16x8*)(lds + PG8_SB(b, h) + boff + n * 2048 + k * 1024); } while (0)
; #define PG8_MMA(ai, bj, At, Bt) do { __builtin_amdgcn_s_setprio(1); _Pragma("unroll") for (int m = 0; m < 4; ++m) _Pragma("unroll") for (int n = 0; n < 2; ++n) _Pragma("unroll") for (int k = 0; k < 2; ++k) \
;         acc[ai][bj][m][n] = __builtin_amdgcn_mfma_f32_16x16x32_bf16(Bt[n][k], At[m][k], acc[ai][bj][m][n], 0, 0, 0); __builtin_amdgcn_s_setprio(0); } while (0)
; #define PG8_WAIT_V(n) asm volatile("s_waitcnt vmcnt(" #n ")" ::: "memory")
; #define PG8_WAIT_L(n) asm volatile("s_waitcnt lgkmcnt(" #n ")" ::: "memory")
; #define PG8_BAR __builtin_amdgcn_s_barrier()
; #define PG8_SCHED __builtin_amdgcn_sched_barrier(0)
; template <class Epi, class Sched>
; DI void gemm_phase(LAS unsigned char* lds, const Gemm g, const Sched& S, const Epi& E) {
;     ...
;             PG8_LDB(B0, 0, 0); PG8_SCHED; PG8_LDA(At, 0, 0); PG8_STAGE(PG8_SA(1, 1), a1 + hstep, voffA);
;             PG8_WAIT_L(8); PG8_BAR; PG8_WAIT_L(0); PG8_MMA(0, 0, At, B0); PG8_BAR; PG8_SCHED;
;             PG8_LDB(B1, 0, 1); PG8_STAGE(PG8_SB(0, 0), b2, voffB);
;             PG8_BAR; PG8_WAIT_L(0); PG8_MMA(0, 1, At, B1); PG8_BAR;
;     ...
;             PG8_BAR; PG8_WAIT_L(0); PG8_MMA(1, 0, At, B0); PG8_BAR; PG8_SCHED;
;             PG8_STAGE(PG8_SB(1, 1), b3 + hstep, voffB);
;             PG8_WAIT_V(6); PG8_BAR; PG8_MMA(1, 1, At, B1); PG8_BAR;
	s_waitcnt lgkmcnt(0)
	s_setprio 1
	v_mfma_f32_16x16x32_bf16 v[60:63], v[144:147], v[172:175], v[60:63]
	v_mfma_f32_16x16x32_bf16 v[56:59], v[164:167], v[172:175], v[56:59]
	v_mfma_f32_16x16x32_bf16 v[44:47], v[144:147], v[180:183], v[44:47]
	v_mfma_f32_16x16x32_bf16 v[40:43], v[164:167], v[180:183], v[40:43]
	v_mfma_f32_16x16x32_bf16 v[28:31], v[144:147], v[206:209], v[28:31]
	v_mfma_f32_16x16x32_bf16 v[24:27], v[164:167], v[206:209], v[24:27]
	v_mfma_f32_16x16x32_bf16 v[12:15], v[144:147], v[214:217], v[12:15]
	v_mfma_f32_16x16x32_bf16 v[8:11], v[164:167], v[214:217], v[8:11]
	v_mfma_f32_16x16x32_bf16 v[60:63], v[160:163], v[176:179], v[60:63]
	v_mfma_f32_16x16x32_bf16 v[56:59], v[168:171], v[176:179], v[56:59]
	v_mfma_f32_16x16x32_bf16 v[44:47], v[160:163], v[188:191], v[44:47]
	v_mfma_f32_16x16x32_bf16 v[40:43], v[168:171], v[188:191], v[40:43]
	v_mfma_f32_16x16x32_bf16 v[28:31], v[160:163], v[210:213], v[28:31]
	v_mfma_f32_16x16x32_bf16 v[24:27], v[168:171], v[210:213], v[24:27]
	v_mfma_f32_16x16x32_bf16 v[12:15], v[160:163], v[218:221], v[12:15]
	v_mfma_f32_16x16x32_bf16 v[8:11], v[168:171], v[218:221], v[8:11]
	s_setprio 0
	s_barrier
	s_add_u32 s0, s40, 0x160080
	s_addc_u32 s1, s41, 0
	s_add_i32 s4, s5, s51
	s_mov_b32 m0, s4
	s_nop 0
	global_load_lds_dwordx4 v130, s[0:1]
	s_add_i32 m0, s4, 0x2000
	s_nop 0
	global_load_lds_dwordx4 v134, s[0:1]
	s_waitcnt vmcnt(6)
	s_barrier
	s_setprio 1
	v_mfma_f32_16x16x32_bf16 v[52:55], v[222:225], v[172:175], v[52:55]
	v_mfma_f32_16x16x32_bf16 v[48:51], v[230:233], v[172:175], v[48:51]
	v_mfma_f32_16x16x32_bf16 v[36:39], v[222:225], v[180:183], v[36:39]
	v_mfma_f32_16x16x32_bf16 v[32:35], v[230:233], v[180:183], v[32:35]
	v_mfma_f32_16x16x32_bf16 v[20:23], v[222:225], v[206:209], v[20:23]
	v_mfma_f32_16x16x32_bf16 v[16:19], v[230:233], v[206:209], v[16:19]
	v_mfma_f32_16x16x32_bf16 v[4:7], v[222:225], v[214:217], v[4:7]
	v_mfma_f32_16x16x32_bf16 v[0:3], v[230:233], v[214:217], v[0:3]
	v_mfma_f32_16x16x32_bf16 v[52:55], v[226:229], v[176:179], v[52:55]
	v_mfma_f32_16x16x32_bf16 v[48:51], v[234:237], v[176:179], v[48:51]
	v_mfma_f32_16x16x32_bf16 v[36:39], v[226:229], v[188:191], v[36:39]
	v_mfma_f32_16x16x32_bf16 v[32:35], v[234:237], v[188:191], v[32:35]
	v_mfma_f32_16x16x32_bf16 v[20:23], v[226:229], v[210:213], v[20:23]
	v_mfma_f32_16x16x32_bf16 v[16:19], v[234:237], v[210:213], v[16:19]
	v_mfma_f32_16x16x32_bf16 v[4:7], v[226:229], v[218:221], v[4:7]
	v_mfma_f32_16x16x32_bf16 v[0:3], v[234:237], v[218:221], v[0:3]
	s_setprio 0
	s_add_i32 s68, s68, 2
	s_add_u32 s38, s38, 0x100
	s_addc_u32 s39, s39, 0
	s_add_u32 s35, s35, 0x100
	s_addc_u32 s67, s67, 0
	s_cmpk_gt_u32 s68, 0x55
	s_barrier
	s_cbranch_scc0 .LBB0_1746
	s_branch .Lpeel_done_1746
.LBB0_1746:
	ds_read_b128 v[144:147], v155
	ds_read_b128 v[160:163], v155 offset:1024
	ds_read_b128 v[164:167], v155 offset:2048
	ds_read_b128 v[168:171], v155 offset:3072
	s_add_u32 s0, s38, 0xffea0080
	s_addc_u32 s1, s39, -1
	s_cmpk_eq_i32 s68, 0x54
	s_cselect_b32 s43, s9, s1
	s_cselect_b32 s42, s8, s0
	s_cselect_b32 s41, s11, s67
	s_cselect_b32 s40, s10, s35
	s_add_i32 m0, s52, 0xc000
	ds_read_b128 v[172:175], v156
	ds_read_b128 v[176:179], v156 offset:1024
	ds_read_b128 v[180:183], v156 offset:2048
	ds_read_b128 v[188:191], v156 offset:3072
	ds_read_b128 v[206:209], v156 offset:4096
	ds_read_b128 v[210:213], v156 offset:5120
	ds_read_b128 v[214:217], v156 offset:6144
	global_load_lds_dwordx4 v136, s[38:39]
	s_add_i32 m0, s52, 0xe000
	ds_read_b128 v[218:221], v156 offset:7168
	global_load_lds_dwordx4 v138, s[38:39]
	s_waitcnt lgkmcnt(8)
	s_barrier
	s_waitcnt lgkmcnt(0)
	s_setprio 1
	v_mfma_f32_16x16x32_bf16 v[124:127], v[144:147], v[172:175], v[124:127]
	v_mfma_f32_16x16x32_bf16 v[120:123], v[164:167], v[172:175], v[120:123]
	v_mfma_f32_16x16x32_bf16 v[108:111], v[144:147], v[180:183], v[108:111]
	v_mfma_f32_16x16x32_bf16 v[104:107], v[164:167], v[180:183], v[104:107]
	v_mfma_f32_16x16x32_bf16 v[92:95], v[144:147], v[206:209], v[92:95]
	v_mfma_f32_16x16x32_bf16 v[88:91], v[164:167], v[206:209], v[88:91]
	v_mfma_f32_16x16x32_bf16 v[76:79], v[144:147], v[214:217], v[76:79]
	v_mfma_f32_16x16x32_bf16 v[72:75], v[164:167], v[214:217], v[72:75]
	v_mfma_f32_16x16x32_bf16 v[124:127], v[160:163], v[176:179], v[124:127]
	v_mfma_f32_16x16x32_bf16 v[120:123], v[168:171], v[176:179], v[120:123]
	v_mfma_f32_16x16x32_bf16 v[108:111], v[160:163], v[188:191], v[108:111]
	v_mfma_f32_16x16x32_bf16 v[104:107], v[168:171], v[188:191], v[104:107]
	v_mfma_f32_16x16x32_bf16 v[92:95], v[160:163], v[210:213], v[92:95]
	v_mfma_f32_16x16x32_bf16 v[88:91], v[168:171], v[210:213], v[88:91]
	v_mfma_f32_16x16x32_bf16 v[76:79], v[160:163], v[218:221], v[76:79]
	v_mfma_f32_16x16x32_bf16 v[72:75], v[168:171], v[218:221], v[72:75]
	s_setprio 0
	s_barrier
	s_add_i32 s0, s61, s51
	s_mov_b32 m0, s0
	ds_read_b128 v[222:225], v157
	ds_read_b128 v[226:229], v157 offset:1024
	ds_read_b128 v[230:233], v157 offset:2048
	global_load_lds_dwordx4 v130, s[40:41]
	s_add_i32 m0, s0, 0x2000
	ds_read_b128 v[234:237], v157 offset:3072
	global_load_lds_dwordx4 v134, s[40:41]
	s_barrier
; #define PG8_STAGE(bufoff, gbase, voff) do { _Pragma("unroll") for (int _i = 0; _i < 2; ++_i) \
;         __builtin_amdgcn_global_load_lds((const unsigned*)((const char*)(gbase) + (voff)[_i]), (LAS unsigned*)(lds + (bufoff) + ldsw + _i * 8192), 16, 0, 0); } while (0)
; #define PG8_LDA(dst, b, h) do { _Pragma("unroll") for (int m = 0; m < 4; ++m) _Pragma("unroll") for (int k = 0; k < 2; ++k) dst[m][k] = *(const LAS bf16x8*)(lds + PG8_SA(b, h) + aoff + m * 2048 + k * 1024); } while (0)
; #define PG8_LDB(dst, b, h) do { _Pragma("unroll") for (int n = 0; n < 2; ++n) _Pragma("unroll") for (int k = 0; k < 2; ++k) dst[n][k] = *(const LAS bf16x8*)(lds + PG8_SB(b, h) + boff + n * 2048 + k * 1024); } while (0)
; #define PG8_MMA(ai, bj, At, Bt) do { __builtin_amdgcn_s_setprio(1); _Pragma("unroll") for (int m = 0; m < 4; ++m) _Pragma("unroll") for (int n = 0; n < 2; ++n) _Pragma("unroll") for (int k = 0; k < 2; ++k) \
;         acc[ai][bj][m][n] = __builtin_amdgcn_mfma_f32_16x16x32_bf16(Bt[n][k], At[m][k], acc[ai][bj][m][n], 0, 0, 0); __builtin_amdgcn_s_setprio(0); } while (0)
; #define PG8_WAIT_V(n) asm volatile("s_waitcnt vmcnt(" #n ")" ::: "memory")
; #define PG8_WAIT_L(n) asm volatile("s_waitcnt lgkmcnt(" #n ")" ::: "memory")
; #define PG8_BAR __builtin_amdgcn_s_barrier()
; #define PG8_SCHED __builtin_amdgcn_sched_barrier(0)
; template <class Epi, class Sched>
; DI void gemm_phase(LAS unsigned char* lds, const Gemm g, const Sched& S, const Epi& E) {
;     ...
;             PG8_BAR; PG8_WAIT_L(0); PG8_MMA(0, 1, At, B1); PG8_BAR;
;             PG8_LDA(At, 0, 1); PG8_STAGE(PG8_SA(0, 0), a2, voffA);
;             PG8_BAR; PG8_WAIT_L(0); PG8_MMA(1, 0, At, B0); PG8_BAR; PG8_SCHED;
;             PG8_STAGE(PG8_SB(0, 1), b2 + hstep, voffB);
;             PG8_WAIT_V(6); PG8_BAR; PG8_MMA(1, 1, At, B1); PG8_BAR;
;             PG8_LDB(B0, 1, 0); PG8_SCHED; PG8_LDA(At, 1, 0); PG8_STAGE(PG8_SA(0, 1), a2 + hstep, voffA);
;             PG8_WAIT_L(8); PG8_BAR; PG8_WAIT_L(0); PG8_MMA(0, 0, At, B0); PG8_BAR; PG8_SCHED;
;             PG8_LDB(B1, 1, 1); PG8_STAGE(PG8_SB(1, 0), b3, voffB);
	s_waitcnt lgkmcnt(0)
	s_setprio 1
	v_mfma_f32_16x16x32_bf16 v[116:119], v[222:225], v[172:175], v[116:119]
	v_mfma_f32_16x16x32_bf16 v[112:115], v[230:233], v[172:175], v[112:115]
	v_mfma_f32_16x16x32_bf16 v[100:103], v[222:225], v[180:183], v[100:103]
	v_mfma_f32_16x16x32_bf16 v[96:99], v[230:233], v[180:183], v[96:99]
	v_mfma_f32_16x16x32_bf16 v[84:87], v[222:225], v[206:209], v[84:87]
	v_mfma_f32_16x16x32_bf16 v[80:83], v[230:233], v[206:209], v[80:83]
	v_mfma_f32_16x16x32_bf16 v[68:71], v[222:225], v[214:217], v[68:71]
	v_mfma_f32_16x16x32_bf16 v[64:67], v[230:233], v[214:217], v[64:67]
	v_mfma_f32_16x16x32_bf16 v[116:119], v[226:229], v[176:179], v[116:119]
	v_mfma_f32_16x16x32_bf16 v[112:115], v[234:237], v[176:179], v[112:115]
	v_mfma_f32_16x16x32_bf16 v[100:103], v[226:229], v[188:191], v[100:103]
	v_mfma_f32_16x16x32_bf16 v[96:99], v[234:237], v[188:191], v[96:99]
	v_mfma_f32_16x16x32_bf16 v[84:87], v[226:229], v[210:213], v[84:87]
	v_mfma_f32_16x16x32_bf16 v[80:83], v[234:237], v[210:213], v[80:83]
	v_mfma_f32_16x16x32_bf16 v[68:71], v[226:229], v[218:221], v[68:71]
	v_mfma_f32_16x16x32_bf16 v[64:67], v[234:237], v[218:221], v[64:67]
	s_setprio 0
	s_mov_b32 m0, s52
	s_barrier
	ds_read_b128 v[172:175], v156 offset:16384
	ds_read_b128 v[176:179], v156 offset:17408
	ds_read_b128 v[180:183], v156 offset:18432
	ds_read_b128 v[188:191], v156 offset:19456
	ds_read_b128 v[206:209], v156 offset:20480
	ds_read_b128 v[210:213], v156 offset:21504
	ds_read_b128 v[214:217], v156 offset:22528
	global_load_lds_dwordx4 v128, s[42:43]
	s_mov_b32 m0, s53
	ds_read_b128 v[218:221], v156 offset:23552
	global_load_lds_dwordx4 v132, s[42:43]
	s_barrier
	s_waitcnt lgkmcnt(0)
	s_setprio 1
	v_mfma_f32_16x16x32_bf16 v[60:63], v[144:147], v[172:175], v[60:63]
	v_mfma_f32_16x16x32_bf16 v[56:59], v[164:167], v[172:175], v[56:59]
	v_mfma_f32_16x16x32_bf16 v[44:47], v[144:147], v[180:183], v[44:47]
	v_mfma_f32_16x16x32_bf16 v[40:43], v[164:167], v[180:183], v[40:43]
	v_mfma_f32_16x16x32_bf16 v[28:31], v[144:147], v[206:209], v[28:31]
	v_mfma_f32_16x16x32_bf16 v[24:27], v[164:167], v[206:209], v[24:27]
	v_mfma_f32_16x16x32_bf16 v[12:15], v[144:147], v[214:217], v[12:15]
	v_mfma_f32_16x16x32_bf16 v[8:11], v[164:167], v[214:217], v[8:11]
	v_mfma_f32_16x16x32_bf16 v[60:63], v[160:163], v[176:179], v[60:63]
	v_mfma_f32_16x16x32_bf16 v[56:59], v[168:171], v[176:179], v[56:59]
	v_mfma_f32_16x16x32_bf16 v[44:47], v[160:163], v[188:191], v[44:47]
	v_mfma_f32_16x16x32_bf16 v[40:43], v[168:171], v[188:191], v[40:43]
	v_mfma_f32_16x16x32_bf16 v[28:31], v[160:163], v[210:213], v[28:31]
	v_mfma_f32_16x16x32_bf16 v[24:27], v[168:171], v[210:213], v[24:27]
	v_mfma_f32_16x16x32_bf16 v[12:15], v[160:163], v[218:221], v[12:15]
	v_mfma_f32_16x16x32_bf16 v[8:11], v[168:171], v[218:221], v[8:11]
	s_setprio 0
	s_barrier
	s_add_u32 s0, s40, 0x160000
	s_addc_u32 s1, s41, 0
	s_add_i32 s4, s62, s51
	s_mov_b32 m0, s4
	s_nop 0
	global_load_lds_dwordx4 v130, s[0:1]
	s_add_i32 m0, s4, 0x2000
	s_nop 0
	global_load_lds_dwordx4 v134, s[0:1]
	s_waitcnt vmcnt(6)
	s_barrier
	s_setprio 1
	v_mfma_f32_16x16x32_bf16 v[52:55], v[222:225], v[172:175], v[52:55]
	v_mfma_f32_16x16x32_bf16 v[48:51], v[230:233], v[172:175], v[48:51]
	v_mfma_f32_16x16x32_bf16 v[36:39], v[222:225], v[180:183], v[36:39]
	v_mfma_f32_16x16x32_bf16 v[32:35], v[230:233], v[180:183], v[32:35]
	v_mfma_f32_16x16x32_bf16 v[20:23], v[222:225], v[206:209], v[20:23]
	v_mfma_f32_16x16x32_bf16 v[16:19], v[230:233], v[206:209], v[16:19]
	v_mfma_f32_16x16x32_bf16 v[4:7], v[222:225], v[214:217], v[4:7]
	v_mfma_f32_16x16x32_bf16 v[0:3], v[230:233], v[214:217], v[0:3]
	v_mfma_f32_16x16x32_bf16 v[52:55], v[226:229], v[176:179], v[52:55]
	v_mfma_f32_16x16x32_bf16 v[48:51], v[234:237], v[176:179], v[48:51]
	v_mfma_f32_16x16x32_bf16 v[36:39], v[226:229], v[188:191], v[36:39]
	v_mfma_f32_16x16x32_bf16 v[32:35], v[234:237], v[188:191], v[32:35]
	v_mfma_f32_16x16x32_bf16 v[20:23], v[226:229], v[210:213], v[20:23]
	v_mfma_f32_16x16x32_bf16 v[16:19], v[234:237], v[210:213], v[16:19]
	v_mfma_f32_16x16x32_bf16 v[4:7], v[226:229], v[218:221], v[4:7]
	v_mfma_f32_16x16x32_bf16 v[0:3], v[234:237], v[218:221], v[0:3]
	s_setprio 0
	s_add_i32 s4, 0, 0x18000
	s_barrier
	ds_read_b128 v[144:147], v202
	ds_read_b128 v[160:163], v202 offset:1024
	ds_read_b128 v[164:167], v202 offset:2048
	ds_read_b128 v[168:171], v202 offset:3072
	s_add_u32 s0, s42, 0x160000
	s_addc_u32 s1, s43, 0
	s_mov_b32 m0, s54
	ds_read_b128 v[172:175], v156 offset:32768
	ds_read_b128 v[176:179], v156 offset:33792
	ds_read_b128 v[180:183], v156 offset:34816
	ds_read_b128 v[188:191], v156 offset:35840
	ds_read_b128 v[206:209], v156 offset:36864
	ds_read_b128 v[210:213], v156 offset:37888
	ds_read_b128 v[214:217], v156 offset:38912
	global_load_lds_dwordx4 v128, s[0:1]
	s_mov_b32 m0, s55
	ds_read_b128 v[218:221], v156 offset:39936
	global_load_lds_dwordx4 v132, s[0:1]
	s_waitcnt lgkmcnt(8)
	s_barrier
; #define PG8_STAGE(bufoff, gbase, voff) do { _Pragma("unroll") for (int _i = 0; _i < 2; ++_i) \
;         __builtin_amdgcn_global_load_lds((const unsigned*)((const char*)(gbase) + (voff)[_i]), (LAS unsigned*)(lds + (bufoff) + ldsw + _i * 8192), 16, 0, 0); } while (0)
; #define PG8_LDA(dst, b, h) do { _Pragma("unroll") for (int m = 0; m < 4; ++m) _Pragma("unroll") for (int k = 0; k < 2; ++k) dst[m][k] = *(const LAS bf16x8*)(lds + PG8_SA(b, h) + aoff + m * 2048 + k * 1024); } while (0)
; #define PG8_LDB(dst, b, h) do { _Pragma("unroll") for (int n = 0; n < 2; ++n) _Pragma("unroll") for (int k = 0; k < 2; ++k) dst[n][k] = *(const LAS bf16x8*)(lds + PG8_SB(b, h) + boff + n * 2048 + k * 1024); } while (0)
; #define PG8_MMA(ai, bj, At, Bt) do { __builtin_amdgcn_s_setprio(1); _Pragma("unroll") for (int m = 0; m < 4; ++m) _Pragma("unroll") for (int n = 0; n < 2; ++n) _Pragma("unroll") for (int k = 0; k < 2; ++k) \
;         acc[ai][bj][m][n] = __builtin_amdgcn_mfma_f32_16x16x32_bf16(Bt[n][k], At[m][k], acc[ai][bj][m][n], 0, 0, 0); __builtin_amdgcn_s_setprio(0); } while (0)
; #define PG8_WAIT_V(n) asm volatile("s_waitcnt vmcnt(" #n ")" ::: "memory")
; #define PG8_WAIT_L(n) asm volatile("s_waitcnt lgkmcnt(" #n ")" ::: "memory")
; #define PG8_BAR __builtin_amdgcn_s_barrier()
; #define PG8_SCHED __builtin_amdgcn_sched_barrier(0)
; template <class Epi, class Sched>
; DI void gemm_phase(LAS unsigned char* lds, const Gemm g, const Sched& S, const Epi& E) {
;     ...
;             PG8_LDB(B1, 1, 1); PG8_STAGE(PG8_SB(1, 0), b3, voffB);
;             PG8_BAR; PG8_WAIT_L(0); PG8_MMA(0, 1, At, B1); PG8_BAR;
;             PG8_LDA(At, 1, 1); PG8_STAGE(PG8_SA(1, 0), a3, voffA);
;             PG8_BAR; PG8_WAIT_L(0); PG8_MMA(1, 0, At, B0); PG8_BAR; PG8_SCHED;
;             PG8_STAGE(PG8_SB(1, 1), b3 + hstep, voffB);
;             PG8_WAIT_V(6); PG8_BAR; PG8_MMA(1, 1, At, B1); PG8_BAR;
	s_waitcnt lgkmcnt(0)
	s_setprio 1
	v_mfma_f32_16x16x32_bf16 v[124:127], v[144:147], v[172:175], v[124:127]
	v_mfma_f32_16x16x32_bf16 v[120:123], v[164:167], v[172:175], v[120:123]
	v_mfma_f32_16x16x32_bf16 v[108:111], v[144:147], v[180:183], v[108:111]
	v_mfma_f32_16x16x32_bf16 v[104:107], v[164:167], v[180:183], v[104:107]
	v_mfma_f32_16x16x32_bf16 v[92:95], v[144:147], v[206:209], v[92:95]
	v_mfma_f32_16x16x32_bf16 v[88:91], v[164:167], v[206:209], v[88:91]
	v_mfma_f32_16x16x32_bf16 v[76:79], v[144:147], v[214:217], v[76:79]
	v_mfma_f32_16x16x32_bf16 v[72:75], v[164:167], v[214:217], v[72:75]
	v_mfma_f32_16x16x32_bf16 v[124:127], v[160:163], v[176:179], v[124:127]
	v_mfma_f32_16x16x32_bf16 v[120:123], v[168:171], v[176:179], v[120:123]
	v_mfma_f32_16x16x32_bf16 v[108:111], v[160:163], v[188:191], v[108:111]
	v_mfma_f32_16x16x32_bf16 v[104:107], v[168:171], v[188:191], v[104:107]
	v_mfma_f32_16x16x32_bf16 v[92:95], v[160:163], v[210:213], v[92:95]
	v_mfma_f32_16x16x32_bf16 v[88:91], v[168:171], v[210:213], v[88:91]
	v_mfma_f32_16x16x32_bf16 v[76:79], v[160:163], v[218:221], v[76:79]
	v_mfma_f32_16x16x32_bf16 v[72:75], v[168:171], v[218:221], v[72:75]
	s_setprio 0
	s_barrier
	s_add_i32 s5, 0, 0x1c000
	s_add_i32 s0, s4, s51
	s_add_i32 m0, s0, 0xffffff80
	ds_read_b128 v[222:225], v203
	ds_read_b128 v[226:229], v203 offset:1024
	ds_read_b128 v[230:233], v203 offset:2048
	global_load_lds_dwordx4 v130, s[40:41] offset:128
	s_add_i32 m0, s0, 0x1f80
	ds_read_b128 v[234:237], v203 offset:3072
	global_load_lds_dwordx4 v134, s[40:41] offset:128
	s_barrier
	s_waitcnt lgkmcnt(0)
	s_setprio 1
	v_mfma_f32_16x16x32_bf16 v[116:119], v[222:225], v[172:175], v[116:119]
	v_mfma_f32_16x16x32_bf16 v[112:115], v[230:233], v[172:175], v[112:115]
	v_mfma_f32_16x16x32_bf16 v[100:103], v[222:225], v[180:183], v[100:103]
	v_mfma_f32_16x16x32_bf16 v[96:99], v[230:233], v[180:183], v[96:99]
	v_mfma_f32_16x16x32_bf16 v[84:87], v[222:225], v[206:209], v[84:87]
	v_mfma_f32_16x16x32_bf16 v[80:83], v[230:233], v[206:209], v[80:83]
	v_mfma_f32_16x16x32_bf16 v[68:71], v[222:225], v[214:217], v[68:71]
	v_mfma_f32_16x16x32_bf16 v[64:67], v[230:233], v[214:217], v[64:67]
	v_mfma_f32_16x16x32_bf16 v[116:119], v[226:229], v[176:179], v[116:119]
	v_mfma_f32_16x16x32_bf16 v[112:115], v[234:237], v[176:179], v[112:115]
	v_mfma_f32_16x16x32_bf16 v[100:103], v[226:229], v[188:191], v[100:103]
	v_mfma_f32_16x16x32_bf16 v[96:99], v[234:237], v[188:191], v[96:99]
	v_mfma_f32_16x16x32_bf16 v[84:87], v[226:229], v[210:213], v[84:87]
	v_mfma_f32_16x16x32_bf16 v[80:83], v[234:237], v[210:213], v[80:83]
	v_mfma_f32_16x16x32_bf16 v[68:71], v[226:229], v[218:221], v[68:71]
	v_mfma_f32_16x16x32_bf16 v[64:67], v[234:237], v[218:221], v[64:67]
	s_setprio 0
	s_add_i32 m0, s59, 0xffffff80
	s_barrier
	ds_read_b128 v[172:175], v156 offset:49152
	ds_read_b128 v[176:179], v156 offset:50176
	ds_read_b128 v[180:183], v156 offset:51200
	ds_read_b128 v[188:191], v156 offset:52224
	ds_read_b128 v[206:209], v156 offset:53248
	ds_read_b128 v[210:213], v156 offset:54272
	ds_read_b128 v[214:217], v156 offset:55296
	global_load_lds_dwordx4 v128, s[42:43] offset:128
	s_add_i32 m0, s60, 0xffffff80
	ds_read_b128 v[218:221], v156 offset:56320
	global_load_lds_dwordx4 v132, s[42:43] offset:128
	s_barrier
	s_waitcnt lgkmcnt(0)
	s_setprio 1
	v_mfma_f32_16x16x32_bf16 v[60:63], v[144:147], v[172:175], v[60:63]
	v_mfma_f32_16x16x32_bf16 v[56:59], v[164:167], v[172:175], v[56:59]
	v_mfma_f32_16x16x32_bf16 v[44:47], v[144:147], v[180:183], v[44:47]
	v_mfma_f32_16x16x32_bf16 v[40:43], v[164:167], v[180:183], v[40:43]
	v_mfma_f32_16x16x32_bf16 v[28:31], v[144:147], v[206:209], v[28:31]
	v_mfma_f32_16x16x32_bf16 v[24:27], v[164:167], v[206:209], v[24:27]
	v_mfma_f32_16x16x32_bf16 v[12:15], v[144:147], v[214:217], v[12:15]
	v_mfma_f32_16x16x32_bf16 v[8:11], v[164:167], v[214:217], v[8:11]
	v_mfma_f32_16x16x32_bf16 v[60:63], v[160:163], v[176:179], v[60:63]
	v_mfma_f32_16x16x32_bf16 v[56:59], v[168:171], v[176:179], v[56:59]
	v_mfma_f32_16x16x32_bf16 v[44:47], v[160:163], v[188:191], v[44:47]
	v_mfma_f32_16x16x32_bf16 v[40:43], v[168:171], v[188:191], v[40:43]
	v_mfma_f32_16x16x32_bf16 v[28:31], v[160:163], v[210:213], v[28:31]
	v_mfma_f32_16x16x32_bf16 v[24:27], v[168:171], v[210:213], v[24:27]
	v_mfma_f32_16x16x32_bf16 v[12:15], v[160:163], v[218:221], v[12:15]
	v_mfma_f32_16x16x32_bf16 v[8:11], v[168:171], v[218:221], v[8:11]
	s_setprio 0
	s_barrier
	s_add_u32 s0, s40, 0x160080
	s_addc_u32 s1, s41, 0
	s_add_i32 s4, s5, s51
	s_mov_b32 m0, s4
	s_nop 0
	global_load_lds_dwordx4 v130, s[0:1]
	s_add_i32 m0, s4, 0x2000
	s_nop 0
	global_load_lds_dwordx4 v134, s[0:1]
	s_waitcnt vmcnt(6)
	s_barrier
	s_setprio 1
	v_mfma_f32_16x16x32_bf16 v[52:55], v[222:225], v[172:175], v[52:55]
	v_mfma_f32_16x16x32_bf16 v[48:51], v[230:233], v[172:175], v[48:51]
	v_mfma_f32_16x16x32_bf16 v[36:39], v[222:225], v[180:183], v[36:39]
	v_mfma_f32_16x16x32_bf16 v[32:35], v[230:233], v[180:183], v[32:35]
	v_mfma_f32_16x16x32_bf16 v[20:23], v[222:225], v[206:209], v[20:23]
	v_mfma_f32_16x16x32_bf16 v[16:19], v[230:233], v[206:209], v[16:19]
	v_mfma_f32_16x16x32_bf16 v[4:7], v[222:225], v[214:217], v[4:7]
	v_mfma_f32_16x16x32_bf16 v[0:3], v[230:233], v[214:217], v[0:3]
	v_mfma_f32_16x16x32_bf16 v[52:55], v[226:229], v[176:179], v[52:55]
	v_mfma_f32_16x16x32_bf16 v[48:51], v[234:237], v[176:179], v[48:51]
	v_mfma_f32_16x16x32_bf16 v[36:39], v[226:229], v[188:191], v[36:39]
	v_mfma_f32_16x16x32_bf16 v[32:35], v[234:237], v[188:191], v[32:35]
	v_mfma_f32_16x16x32_bf16 v[20:23], v[226:229], v[210:213], v[20:23]
	v_mfma_f32_16x16x32_bf16 v[16:19], v[234:237], v[210:213], v[16:19]
	v_mfma_f32_16x16x32_bf16 v[4:7], v[226:229], v[218:221], v[4:7]
	v_mfma_f32_16x16x32_bf16 v[0:3], v[234:237], v[218:221], v[0:3]
	s_setprio 0
	s_add_i32 s68, s68, 2
	s_add_u32 s38, s38, 0x100
	s_addc_u32 s39, s39, 0
	s_add_u32 s35, s35, 0x100
	s_addc_u32 s67, s67, 0
	s_cmpk_gt_u32 s68, 0x55
	s_barrier
	s_cbranch_scc0 .LBB0_1746
